# v81 + attention bias / rescale paths: packed f32 adds and multiplies replaced by scalar pairs (sec 7.5 packed vs scalar fp32)
# speedup vs baseline: 1.0062x; 1.0040x over previous
; DI float bf2f(unsigned short h) { return __uint_as_float((unsigned)h << 16); }
; template <int DQK, int MODE, int LDQ, int LDK, int LDV> ...
;     ...
;     int kgo[NKP], vgo[2];
; #pragma unroll
;     for (int i = 0; i < NKP; ++i) { const int L = (wid + 8 * i) * 64 + lane, row = L / CPR, slot = L % CPR, cc = (slot & ~7) | ((slot & 7) ^ ((row >> 1) & 7)); kgo[i] = row * LDK + cc * 8; }
; #pragma unroll
;     for (int i = 0; i < 2; ++i) { const int L = (2 * wid + i) * 64 + lane, st = L >> 5, w5 = L & 31, kk = (st >> 2) * 8 + (w5 >> 2), c = (st & 3) * 32 + (w5 & 3) * 8;
;         const int k = (kk & ~0xC) | ((kk & 4) << 1) | ((kk & 8) >> 1); vgo[i] = k * LDV + c; }
;     ...
;     ATT_DMA_K(0); ATT_DMA_K(1); ATT_DMA_V(0, 0); ATT_DMA_K(2); ATT_DMA_V(1, 1);
;     bf16x8 qr[ND0];
;     { const bf16_t* Qw = Qb + (size_t)(wid * 32 + r32) * LDQ + hi * 8;
; #pragma unroll
;       for (int d0 = 0; d0 < ND0; ++d0) qr[d0] = *(const bf16x8*)(Qw + d0 * 16);
;       if constexpr (MODE == 0) {
;           float ss = 0.f;
; #pragma unroll
;           for (int d0 = 0; d0 < ND0; ++d0)
; #pragma unroll
;               for (int j = 0; j < 8; ++j) { const float f = bf2f((unsigned short)qr[d0][j]); ss += f * f; }
;           ss = swap_sum(ss);
;           const float rstd = rsqrtf(ss * (1.f / DQK) + EPS) * C;
; #pragma unroll
;           for (int d0 = 0; d0 < ND0; ++d0) { const float* g = gq + d0 * 16 + hi * 8;
;               { float f[8]; _Pragma("unroll") for (int j = 0; j < 8; ++j) f[j] = bf2f((unsigned short)qr[d0][j]) * rstd * g[j];
;                 u32x4 w = {cvtpk(f[0], f[1]), cvtpk(f[2], f[3]), cvtpk(f[4], f[5]), cvtpk(f[6], f[7])}; qr[d0] = __builtin_bit_cast(bf16x8, w); asm volatile("" ::: "memory"); } }
;       } }
;     const int qlo = q0 + wid * 32, qpos = qlo + r32;
;     const int tL = MODE == 0 ? 0 : (qlo >= 191 ? (qlo - 127) >> 6 : 0), tR = MODE == 0 ? NT : min(NT, (qlo + 222) >> 6);
;     float fL = 1.f, fR = 1.f; if constexpr (MODE != 0) { fL = __builtin_amdgcn_exp2f(bt[0]); fR = __builtin_amdgcn_exp2f(-bt[448]); }
;     ...
;     const int vbase = (int)(unsigned)(size_t)lds + V_OFF + v_rd_base(lane);
;     ...
;     constexpr int NDA = ND0 > 6 ? 6 : ND0;
;     ...
;     f32x16 pA, pB; bf16x8 pa0, pa1;
;     int v0 = 0, v1 = 1, v2 = 2;
;     ATT_TOP(NKP + 2);
;     { bf16x8 kf[NDA]; k_reads<DQK, 0, NDA>(kf, lds, 0, r32, hi); ATT_LGKM0(); qk_mma<0, NDA>(pA, kf, qr);
.LBB0_1915:
	s_or_b64 exec, exec, s[2:3]
	s_lshl_b64 s[0:1], s[40:41], 12
	s_add_u32 s0, s14, s0
	s_addc_u32 s1, s15, s1
	s_lshl_b32 s4, s86, 8
	s_add_u32 s44, s0, s4
	s_addc_u32 s45, s1, 0
	s_lshl_b64 s[2:3], s[42:43], 24
	s_add_u32 s0, s14, s2
	s_addc_u32 s1, s15, s3
	s_add_u32 s46, s0, s4
	s_addc_u32 s47, s1, 0
	s_add_u32 s48, s46, 0x800
	s_waitcnt lgkmcnt(0)
	s_barrier
	s_addc_u32 s49, s47, 0
	v_mbcnt_lo_u32_b32 v7, -1, 0
	v_mbcnt_hi_u32_b32 v7, -1, v7
	s_add_u32 s56, s46, 0xc00
	v_add_u32_e32 v0, s33, v7
	s_addc_u32 s57, s47, 0
	v_readfirstlane_b32 s0, v0
	s_ashr_i32 s4, s0, 31
	s_ashr_i32 s1, s0, 6
	v_mov_b32_e32 v1, s0
	v_bfi_b32 v1, s63, v1, v7
	s_lshr_b32 s4, s4, 29
	v_add_u32_e32 v3, s4, v1
	s_lshl_b32 s4, s1, 7
	v_ashrrev_i32_e32 v9, 3, v3
	v_and_b32_e32 v3, 0x1ffffff8, v3
	s_ashr_i32 s4, s4, 4
	v_bfe_u32 v4, v0, 2, 2
	v_lshrrev_b32_e32 v0, 2, v0
	v_sub_u32_e32 v1, v1, v3
	v_lshrrev_b32_e32 v3, 1, v9
	v_lshlrev_b32_e32 v18, 3, v7
	s_and_b32 s6, s4, -16
	v_and_b32_e32 v6, 4, v0
	s_lshr_b32 s4, s4, 0
	v_bitop3_b32 v1, v3, v1, 7 bitop3:0x6c
	v_and_b32_e32 v3, 32, v7
	v_and_b32_e32 v5, 24, v18
	s_and_b32 s7, s4, 8
	v_or3_b32 v0, v6, v4, s6
	v_or_b32_e32 v10, v3, v5
	v_or_b32_e32 v0, s7, v0
	v_lshl_or_b32 v96, v0, 11, v10
	v_lshlrev_b32_e32 v0, 11, v9
	v_lshl_add_u32 v0, v1, 3, v0
	v_ashrrev_i32_e32 v1, 31, v0
	v_lshlrev_b64 v[10:11], 1, v[0:1]
	v_lshl_add_u64 v[12:13], s[46:47], 0, v[10:11]
	s_mov_b64 s[4:5], 0x800
	v_lshl_add_u64 v[12:13], v[12:13], 0, s[4:5]
	s_lshl_b32 s4, s1, 10
	s_add_i32 s59, s4, 0
	s_mov_b32 m0, s59
	v_lshl_add_u64 v[10:11], s[48:49], 0, v[10:11]
	global_load_lds_dwordx4 v[12:13], off
	v_lshl_add_u64 v[12:13], v[10:11], 0, s[8:9]
	s_add_i32 m0, s59, 0x2000
	s_lshl_b32 s4, s1, 11
	v_ashrrev_i32_e32 v97, 31, v96
	global_load_lds_dwordx4 v[12:13], off
	s_add_i32 s22, s4, 0
	v_lshlrev_b64 v[12:13], 1, v[96:97]
	s_add_i32 s95, s22, 0x18000
	v_lshl_add_u64 v[14:15], s[46:47], 0, v[12:13]
	v_lshl_add_u64 v[16:17], v[14:15], 0, s[96:97]
	s_mov_b32 m0, s95
	s_mov_b64 s[4:5], 0xc80
	global_load_lds_dwordx4 v[16:17], off
	v_lshl_add_u64 v[14:15], v[14:15], 0, s[4:5]
	s_add_i32 m0, s22, 0x18400
	s_mov_b64 s[4:5], 0x80000
	global_load_lds_dwordx4 v[14:15], off
	s_add_i32 m0, s59, 0x4000
	s_add_u32 s52, s46, 0x40c00
	v_or_b32_e32 v98, 64, v96
	v_lshl_add_u64 v[10:11], v[10:11], 0, s[4:5]
	s_addc_u32 s53, s47, 0
	v_ashrrev_i32_e32 v99, 31, v98
	global_load_lds_dwordx4 v[10:11], off
	s_add_i32 m0, s22, 0x1c000
	v_lshl_add_u64 v[10:11], s[52:53], 0, v[12:13]
	v_and_b32_e32 v2, 31, v7
	global_load_lds_dwordx4 v[10:11], off
	v_lshl_add_u64 v[10:11], v[98:99], 1, s[52:53]
	s_add_i32 m0, s22, 0x1c400
	s_lshl_b32 s94, s1, 5
	global_load_lds_dwordx4 v[10:11], off
	v_or_b32_e32 v10, s94, v2
	v_ashrrev_i32_e32 v11, 31, v10
	v_bfe_u32 v8, v7, 5, 1
	v_lshlrev_b64 v[10:11], 12, v[10:11]
	v_lshl_add_u64 v[10:11], s[44:45], 0, v[10:11]
	v_lshlrev_b32_e32 v130, 4, v8
	v_lshl_add_u64 v[10:11], v[10:11], 0, v[130:131]
	global_load_dwordx4 v[92:95], v[10:11], off offset:1024
	global_load_dwordx4 v[88:91], v[10:11], off offset:1056
	global_load_dwordx4 v[84:87], v[10:11], off offset:1088
	global_load_dwordx4 v[80:83], v[10:11], off offset:1120
	s_add_i32 s4, s94, s89
	s_add_i32 s5, s4, 0xffffff81
	s_ashr_i32 s5, s5, 6
	s_cmpk_gt_i32 s4, 0xbe
	s_cselect_b32 s55, s5, 0
	s_add_i32 s88, 0, 0x24800
	v_and_b32_e32 v11, 0x70, v18
	v_mov_b32_e32 v9, s88
	v_mov_b32_e32 v10, s81
	v_lshl_add_u32 v114, v2, 7, 0
	v_bitop3_b32 v115, v130, v18, s64 bitop3:0x78
	v_bitop3_b32 v117, v130, v11, 64 bitop3:0x36
	ds_read_b32 v9, v9
	ds_read_b32 v10, v10
	s_waitcnt vmcnt(3)
	s_barrier
	v_add_u32_e32 v107, v114, v115
	v_bitop3_b32 v116, v130, v11, 32 bitop3:0x36
	v_add_u32_e32 v109, v114, v117
	v_bitop3_b32 v118, v130, v11, s65 bitop3:0x36
	v_add_u32_e32 v108, v114, v116
	ds_read_b128 v[12:15], v107
	ds_read_b128 v[16:19], v108
	v_add_u32_e32 v110, v114, v118
	ds_read_b128 v[20:23], v109
	ds_read_b128 v[24:27], v110
	v_or_b32_e32 v111, s4, v2
	s_addk_i32 s4, 0xde
	s_ashr_i32 s58, s4, 6
	s_waitcnt lgkmcnt(0)
	s_waitcnt vmcnt(0) lgkmcnt(0)
	v_mfma_f32_32x32x16_bf16 v[64:79], v[12:15], v[92:95], 0
	s_cmp_gt_i32 s55, 0
	s_cselect_b64 s[4:5], -1, 0
	s_cmp_lt_i32 s58, 1
	s_cselect_b64 s[22:23], -1, 0
	s_or_b64 s[4:5], s[22:23], s[4:5]
	s_and_b64 vcc, exec, s[4:5]
	v_mfma_f32_32x32x16_bf16 v[64:79], v[16:19], v[88:91], v[64:79]
	v_mfma_f32_32x32x16_bf16 v[64:79], v[20:23], v[84:87], v[64:79]
	v_mfma_f32_32x32x16_bf16 v[64:79], v[24:27], v[80:83], v[64:79]
	s_cbranch_vccnz .LBB0_1917
	v_lshlrev_b32_e32 v8, 2, v8
	v_sub_u32_e32 v8, v8, v111
	v_lshl_add_u32 v8, v8, 2, s88
	ds_read2_b32 v[12:13], v8 offset0:240 offset1:241
	ds_read2_b32 v[14:15], v8 offset0:242 offset1:243
	ds_read2_b32 v[16:17], v8 offset0:248 offset1:249
	ds_read2_b32 v[18:19], v8 offset0:250 offset1:251
	ds_read2_b32 v[20:21], v8 offset0:224 offset1:225
	ds_read2_b32 v[22:23], v8 offset0:226 offset1:227
	ds_read2_b32 v[24:25], v8 offset0:232 offset1:233
	ds_read2_b32 v[26:27], v8 offset0:234 offset1:235
	s_waitcnt lgkmcnt(4)
	v_add_f32_e32 v78, v78, v18
	v_add_f32_e32 v79, v79, v19
	v_add_f32_e32 v76, v76, v16
	v_add_f32_e32 v77, v77, v17
	v_add_f32_e32 v74, v74, v14
	v_add_f32_e32 v75, v75, v15
	v_add_f32_e32 v72, v72, v12
	v_add_f32_e32 v73, v73, v13
	s_waitcnt lgkmcnt(0)
	v_add_f32_e32 v70, v70, v26
	v_add_f32_e32 v71, v71, v27
	v_add_f32_e32 v68, v68, v24
	v_add_f32_e32 v69, v69, v25
	v_add_f32_e32 v66, v66, v22
	v_add_f32_e32 v67, v67, v23
	v_add_f32_e32 v64, v64, v20
	v_add_f32_e32 v65, v65, v21

.Lhw_d0_b_dtd0resc:
	s_cmp_eq_u32 s0, s98
	s_cselect_b64 s[2:3], -1, 0
	s_and_b64 vcc, s[4:5], s[2:3]
	s_cmp_eq_u32 s0, s99
	s_cselect_b64 s[2:3], -1, 0
	s_or_b64 vcc, s[2:3], vcc
	s_andn2_b64 vcc, exec, vcc
	s_cbranch_vccnz .Lhw_d0_b_n1922
	v_cndmask_b32_e64 v122, v112, v113, s[2:3]
	v_mul_f32_e32 v14, v14, v122
	v_mul_f32_e32 v15, v15, v122
	v_mul_f32_e32 v12, v12, v122
	v_mul_f32_e32 v13, v13, v122
	v_mul_f32_e32 v10, v10, v122
	v_mul_f32_e32 v11, v11, v122
	v_mul_f32_e32 v8, v8, v122
	v_mul_f32_e32 v9, v9, v122
	v_mul_f32_e32 v6, v6, v122
	v_mul_f32_e32 v7, v7, v122
	v_mul_f32_e32 v4, v4, v122
	v_mul_f32_e32 v5, v5, v122
	v_mul_f32_e32 v2, v2, v122
	v_mul_f32_e32 v3, v3, v122
	v_mul_f32_e32 v0, v0, v122
	v_mul_f32_e32 v1, v1, v122
	v_mul_f32_e32 v62, v62, v122
	v_mul_f32_e32 v63, v63, v122
	v_mul_f32_e32 v60, v60, v122
	v_mul_f32_e32 v61, v61, v122
	v_mul_f32_e32 v58, v58, v122
	v_mul_f32_e32 v59, v59, v122
	v_mul_f32_e32 v56, v56, v122
	v_mul_f32_e32 v57, v57, v122
	v_mul_f32_e32 v54, v54, v122
	v_mul_f32_e32 v55, v55, v122
	v_mul_f32_e32 v52, v52, v122
	v_mul_f32_e32 v53, v53, v122
	v_mul_f32_e32 v50, v50, v122
	v_mul_f32_e32 v51, v51, v122
	v_mul_f32_e32 v48, v48, v122
	v_mul_f32_e32 v49, v49, v122
	v_mul_f32_e32 v46, v46, v122
	v_mul_f32_e32 v47, v47, v122
	v_mul_f32_e32 v44, v44, v122
	v_mul_f32_e32 v45, v45, v122
	v_mul_f32_e32 v42, v42, v122
	v_mul_f32_e32 v43, v43, v122
	v_mul_f32_e32 v40, v40, v122
	v_mul_f32_e32 v41, v41, v122
	v_mul_f32_e32 v38, v38, v122
	v_mul_f32_e32 v39, v39, v122
	v_mul_f32_e32 v36, v36, v122
	v_mul_f32_e32 v37, v37, v122
	v_mul_f32_e32 v34, v34, v122
	v_mul_f32_e32 v35, v35, v122
	v_mul_f32_e32 v32, v32, v122
	v_mul_f32_e32 v33, v33, v122
	v_mul_f32_e32 v30, v30, v122
	v_mul_f32_e32 v31, v31, v122
	v_mul_f32_e32 v28, v28, v122
	v_mul_f32_e32 v29, v29, v122
	v_mul_f32_e32 v26, v26, v122
	v_mul_f32_e32 v27, v27, v122
	v_mul_f32_e32 v24, v24, v122
	v_mul_f32_e32 v25, v25, v122
	v_mul_f32_e32 v22, v22, v122
	v_mul_f32_e32 v23, v23, v122
	v_mul_f32_e32 v20, v20, v122
	v_mul_f32_e32 v21, v21, v122
	v_mul_f32_e32 v18, v18, v122
	v_mul_f32_e32 v19, v19, v122
	v_mul_f32_e32 v16, v16, v122
	v_mul_f32_e32 v17, v17, v122
	v_mul_f32_e32 v120, v120, v122
	s_branch .Lhw_d0_b_n1922
.Lhw_d0_b_dtd0bias1:
	v_add_u32_e32 v122, s7, v119
	v_add_u32_e32 v138, 0x28908, v122
	v_add_u32_e32 v140, 0x28920, v122
	v_add_u32_e32 v142, 0x28928, v122
	v_add_u32_e32 v124, 0x28940, v122
	v_add_u32_e32 v126, 0x28948, v122
	v_add_u32_e32 v132, 0x28960, v122
	v_add_u32_e32 v134, 0x28968, v122
	v_add_u32_e32 v123, 0x28900, v122
	ds_read2_b32 v[124:125], v124 offset1:1
	ds_read2_b32 v[126:127], v126 offset1:1
	ds_read2_b32 v[132:133], v132 offset1:1
	ds_read2_b32 v[134:135], v134 offset1:1
	ds_read2_b32 v[136:137], v123 offset1:1
	ds_read2_b32 v[138:139], v138 offset1:1
	ds_read2_b32 v[140:141], v140 offset1:1
	ds_read2_b32 v[142:143], v142 offset1:1
	s_waitcnt lgkmcnt(0)
	v_add_f32_e32 v78, v78, v134
	v_add_f32_e32 v79, v79, v135
	v_add_f32_e32 v76, v76, v132
	v_add_f32_e32 v77, v77, v133
	v_add_f32_e32 v74, v74, v126
	v_add_f32_e32 v75, v75, v127
	v_add_f32_e32 v72, v72, v124
	v_add_f32_e32 v73, v73, v125
	v_add_f32_e32 v70, v70, v142
	v_add_f32_e32 v71, v71, v143
	v_add_f32_e32 v68, v68, v140
	v_add_f32_e32 v69, v69, v141
	v_add_f32_e32 v66, v66, v138
	v_add_f32_e32 v67, v67, v139
	v_add_f32_e32 v64, v64, v136
	v_add_f32_e32 v65, v65, v137
	s_branch .Lhw_d0_b_n1924
.Lhw_d0_b_dtd0bias2:
	v_add_u32_e32 v122, s7, v119
	v_add_u32_e32 v136, 0x28988, v122
	v_add_u32_e32 v138, 0x289a0, v122
	v_add_u32_e32 v140, 0x289a8, v122
	v_add_u32_e32 v123, 0x289c0, v122
	v_add_u32_e32 v124, 0x289c8, v122
	v_add_u32_e32 v126, 0x289e0, v122
	v_add_u32_e32 v132, 0x289e8, v122
	v_add_u32_e32 v121, 0x28980, v122
	ds_read2_b32 v[122:123], v123 offset1:1
	ds_read2_b32 v[124:125], v124 offset1:1
	ds_read2_b32 v[126:127], v126 offset1:1
	ds_read2_b32 v[132:133], v132 offset1:1
	ds_read2_b32 v[134:135], v121 offset1:1
	ds_read2_b32 v[136:137], v136 offset1:1
	ds_read2_b32 v[138:139], v138 offset1:1
	ds_read2_b32 v[140:141], v140 offset1:1
	s_waitcnt lgkmcnt(0)
	v_add_f32_e32 v78, v78, v132
	v_add_f32_e32 v79, v79, v133
	v_add_f32_e32 v76, v76, v126
	v_add_f32_e32 v77, v77, v127
	v_add_f32_e32 v74, v74, v124
	v_add_f32_e32 v75, v75, v125
	v_add_f32_e32 v72, v72, v122
	v_add_f32_e32 v73, v73, v123
	v_add_f32_e32 v70, v70, v140
	v_add_f32_e32 v71, v71, v141
	v_add_f32_e32 v68, v68, v138
	v_add_f32_e32 v69, v69, v139
	v_add_f32_e32 v66, v66, v136
	v_add_f32_e32 v67, v67, v137
	v_add_f32_e32 v64, v64, v134
	v_add_f32_e32 v65, v65, v135
	v_lshl_add_u32 v121, s64, 14, v106
	s_branch .Lhw_d0_b_n1926

; #define SBAR() __builtin_amdgcn_sched_barrier(0)
; DI int v_rd_base(int lane) { return ((lane & 3) << 3) | (((lane >> 2) & 3) << 6) | (((lane >> 4) & 1) << 5) | (((lane >> 5) & 1) << 8); }
; #define ATT_DMA_K(t) do { const bf16_t* kg_ = Kh + (size_t)(t) * 64 * LDK; LAS unsigned char* sb_ = lds + ((t) & 3) * KBUF; \
;     _Pragma("unroll") for (int i_ = 0; i_ < NKP; ++i_) __builtin_amdgcn_global_load_lds((const unsigned*)(kg_ + kgo[i_]), (LAS unsigned*)(sb_ + (wid + 8 * i_) * 1024), 16, 0, 0); } while (0)
; #define ATT_DMA_V(t, vs) do { const bf16_t* vg_ = Vh + (size_t)(t) * 64 * LDV; LAS unsigned char* sb_ = lds + V_OFF + (vs) * SHM_V; \
;     _Pragma("unroll") for (int i_ = 0; i_ < 2; ++i_) __builtin_amdgcn_global_load_lds((const unsigned*)(vg_ + vgo[i_]), (LAS unsigned*)(sb_ + (2 * wid + i_) * 1024), 16, 0, 0); } while (0)
; #define ATT_SEG(t) do { if constexpr (MODE != 0) { if (((t) == tL && tL > 0) || (t) == tR) { const float f_ = (t) == tR ? fR : fL; l_reg *= f_; \
;     _Pragma("unroll") for (int d = 0; d < 4; ++d) _Pragma("unroll") for (int r = 0; r < 16; ++r) o[d][r] *= f_; } } } while (0)
; template <int DQK, int MODE, int LDQ, int LDK, int LDV> ...
;     ...
;     const int vbase = (int)(unsigned)(size_t)lds + V_OFF + v_rd_base(lane);
;     ...
;     constexpr int NDA = ND0 > 6 ? 6 : ND0;
;     ...
;         if (j + 3 < NT) ATT_DMA_K(j + 3);
;         if (j + 2 < NT) ATT_DMA_V(j + 2, v2);
;         ATT_SEG(j); SBAR();
;         ATT_STEP(pA, pB, 0, v0, true, 1, j);
;         ATT_STEP(pB, pA, 1, v0, (j + 1 < NT), 0, j + 1);
.Lstg_d0_t61_12:
	s_setprio 0
	v_lshl_add_u64 v[96:97], v[96:97], 1, s[56:57]
	s_mov_b32 m0, s0
	v_lshl_add_u64 v[98:99], v[98:99], 1, s[56:57]
	global_load_lds_dwordx4 v[96:97], off
	s_mov_b32 m0, s1
	s_cmp_lg_u32 s55, 61
	global_load_lds_dwordx4 v[98:99], off
	s_cselect_b64 s[0:1], -1, 0
	s_cmp_eq_u32 s58, 61
	s_cselect_b64 s[2:3], -1, 0
	s_cmp_lg_u32 s58, 61
	s_cselect_b64 s[4:5], -1, 0
	s_and_b64 s[0:1], s[4:5], s[0:1]
	s_and_b64 vcc, exec, s[0:1]
	s_cbranch_vccnz .LBB0_1930
	v_cndmask_b32_e64 v96, v112, v113, s[2:3]
	v_mul_f32_e32 v14, v14, v96
	v_mul_f32_e32 v15, v15, v96
	v_mul_f32_e32 v12, v12, v96
	v_mul_f32_e32 v13, v13, v96
	v_mul_f32_e32 v10, v10, v96
	v_mul_f32_e32 v11, v11, v96
	v_mul_f32_e32 v8, v8, v96
	v_mul_f32_e32 v9, v9, v96
	v_mul_f32_e32 v6, v6, v96
	v_mul_f32_e32 v7, v7, v96
	v_mul_f32_e32 v4, v4, v96
	v_mul_f32_e32 v5, v5, v96
	v_mul_f32_e32 v2, v2, v96
	v_mul_f32_e32 v3, v3, v96
	v_mul_f32_e32 v0, v0, v96
	v_mul_f32_e32 v1, v1, v96
	v_mul_f32_e32 v62, v62, v96
	v_mul_f32_e32 v63, v63, v96
	v_mul_f32_e32 v60, v60, v96
	v_mul_f32_e32 v61, v61, v96
	v_mul_f32_e32 v58, v58, v96
	v_mul_f32_e32 v59, v59, v96
	v_mul_f32_e32 v56, v56, v96
	v_mul_f32_e32 v57, v57, v96
	v_mul_f32_e32 v54, v54, v96
	v_mul_f32_e32 v55, v55, v96
	v_mul_f32_e32 v52, v52, v96
	v_mul_f32_e32 v53, v53, v96
	v_mul_f32_e32 v50, v50, v96
	v_mul_f32_e32 v51, v51, v96
	v_mul_f32_e32 v48, v48, v96
	v_mul_f32_e32 v49, v49, v96
	v_mul_f32_e32 v46, v46, v96
	v_mul_f32_e32 v47, v47, v96
	v_mul_f32_e32 v44, v44, v96
	v_mul_f32_e32 v45, v45, v96
	v_mul_f32_e32 v42, v42, v96
	v_mul_f32_e32 v43, v43, v96
	v_mul_f32_e32 v40, v40, v96
	v_mul_f32_e32 v41, v41, v96
	v_mul_f32_e32 v38, v38, v96
	v_mul_f32_e32 v39, v39, v96
	v_mul_f32_e32 v36, v36, v96
	v_mul_f32_e32 v37, v37, v96
	v_mul_f32_e32 v34, v34, v96
	v_mul_f32_e32 v35, v35, v96
	v_mul_f32_e32 v32, v32, v96
	v_mul_f32_e32 v33, v33, v96
	v_mul_f32_e32 v30, v30, v96
	v_mul_f32_e32 v31, v31, v96
	v_mul_f32_e32 v28, v28, v96
	v_mul_f32_e32 v29, v29, v96
	v_mul_f32_e32 v26, v26, v96
	v_mul_f32_e32 v27, v27, v96
	v_mul_f32_e32 v24, v24, v96
	v_mul_f32_e32 v25, v25, v96
	v_mul_f32_e32 v22, v22, v96
	v_mul_f32_e32 v23, v23, v96
	v_mul_f32_e32 v20, v20, v96
	v_mul_f32_e32 v21, v21, v96
	v_mul_f32_e32 v18, v18, v96
	v_mul_f32_e32 v19, v19, v96
	v_mul_f32_e32 v16, v16, v96
	v_mul_f32_e32 v17, v17, v96
	v_mul_f32_e32 v120, v120, v96
.LBB0_1930:
	s_mov_b64 s[96:97], 0xc00
	ds_read_b128 v[98:101], v107 offset:12288
	ds_read_b128 v[102:105], v108 offset:12288
	ds_read_b128 v[114:117], v109 offset:12288
	ds_read_b128 v[122:125], v110 offset:12288
	v_lshl_add_u32 v96, s64, 14, v106
	ds_read_b64_tr_b16 v[132:133], v96 offset:0
	ds_read_b64_tr_b16 v[134:135], v96 offset:0x800
	ds_read_b64_tr_b16 v[136:137], v96 offset:0x1000
	ds_read_b64_tr_b16 v[138:139], v96 offset:0x1800
	ds_read_b64_tr_b16 v[140:141], v96 offset:0x200
	ds_read_b64_tr_b16 v[142:143], v96 offset:0xa00
	ds_read_b64_tr_b16 v[144:145], v96 offset:0x1200
	ds_read_b64_tr_b16 v[146:147], v96 offset:0x1a00
	ds_read_b64_tr_b16 v[148:149], v96 offset:0x400
	ds_read_b64_tr_b16 v[150:151], v96 offset:0xc00
	ds_read_b64_tr_b16 v[152:153], v96 offset:0x1400
	ds_read_b64_tr_b16 v[154:155], v96 offset:0x1c00
	ds_read_b64_tr_b16 v[156:157], v96 offset:0x600
	ds_read_b64_tr_b16 v[158:159], v96 offset:0xe00
	ds_read_b64_tr_b16 v[162:163], v96 offset:0x1600
	ds_read_b64_tr_b16 v[164:165], v96 offset:0x1e00
	s_setprio 1
	v_exp_f32_e32 v64, v64
	v_exp_f32_e32 v65, v65
	v_exp_f32_e32 v66, v66
	v_exp_f32_e32 v67, v67
	v_exp_f32_e32 v68, v68
	v_exp_f32_e32 v69, v69
	v_add_f32_e32 v97, v65, v64
	v_exp_f32_e32 v70, v70
	v_add_f32_e32 v97, v66, v97
	v_exp_f32_e32 v71, v71
	v_add_f32_e32 v97, v67, v97
	v_exp_f32_e32 v72, v72
	v_add_f32_e32 v97, v68, v97
	v_exp_f32_e32 v73, v73
	v_add_f32_e32 v97, v69, v97
	v_exp_f32_e32 v74, v74
	v_add_f32_e32 v97, v70, v97
	v_exp_f32_e32 v75, v75
	v_add_f32_e32 v97, v71, v97
	v_exp_f32_e32 v76, v76
	v_add_f32_e32 v97, v72, v97
	v_exp_f32_e32 v77, v77
	v_add_f32_e32 v97, v73, v97
	v_exp_f32_e32 v78, v78
	v_add_f32_e32 v97, v74, v97
	v_exp_f32_e32 v79, v79
	v_add_f32_e32 v97, v75, v97
	v_add_f32_e32 v97, v76, v97
	v_add_f32_e32 v97, v77, v97
	v_add_f32_e32 v97, v78, v97
	v_add_f32_e32 v97, v79, v97
	v_add_f32_e32 v97, v97, v120
	v_cvt_pk_bf16_f32 v64, v64, v65
	v_cvt_pk_bf16_f32 v65, v66, v67
	v_cvt_pk_bf16_f32 v66, v68, v69
	v_cvt_pk_bf16_f32 v67, v70, v71
	v_cvt_pk_bf16_f32 v68, v72, v73
	v_cvt_pk_bf16_f32 v69, v74, v75
	v_cvt_pk_bf16_f32 v70, v76, v77
	v_cvt_pk_bf16_f32 v71, v78, v79
	s_waitcnt lgkmcnt(0)
	s_setprio 2
	v_mfma_f32_32x32x16_bf16 v[0:15], v[64:67], v[132:135], v[0:15]
	s_cmp_gt_i32 s55, 61
	s_cselect_b64 s[0:1], -1, 0
	s_cmp_lt_i32 s58, 62
	s_cselect_b64 s[2:3], -1, 0
	s_or_b64 s[0:1], s[0:1], s[2:3]
	s_and_b64 vcc, exec, s[0:1]
	v_mfma_f32_32x32x16_bf16 v[48:63], v[64:67], v[140:143], v[48:63]
	v_mfma_f32_32x32x16_bf16 v[32:47], v[64:67], v[148:151], v[32:47]
	v_mfma_f32_32x32x16_bf16 v[16:31], v[64:67], v[156:159], v[16:31]
	v_mfma_f32_32x32x16_bf16 v[0:15], v[68:71], v[136:139], v[0:15]
	v_mfma_f32_32x32x16_bf16 v[48:63], v[68:71], v[144:147], v[48:63]
	v_mfma_f32_32x32x16_bf16 v[32:47], v[68:71], v[152:155], v[32:47]
	v_mfma_f32_32x32x16_bf16 v[16:31], v[68:71], v[162:165], v[16:31]
	s_waitcnt lgkmcnt(0)
	v_mfma_f32_32x32x16_bf16 v[64:79], v[98:101], v[92:95], 0
	v_mfma_f32_32x32x16_bf16 v[64:79], v[102:105], v[88:91], v[64:79]
	v_mfma_f32_32x32x16_bf16 v[64:79], v[114:117], v[84:87], v[64:79]
	v_mfma_f32_32x32x16_bf16 v[64:79], v[122:125], v[80:83], v[64:79]
	s_setprio 0
	s_cbranch_vccnz .LBB0_1932
	v_sub_u32_e32 v98, 0xf40, v111
	v_lshlrev_b32_e32 v98, 2, v98
	v_add3_u32 v98, s88, v98, v130
	v_add_u32_e32 v114, 0x400, v98
	v_add_u32_e32 v116, 0x408, v98
	v_add_u32_e32 v118, 0x420, v98
	v_add_u32_e32 v120, 0x428, v98
	v_add_u32_e32 v99, 0x440, v98
	v_add_u32_e32 v100, 0x448, v98
	v_add_u32_e32 v102, 0x460, v98
	v_add_u32_e32 v104, 0x468, v98
	ds_read2_b32 v[98:99], v99 offset1:1
	ds_read2_b32 v[100:101], v100 offset1:1
	ds_read2_b32 v[102:103], v102 offset1:1
	ds_read2_b32 v[104:105], v104 offset1:1
	ds_read2_b32 v[114:115], v114 offset1:1
	ds_read2_b32 v[116:117], v116 offset1:1
	ds_read2_b32 v[118:119], v118 offset1:1
	ds_read2_b32 v[120:121], v120 offset1:1
	s_waitcnt lgkmcnt(0)
	v_add_f32_e32 v78, v78, v104
	v_add_f32_e32 v79, v79, v105
	v_add_f32_e32 v76, v76, v102
	v_add_f32_e32 v77, v77, v103
	v_add_f32_e32 v74, v74, v100
	v_add_f32_e32 v75, v75, v101
	v_add_f32_e32 v72, v72, v98
	v_add_f32_e32 v73, v73, v99
	v_add_f32_e32 v70, v70, v120
	v_add_f32_e32 v71, v71, v121
	v_add_f32_e32 v68, v68, v118
	v_add_f32_e32 v69, v69, v119
	v_add_f32_e32 v66, v66, v116
	v_add_f32_e32 v67, v67, v117
	v_add_f32_e32 v64, v64, v114
	v_add_f32_e32 v65, v65, v115

.Lstg_d0_m61_13:
	v_mfma_f32_32x32x16_bf16 v[0:15], v[64:67], v[122:125], v[0:15]
	s_cmp_lt_i32 s55, 63
	s_cselect_b64 s[0:1], -1, 0
	s_cmp_gt_i32 s58, 62
	s_cselect_b64 s[2:3], -1, 0
	s_and_b64 s[0:1], s[0:1], s[2:3]
	v_cndmask_b32_e64 v97, 0, 1, s[0:1]
	v_cmp_ne_u32_e64 s[2:3], 1, v97
	v_mfma_f32_32x32x16_bf16 v[48:63], v[64:67], v[136:139], v[48:63]
	v_sub_u32_e32 v97, 0xf80, v111
	s_andn2_b64 vcc, exec, s[0:1]
	v_lshlrev_b32_e32 v97, 2, v97
	v_mfma_f32_32x32x16_bf16 v[32:47], v[64:67], v[144:147], v[32:47]
	v_mfma_f32_32x32x16_bf16 v[16:31], v[64:67], v[152:155], v[16:31]
	v_mfma_f32_32x32x16_bf16 v[0:15], v[68:71], v[132:135], v[0:15]
	v_mfma_f32_32x32x16_bf16 v[48:63], v[68:71], v[140:143], v[48:63]
	v_mfma_f32_32x32x16_bf16 v[32:47], v[68:71], v[148:151], v[32:47]
	v_mfma_f32_32x32x16_bf16 v[16:31], v[68:71], v[156:159], v[16:31]
	s_waitcnt lgkmcnt(0)
	v_mfma_f32_32x32x16_bf16 v[64:79], v[98:101], v[92:95], 0
	v_mfma_f32_32x32x16_bf16 v[64:79], v[102:105], v[88:91], v[64:79]
	v_mfma_f32_32x32x16_bf16 v[64:79], v[114:117], v[84:87], v[64:79]
	v_mfma_f32_32x32x16_bf16 v[64:79], v[118:121], v[80:83], v[64:79]
	s_cbranch_vccnz .LBB0_1934
	v_add3_u32 v120, s88, v97, v130
	ds_read2_b32 v[98:99], v120 offset0:240 offset1:241
	ds_read2_b32 v[100:101], v120 offset0:242 offset1:243
	ds_read2_b32 v[102:103], v120 offset0:248 offset1:249
	ds_read2_b32 v[104:105], v120 offset0:250 offset1:251
	ds_read2_b32 v[114:115], v120 offset0:224 offset1:225
	ds_read2_b32 v[116:117], v120 offset0:226 offset1:227
	ds_read2_b32 v[118:119], v120 offset0:232 offset1:233
	ds_read2_b32 v[120:121], v120 offset0:234 offset1:235
	s_waitcnt lgkmcnt(0)
	s_nop 0
	v_add_f32_e32 v78, v78, v104
	v_add_f32_e32 v79, v79, v105
	v_add_f32_e32 v76, v76, v102
	v_add_f32_e32 v77, v77, v103
	v_add_f32_e32 v74, v74, v100
	v_add_f32_e32 v75, v75, v101
	v_add_f32_e32 v72, v72, v98
	v_add_f32_e32 v73, v73, v99
	v_add_f32_e32 v70, v70, v120
	v_add_f32_e32 v71, v71, v121
	v_add_f32_e32 v68, v68, v118
	v_add_f32_e32 v69, v69, v119
	v_add_f32_e32 v66, v66, v116
	v_add_f32_e32 v67, v67, v117
	v_add_f32_e32 v64, v64, v114
	v_add_f32_e32 v65, v65, v115

.LBB0_1936:
	ds_read_b128 v[100:103], v107 offset:20480
	ds_read_b128 v[114:117], v108 offset:20480
	ds_read_b128 v[118:121], v109 offset:20480
	ds_read_b128 v[122:125], v110 offset:20480
	v_add_u32_e32 v98, 0x8000, v106
	ds_read_b64_tr_b16 v[132:133], v98 offset:0
	ds_read_b64_tr_b16 v[134:135], v98 offset:0x800
	ds_read_b64_tr_b16 v[136:137], v98 offset:0x1000
	ds_read_b64_tr_b16 v[138:139], v98 offset:0x1800
	ds_read_b64_tr_b16 v[140:141], v98 offset:0x200
	ds_read_b64_tr_b16 v[142:143], v98 offset:0xa00
	ds_read_b64_tr_b16 v[144:145], v98 offset:0x1200
	ds_read_b64_tr_b16 v[146:147], v98 offset:0x1a00
	ds_read_b64_tr_b16 v[148:149], v98 offset:0x400
	ds_read_b64_tr_b16 v[150:151], v98 offset:0xc00
	ds_read_b64_tr_b16 v[152:153], v98 offset:0x1400
	ds_read_b64_tr_b16 v[154:155], v98 offset:0x1c00
	ds_read_b64_tr_b16 v[156:157], v98 offset:0x600
	ds_read_b64_tr_b16 v[158:159], v98 offset:0xe00
	ds_read_b64_tr_b16 v[162:163], v98 offset:0x1600
	ds_read_b64_tr_b16 v[164:165], v98 offset:0x1e00
	s_setprio 1
	v_exp_f32_e32 v64, v64
	v_exp_f32_e32 v65, v65
	v_exp_f32_e32 v66, v66
	v_exp_f32_e32 v67, v67
	v_exp_f32_e32 v68, v68
	v_exp_f32_e32 v69, v69
	v_add_f32_e32 v99, v65, v64
	v_exp_f32_e32 v70, v70
	v_add_f32_e32 v99, v66, v99
	v_exp_f32_e32 v71, v71
	v_add_f32_e32 v99, v67, v99
	v_exp_f32_e32 v72, v72
	v_add_f32_e32 v99, v68, v99
	v_exp_f32_e32 v73, v73
	v_add_f32_e32 v99, v69, v99
	v_exp_f32_e32 v74, v74
	v_add_f32_e32 v99, v70, v99
	v_exp_f32_e32 v75, v75
	v_add_f32_e32 v99, v71, v99
	v_exp_f32_e32 v76, v76
	v_add_f32_e32 v99, v72, v99
	v_exp_f32_e32 v77, v77
	v_add_f32_e32 v99, v73, v99
	v_exp_f32_e32 v78, v78
	v_add_f32_e32 v99, v74, v99
	v_exp_f32_e32 v79, v79
	v_add_f32_e32 v99, v75, v99
	v_add_f32_e32 v99, v76, v99
	v_add_f32_e32 v99, v77, v99
	v_add_f32_e32 v99, v78, v99
	v_add_f32_e32 v99, v79, v99
	v_add_f32_e32 v96, v99, v96
	v_cvt_pk_bf16_f32 v64, v64, v65
	v_cvt_pk_bf16_f32 v65, v66, v67
	v_cvt_pk_bf16_f32 v66, v68, v69
	v_cvt_pk_bf16_f32 v67, v70, v71
	v_cvt_pk_bf16_f32 v68, v72, v73
	v_cvt_pk_bf16_f32 v69, v74, v75
	v_cvt_pk_bf16_f32 v70, v76, v77
	v_cvt_pk_bf16_f32 v71, v78, v79
	s_waitcnt lgkmcnt(0)
	s_setprio 2
	v_mfma_f32_32x32x16_bf16 v[0:15], v[64:67], v[132:135], v[0:15]
	s_and_b64 vcc, exec, s[2:3]
	v_mfma_f32_32x32x16_bf16 v[48:63], v[64:67], v[140:143], v[48:63]
	v_mfma_f32_32x32x16_bf16 v[32:47], v[64:67], v[148:151], v[32:47]
	v_mfma_f32_32x32x16_bf16 v[16:31], v[64:67], v[156:159], v[16:31]
	v_mfma_f32_32x32x16_bf16 v[0:15], v[68:71], v[136:139], v[0:15]
	v_mfma_f32_32x32x16_bf16 v[48:63], v[68:71], v[144:147], v[48:63]
	v_mfma_f32_32x32x16_bf16 v[32:47], v[68:71], v[152:155], v[32:47]
	v_mfma_f32_32x32x16_bf16 v[16:31], v[68:71], v[162:165], v[16:31]
	s_waitcnt lgkmcnt(0)
	v_mfma_f32_32x32x16_bf16 v[64:79], v[100:103], v[92:95], 0
	v_mfma_f32_32x32x16_bf16 v[64:79], v[114:117], v[88:91], v[64:79]
	v_mfma_f32_32x32x16_bf16 v[64:79], v[118:121], v[84:87], v[64:79]
	v_mfma_f32_32x32x16_bf16 v[64:79], v[122:125], v[80:83], v[64:79]
	s_setprio 0
	s_cbranch_vccnz .LBB0_1938
	v_add3_u32 v97, s88, v97, v130
	v_add_u32_e32 v118, 0x408, v97
	v_add_u32_e32 v120, 0x420, v97
	v_add_u32_e32 v122, 0x428, v97
	v_add_u32_e32 v100, 0x440, v97
	v_add_u32_e32 v102, 0x448, v97
	v_add_u32_e32 v104, 0x460, v97
	v_add_u32_e32 v99, 0x400, v97
	v_add_u32_e32 v97, 0x468, v97
	ds_read2_b32 v[100:101], v100 offset1:1
	ds_read2_b32 v[102:103], v102 offset1:1
	ds_read2_b32 v[104:105], v104 offset1:1
	ds_read2_b32 v[114:115], v97 offset1:1
	ds_read2_b32 v[116:117], v99 offset1:1
	ds_read2_b32 v[118:119], v118 offset1:1
	ds_read2_b32 v[120:121], v120 offset1:1
	ds_read2_b32 v[122:123], v122 offset1:1
	s_waitcnt lgkmcnt(0)
	v_add_f32_e32 v78, v78, v114
	v_add_f32_e32 v79, v79, v115
	v_add_f32_e32 v76, v76, v104
	v_add_f32_e32 v77, v77, v105
	v_add_f32_e32 v74, v74, v102
	v_add_f32_e32 v75, v75, v103
	v_add_f32_e32 v72, v72, v100
	v_add_f32_e32 v73, v73, v101
	v_add_f32_e32 v70, v70, v122
	v_add_f32_e32 v71, v71, v123
	v_add_f32_e32 v68, v68, v120
	v_add_f32_e32 v69, v69, v121
	v_add_f32_e32 v66, v66, v118
	v_add_f32_e32 v67, v67, v119
	v_add_f32_e32 v64, v64, v116
	v_add_f32_e32 v65, v65, v117

.Lstg_d0_m62_15:
	v_mfma_f32_32x32x16_bf16 v[0:15], v[64:67], v[132:135], v[0:15]
	s_cmp_lt_i32 s55, 64
	s_cselect_b64 s[0:1], -1, 0
	s_cmp_gt_i32 s58, 63
	s_cselect_b64 s[2:3], -1, 0
	s_and_b64 s[0:1], s[2:3], s[0:1]
	v_cndmask_b32_e64 v97, 0, 1, s[0:1]
	v_cmp_ne_u32_e64 s[2:3], 1, v97
	v_mfma_f32_32x32x16_bf16 v[48:63], v[64:67], v[140:143], v[48:63]
	v_sub_u32_e32 v97, 0xfc0, v111
	s_andn2_b64 vcc, exec, s[0:1]
	v_lshlrev_b32_e32 v97, 2, v97
	v_mfma_f32_32x32x16_bf16 v[32:47], v[64:67], v[148:151], v[32:47]
	v_mfma_f32_32x32x16_bf16 v[16:31], v[64:67], v[156:159], v[16:31]
	v_mfma_f32_32x32x16_bf16 v[0:15], v[68:71], v[136:139], v[0:15]
	v_mfma_f32_32x32x16_bf16 v[48:63], v[68:71], v[144:147], v[48:63]
	v_mfma_f32_32x32x16_bf16 v[32:47], v[68:71], v[152:155], v[32:47]
	v_mfma_f32_32x32x16_bf16 v[16:31], v[68:71], v[162:165], v[16:31]
	s_waitcnt lgkmcnt(0)
	v_mfma_f32_32x32x16_bf16 v[64:79], v[100:103], v[92:95], 0
	v_mfma_f32_32x32x16_bf16 v[64:79], v[114:117], v[88:91], v[64:79]
	v_mfma_f32_32x32x16_bf16 v[64:79], v[118:121], v[84:87], v[64:79]
	v_mfma_f32_32x32x16_bf16 v[64:79], v[122:125], v[80:83], v[64:79]
	s_cbranch_vccnz .LBB0_1940
	v_add3_u32 v111, s88, v97, v130
	ds_read2_b32 v[98:99], v111 offset0:240 offset1:241
	ds_read2_b32 v[100:101], v111 offset0:242 offset1:243
	ds_read2_b32 v[102:103], v111 offset0:248 offset1:249
	ds_read2_b32 v[104:105], v111 offset0:250 offset1:251
	ds_read2_b32 v[114:115], v111 offset0:224 offset1:225
	ds_read2_b32 v[116:117], v111 offset0:226 offset1:227
	ds_read2_b32 v[118:119], v111 offset0:232 offset1:233
	ds_read2_b32 v[120:121], v111 offset0:234 offset1:235
	s_waitcnt lgkmcnt(0)
	s_nop 0
	v_add_f32_e32 v78, v78, v104
	v_add_f32_e32 v79, v79, v105
	v_add_f32_e32 v76, v76, v102
	v_add_f32_e32 v77, v77, v103
	v_add_f32_e32 v74, v74, v100
	v_add_f32_e32 v75, v75, v101
	v_add_f32_e32 v72, v72, v98
	v_add_f32_e32 v73, v73, v99
	v_add_f32_e32 v70, v70, v120
	v_add_f32_e32 v71, v71, v121
	v_add_f32_e32 v68, v68, v118
	v_add_f32_e32 v69, v69, v119
	v_add_f32_e32 v66, v66, v116
	v_add_f32_e32 v67, v67, v117
	v_add_f32_e32 v64, v64, v114
	v_add_f32_e32 v65, v65, v115

; template <int DQK, int MODE, int LDQ, int LDK, int LDV> ...
;     ...
;         ATT_STEP(pA, pB, 0, v0, true, 1, j);
;         ATT_STEP(pB, pA, 1, v0, (j + 1 < NT), 0, j + 1);
.LBB0_1942:
	ds_read_b128 v[98:101], v107 offset:28672
	ds_read_b128 v[102:105], v108 offset:28672
	ds_read_b128 v[112:115], v109 offset:28672
	ds_read_b128 v[108:111], v110 offset:28672
	ds_read_b64_tr_b16 v[116:117], v106 offset:0
	ds_read_b64_tr_b16 v[118:119], v106 offset:0x800
	ds_read_b64_tr_b16 v[120:121], v106 offset:0x1000
	ds_read_b64_tr_b16 v[122:123], v106 offset:0x1800
	ds_read_b64_tr_b16 v[124:125], v106 offset:0x200
	ds_read_b64_tr_b16 v[126:127], v106 offset:0xa00
	ds_read_b64_tr_b16 v[132:133], v106 offset:0x1200
	ds_read_b64_tr_b16 v[134:135], v106 offset:0x1a00
	ds_read_b64_tr_b16 v[136:137], v106 offset:0x400
	ds_read_b64_tr_b16 v[138:139], v106 offset:0xc00
	ds_read_b64_tr_b16 v[140:141], v106 offset:0x1400
	ds_read_b64_tr_b16 v[142:143], v106 offset:0x1c00
	ds_read_b64_tr_b16 v[144:145], v106 offset:0x600
	ds_read_b64_tr_b16 v[146:147], v106 offset:0xe00
	ds_read_b64_tr_b16 v[148:149], v106 offset:0x1600
	ds_read_b64_tr_b16 v[150:151], v106 offset:0x1e00
	s_setprio 1
	v_exp_f32_e32 v64, v64
	v_exp_f32_e32 v65, v65
	v_exp_f32_e32 v66, v66
	v_exp_f32_e32 v67, v67
	v_exp_f32_e32 v68, v68
	v_exp_f32_e32 v69, v69
	v_add_f32_e32 v107, v65, v64
	v_exp_f32_e32 v70, v70
	v_add_f32_e32 v107, v66, v107
	v_exp_f32_e32 v71, v71
	v_add_f32_e32 v107, v67, v107
	v_exp_f32_e32 v72, v72
	v_add_f32_e32 v107, v68, v107
	v_exp_f32_e32 v73, v73
	v_add_f32_e32 v107, v69, v107
	v_exp_f32_e32 v74, v74
	v_add_f32_e32 v107, v70, v107
	v_exp_f32_e32 v75, v75
	v_add_f32_e32 v107, v71, v107
	v_exp_f32_e32 v76, v76
	v_add_f32_e32 v107, v72, v107
	v_exp_f32_e32 v77, v77
	v_add_f32_e32 v107, v73, v107
	v_exp_f32_e32 v78, v78
	v_add_f32_e32 v107, v74, v107
	v_exp_f32_e32 v79, v79
	v_add_f32_e32 v107, v75, v107
	v_add_f32_e32 v107, v76, v107
	v_add_f32_e32 v107, v77, v107
	v_add_f32_e32 v107, v78, v107
	v_add_f32_e32 v107, v79, v107
	v_add_f32_e32 v96, v107, v96
	v_cvt_pk_bf16_f32 v64, v64, v65
	v_cvt_pk_bf16_f32 v65, v66, v67
	v_cvt_pk_bf16_f32 v66, v68, v69
	v_cvt_pk_bf16_f32 v67, v70, v71
	v_cvt_pk_bf16_f32 v68, v72, v73
	v_cvt_pk_bf16_f32 v69, v74, v75
	v_cvt_pk_bf16_f32 v70, v76, v77
	v_cvt_pk_bf16_f32 v71, v78, v79
	s_waitcnt lgkmcnt(0)
	s_setprio 2
	v_mfma_f32_32x32x16_bf16 v[0:15], v[64:67], v[116:119], v[0:15]
	s_and_b64 vcc, exec, s[2:3]
	v_mfma_f32_32x32x16_bf16 v[48:63], v[64:67], v[124:127], v[48:63]
	v_mfma_f32_32x32x16_bf16 v[32:47], v[64:67], v[136:139], v[32:47]
	v_mfma_f32_32x32x16_bf16 v[16:31], v[64:67], v[144:147], v[16:31]
	v_mfma_f32_32x32x16_bf16 v[0:15], v[68:71], v[120:123], v[0:15]
	v_mfma_f32_32x32x16_bf16 v[48:63], v[68:71], v[132:135], v[48:63]
	v_mfma_f32_32x32x16_bf16 v[32:47], v[68:71], v[140:143], v[32:47]
	v_mfma_f32_32x32x16_bf16 v[16:31], v[68:71], v[148:151], v[16:31]
	s_waitcnt lgkmcnt(0)
	v_mfma_f32_32x32x16_bf16 v[64:79], v[98:101], v[92:95], 0
	v_mfma_f32_32x32x16_bf16 v[64:79], v[102:105], v[88:91], v[64:79]
	v_mfma_f32_32x32x16_bf16 v[64:79], v[112:115], v[84:87], v[64:79]
	v_mfma_f32_32x32x16_bf16 v[64:79], v[108:111], v[80:83], v[64:79]
	s_setprio 0
	s_cbranch_vccnz .LBB0_1944
	v_add3_u32 v80, s88, v97, v130
	v_add_u32_e32 v88, 0x400, v80
	v_add_u32_e32 v90, 0x408, v80
	v_add_u32_e32 v92, 0x420, v80
	v_add_u32_e32 v94, 0x428, v80
	v_add_u32_e32 v81, 0x440, v80
	v_add_u32_e32 v82, 0x448, v80
	v_add_u32_e32 v84, 0x460, v80
	v_add_u32_e32 v86, 0x468, v80
	ds_read2_b32 v[80:81], v81 offset1:1
	ds_read2_b32 v[82:83], v82 offset1:1
	ds_read2_b32 v[84:85], v84 offset1:1
	ds_read2_b32 v[86:87], v86 offset1:1
	ds_read2_b32 v[88:89], v88 offset1:1
	ds_read2_b32 v[90:91], v90 offset1:1
	ds_read2_b32 v[92:93], v92 offset1:1
	ds_read2_b32 v[94:95], v94 offset1:1
	s_waitcnt lgkmcnt(0)
	v_add_f32_e32 v78, v78, v86
	v_add_f32_e32 v79, v79, v87
	v_add_f32_e32 v76, v76, v84
	v_add_f32_e32 v77, v77, v85
	v_add_f32_e32 v74, v74, v82
	v_add_f32_e32 v75, v75, v83
	v_add_f32_e32 v72, v72, v80
	v_add_f32_e32 v73, v73, v81
	v_add_f32_e32 v70, v70, v94
	v_add_f32_e32 v71, v71, v95
	v_add_f32_e32 v68, v68, v92
	v_add_f32_e32 v69, v69, v93
	v_add_f32_e32 v66, v66, v90
	v_add_f32_e32 v67, v67, v91
	v_add_f32_e32 v64, v64, v88
	v_add_f32_e32 v65, v65, v89
.LBB0_1944:
	s_lshl_b32 s0, s54, 2
	s_add_i32 s0, s0, 0
	s_add_i32 s0, s0, 0x24000
	ds_read_b64_tr_b16 v[80:81], v106 offset:0x2000
	ds_read_b64_tr_b16 v[82:83], v106 offset:0x2800
	ds_read_b64_tr_b16 v[84:85], v106 offset:0x3000
	ds_read_b64_tr_b16 v[86:87], v106 offset:0x3800
	ds_read_b64_tr_b16 v[88:89], v106 offset:0x2200
	ds_read_b64_tr_b16 v[90:91], v106 offset:0x2a00
	ds_read_b64_tr_b16 v[92:93], v106 offset:0x3200
	ds_read_b64_tr_b16 v[94:95], v106 offset:0x3a00
	ds_read_b64_tr_b16 v[98:99], v106 offset:0x2400
	ds_read_b64_tr_b16 v[100:101], v106 offset:0x2c00
	ds_read_b64_tr_b16 v[102:103], v106 offset:0x3400
	ds_read_b64_tr_b16 v[104:105], v106 offset:0x3c00
	ds_read_b64_tr_b16 v[108:109], v106 offset:0x2600
	ds_read_b64_tr_b16 v[110:111], v106 offset:0x2e00
	ds_read_b64_tr_b16 v[112:113], v106 offset:0x3600
	ds_read_b64_tr_b16 v[114:115], v106 offset:0x3e00
	s_nop 7
	s_setprio 1
	v_exp_f32_e32 v97, v64
	v_exp_f32_e32 v65, v65
	v_exp_f32_e32 v106, v66
	v_exp_f32_e32 v67, v67
	v_exp_f32_e32 v68, v68
	v_exp_f32_e32 v69, v69
	v_add_f32_e32 v64, v65, v97
	v_exp_f32_e32 v70, v70
	v_add_f32_e32 v64, v106, v64
	v_exp_f32_e32 v71, v71
	v_add_f32_e32 v64, v67, v64
	v_exp_f32_e32 v72, v72
	v_add_f32_e32 v64, v68, v64
	v_exp_f32_e32 v73, v73
	v_add_f32_e32 v64, v69, v64
	v_exp_f32_e32 v74, v74
	v_add_f32_e32 v64, v70, v64
	v_exp_f32_e32 v75, v75
	v_add_f32_e32 v64, v71, v64
	v_exp_f32_e32 v76, v76
	v_add_f32_e32 v64, v72, v64
	v_exp_f32_e32 v77, v77
	v_add_f32_e32 v64, v73, v64
	v_exp_f32_e32 v78, v78
	v_add_f32_e32 v64, v74, v64
	v_exp_f32_e32 v79, v79
	v_add_f32_e32 v64, v75, v64
	v_add_f32_e32 v64, v76, v64
	v_add_f32_e32 v64, v77, v64
	v_add_f32_e32 v64, v78, v64
	v_add_f32_e32 v64, v79, v64
	v_add_f32_e32 v64, v96, v64
	v_cvt_pk_bf16_f32 v66, v97, v65
	v_cvt_pk_bf16_f32 v67, v106, v67
	v_cvt_pk_bf16_f32 v68, v68, v69
	v_cvt_pk_bf16_f32 v69, v70, v71
	v_cvt_pk_bf16_f32 v70, v72, v73
	v_cvt_pk_bf16_f32 v71, v74, v75
	v_cvt_pk_bf16_f32 v72, v76, v77
	v_cvt_pk_bf16_f32 v73, v78, v79
	s_waitcnt lgkmcnt(0)
; template <int TAG = 0> DI int fresh_tid(int wv) { int l; asm volatile("v_mbcnt_lo_u32_b32 %0, -1, 0\n\tv_mbcnt_hi_u32_b32 %0, -1, %0 ; site %1" : "=v"(l) : "n"(TAG)); return wv * 64 + l; }
; DI unsigned short f2bf(float x) { unsigned u = __float_as_uint(x); u += 0x7fffu + ((u >> 16) & 1u); return (unsigned short)(u >> 16); }
; DI int crow(int r, int hi) { return (r & 3) + 8 * (r >> 2) + 4 * hi; }
; DI float swap_sum(float v) { auto rr = __builtin_amdgcn_permlane32_swap(__float_as_uint(v), __float_as_uint(v), false, false); return __uint_as_float(rr[0]) + __uint_as_float(rr[1]); }
; DI void pv_mma(f32x16* o, const s16x4* vf, bf16x8 pa0, bf16x8 pa1) {
;     ...
; #pragma unroll
;     for (int d0 = 0; d0 < 4; ++d0) {
;         o[d0] = __builtin_amdgcn_mfma_f32_32x32x16_bf16(pa0, ATT_PK(vf[4 * d0], vf[4 * d0 + 1]), o[d0], 0, 0, 0);
;         o[d0] = __builtin_amdgcn_mfma_f32_32x32x16_bf16(pa1, ATT_PK(vf[4 * d0 + 2], vf[4 * d0 + 3]), o[d0], 0, 0, 0); }
; template <int DQK, int MODE, int LDQ, int LDK, int LDV> ...
;     ...
;     l_reg = swap_sum(l_reg);
;     { const int lane2 = fresh_tid<110 + MODE>(wv) & 63, r32 = lane2 & 31, hi = lane2 >> 5;
;     if (hi == 0) li_l[r32] = l_reg;
;     asm volatile("s_waitcnt lgkmcnt(0)" ::: "memory");
;     float s0v[MODE == 2 ? 16 : 1][4];
;     if constexpr (MODE == 2) {
; #pragma unroll
;         for (int r = 0; r < 16; ++r)
; #pragma unroll
;             for (int d0 = 0; d0 < 4; ++d0) s0v[r][d0] = S0[(size_t)(wid * 32 + crow(r, hi)) * 512 + d0 * 32 + r32];
;     }
; #pragma unroll
;     for (int r = 0; r < 16; ++r) { const int orow = wid * 32 + crow(r, hi); const float rl = __builtin_amdgcn_rcpf(li_l[crow(r, hi)]);
;         if constexpr (MODE == 0) {
; #pragma unroll
;             for (int d0 = 0; d0 < 4; ++d0) AOb[(size_t)orow * 1024 + d0 * 32 + r32] = f2bf(o[d0][r] * rl);
;         } else if constexpr (MODE == 1) {
; #pragma unroll
;             for (int d0 = 0; d0 < 4; ++d0) S0[(size_t)orow * 512 + d0 * 32 + r32] = o[d0][r] * rl;
	s_setprio 2
	v_mfma_f32_32x32x16_bf16 v[0:15], v[66:69], v[80:83], v[0:15]
	v_mfma_f32_32x32x16_bf16 v[48:63], v[66:69], v[88:91], v[48:63]
	v_mfma_f32_32x32x16_bf16 v[32:47], v[66:69], v[98:101], v[32:47]
	v_mfma_f32_32x32x16_bf16 v[16:31], v[66:69], v[108:111], v[16:31]
	v_mfma_f32_32x32x16_bf16 v[0:15], v[70:73], v[84:87], v[0:15]
	v_mfma_f32_32x32x16_bf16 v[48:63], v[70:73], v[92:95], v[48:63]
	v_mfma_f32_32x32x16_bf16 v[32:47], v[70:73], v[102:105], v[32:47]
	v_mfma_f32_32x32x16_bf16 v[16:31], v[70:73], v[112:115], v[16:31]
	s_setprio 0
	v_mbcnt_lo_u32_b32 v66, -1, 0
	v_mbcnt_hi_u32_b32 v66, -1, v66
	v_mov_b32_e32 v67, v64
	v_and_b32_e32 v65, 31, v66
	v_bfe_u32 v66, v66, 5, 1
	v_permlane32_swap_b32_e32 v64, v67
	v_cmp_eq_u32_e32 vcc, 0, v66
	s_and_saveexec_b64 s[2:3], vcc
	v_lshl_add_u32 v68, v65, 2, s0
	v_add_f32_e32 v64, v64, v67
	ds_write_b32 v68, v64
	s_or_b64 exec, exec, s[2:3]
	s_waitcnt lgkmcnt(0)
	v_lshl_add_u32 v68, v66, 4, s0
	ds_read_b128 v[70:73], v68
	ds_read_b128 v[74:77], v68 offset:32
	s_lshl_b64 s[58:59], s[40:41], 11
	v_readlane_b32 s1, v255, 2
	s_add_u32 s1, s1, s58
	v_readlane_b32 s2, v255, 0
	s_addc_u32 s2, s2, s59
	s_lshl_b32 s3, s87, 2
	s_waitcnt lgkmcnt(0)
	v_rcp_f32_e32 v69, v70
	s_add_u32 s54, s1, s3
	v_lshl_or_b32 v66, v66, 2, s94
	s_addc_u32 s55, s2, 0
	v_lshlrev_b32_e32 v130, 2, v65
	v_ashrrev_i32_e32 v67, 31, v66
	v_lshl_add_u64 v[64:65], s[54:55], 0, v[130:131]
	v_lshlrev_b64 v[78:79], 11, v[66:67]
	v_lshl_add_u64 v[78:79], v[64:65], 0, v[78:79]
	v_mul_f32_e32 v0, v0, v69
	global_store_dword v[78:79], v0, off
	v_mul_f32_e32 v0, v48, v69
	global_store_dword v[78:79], v0, off offset:128
	v_mul_f32_e32 v0, v32, v69
	global_store_dword v[78:79], v0, off offset:256
	v_mul_f32_e32 v0, v16, v69
	global_store_dword v[78:79], v0, off offset:384
	v_rcp_f32_e32 v0, v71
	v_or_b32_e32 v70, 1, v66
	v_ashrrev_i32_e32 v71, 31, v70
	v_lshlrev_b64 v[70:71], 11, v[70:71]
	v_lshl_add_u64 v[70:71], v[64:65], 0, v[70:71]
	v_mul_f32_e32 v1, v1, v0
	global_store_dword v[70:71], v1, off
	v_mul_f32_e32 v1, v49, v0
	global_store_dword v[70:71], v1, off offset:128
	v_mul_f32_e32 v1, v33, v0
	v_mul_f32_e32 v0, v17, v0
	v_rcp_f32_e32 v16, v72
	global_store_dword v[70:71], v0, off offset:384
	v_or_b32_e32 v0, 2, v66
	global_store_dword v[70:71], v1, off offset:256
	v_ashrrev_i32_e32 v1, 31, v0
	v_lshlrev_b64 v[0:1], 11, v[0:1]
	v_lshl_add_u64 v[0:1], v[64:65], 0, v[0:1]
	v_mul_f32_e32 v2, v2, v16
	global_store_dword v[0:1], v2, off
	v_mul_f32_e32 v2, v50, v16
	global_store_dword v[0:1], v2, off offset:128
	v_mul_f32_e32 v2, v34, v16
	global_store_dword v[0:1], v2, off offset:256
	v_mul_f32_e32 v2, v18, v16
	global_store_dword v[0:1], v2, off offset:384
	v_rcp_f32_e32 v2, v73
	v_or_b32_e32 v0, 3, v66
	v_ashrrev_i32_e32 v1, 31, v0
	v_lshlrev_b64 v[0:1], 11, v[0:1]
	v_lshl_add_u64 v[0:1], v[64:65], 0, v[0:1]
	v_mul_f32_e32 v3, v3, v2
	global_store_dword v[0:1], v3, off
	v_mul_f32_e32 v3, v51, v2
	global_store_dword v[0:1], v3, off offset:128
	v_mul_f32_e32 v3, v35, v2
	v_mul_f32_e32 v2, v19, v2
	global_store_dword v[0:1], v2, off offset:384
	v_rcp_f32_e32 v2, v74
	global_store_dword v[0:1], v3, off offset:256
	v_or_b32_e32 v0, 8, v66
	v_ashrrev_i32_e32 v1, 31, v0
	v_lshlrev_b64 v[0:1], 11, v[0:1]
	v_lshl_add_u64 v[0:1], v[64:65], 0, v[0:1]
	v_mul_f32_e32 v3, v4, v2
	global_store_dword v[0:1], v3, off
	v_mul_f32_e32 v3, v52, v2
	global_store_dword v[0:1], v3, off offset:128
	v_mul_f32_e32 v3, v36, v2
	v_mul_f32_e32 v2, v20, v2
	global_store_dword v[0:1], v2, off offset:384
	v_rcp_f32_e32 v2, v75
	global_store_dword v[0:1], v3, off offset:256
	v_or_b32_e32 v0, 9, v66
	v_ashrrev_i32_e32 v1, 31, v0
	v_lshlrev_b64 v[0:1], 11, v[0:1]
	v_lshl_add_u64 v[0:1], v[64:65], 0, v[0:1]
	v_mul_f32_e32 v3, v5, v2
	global_store_dword v[0:1], v3, off
	v_mul_f32_e32 v3, v53, v2
	global_store_dword v[0:1], v3, off offset:128
	v_mul_f32_e32 v3, v37, v2
	v_mul_f32_e32 v2, v21, v2
	global_store_dword v[0:1], v2, off offset:384
	v_rcp_f32_e32 v2, v76
	global_store_dword v[0:1], v3, off offset:256
	v_or_b32_e32 v0, 10, v66
	v_ashrrev_i32_e32 v1, 31, v0
	v_lshlrev_b64 v[0:1], 11, v[0:1]
	v_lshl_add_u64 v[0:1], v[64:65], 0, v[0:1]
	v_mul_f32_e32 v3, v6, v2
	global_store_dword v[0:1], v3, off
	v_mul_f32_e32 v3, v54, v2
	global_store_dword v[0:1], v3, off offset:128
	v_mul_f32_e32 v3, v38, v2
	v_mul_f32_e32 v2, v22, v2
	v_rcp_f32_e32 v6, v77
	global_store_dword v[0:1], v3, off offset:256
	global_store_dword v[0:1], v2, off offset:384
	v_or_b32_e32 v0, 11, v66
	v_ashrrev_i32_e32 v1, 31, v0
	v_lshlrev_b64 v[0:1], 11, v[0:1]
	v_lshl_add_u64 v[4:5], v[64:65], 0, v[0:1]
	v_mul_f32_e32 v0, v7, v6
	global_store_dword v[4:5], v0, off
	v_mul_f32_e32 v0, v55, v6
	global_store_dword v[4:5], v0, off offset:128
	v_mul_f32_e32 v0, v39, v6
	global_store_dword v[4:5], v0, off offset:256
	ds_read_b128 v[0:3], v68 offset:64
	v_mul_f32_e32 v6, v23, v6
	global_store_dword v[4:5], v6, off offset:384
	ds_read_b128 v[4:7], v68 offset:96
	v_or_b32_e32 v16, 16, v66
	s_waitcnt lgkmcnt(0)
; DI unsigned short f2bf(float x) { unsigned u = __float_as_uint(x); u += 0x7fffu + ((u >> 16) & 1u); return (unsigned short)(u >> 16); }
; DI int crow(int r, int hi) { return (r & 3) + 8 * (r >> 2) + 4 * hi; }
; template <int DQK, int MODE, int LDQ, int LDK, int LDV> ...
;     ...
;     for (int r = 0; r < 16; ++r) { const int orow = wid * 32 + crow(r, hi); const float rl = __builtin_amdgcn_rcpf(li_l[crow(r, hi)]);
;         if constexpr (MODE == 0) {
; #pragma unroll
;             for (int d0 = 0; d0 < 4; ++d0) AOb[(size_t)orow * 1024 + d0 * 32 + r32] = f2bf(o[d0][r] * rl);
;         } else if constexpr (MODE == 1) {
; #pragma unroll
;             for (int d0 = 0; d0 < 4; ++d0) S0[(size_t)orow * 512 + d0 * 32 + r32] = o[d0][r] * rl;
	v_rcp_f32_e32 v0, v0
	v_ashrrev_i32_e32 v17, 31, v16
	v_lshlrev_b64 v[16:17], 11, v[16:17]
	v_lshl_add_u64 v[16:17], v[64:65], 0, v[16:17]
	v_mul_f32_e32 v8, v8, v0
	global_store_dword v[16:17], v8, off
	v_mul_f32_e32 v8, v56, v0
	global_store_dword v[16:17], v8, off offset:128
	v_mul_f32_e32 v8, v40, v0
	global_store_dword v[16:17], v8, off offset:256
	v_mul_f32_e32 v0, v24, v0
	v_rcp_f32_e32 v8, v1
	global_store_dword v[16:17], v0, off offset:384
	v_or_b32_e32 v0, 17, v66
	v_ashrrev_i32_e32 v1, 31, v0
	v_lshlrev_b64 v[0:1], 11, v[0:1]
	v_lshl_add_u64 v[0:1], v[64:65], 0, v[0:1]
	v_mul_f32_e32 v9, v9, v8
	global_store_dword v[0:1], v9, off
	v_mul_f32_e32 v9, v57, v8
	global_store_dword v[0:1], v9, off offset:128
	v_mul_f32_e32 v9, v41, v8
	v_mul_f32_e32 v8, v25, v8
	v_rcp_f32_e32 v2, v2
	global_store_dword v[0:1], v9, off offset:256
	global_store_dword v[0:1], v8, off offset:384
	v_or_b32_e32 v0, 18, v66
	v_ashrrev_i32_e32 v1, 31, v0
	v_lshlrev_b64 v[0:1], 11, v[0:1]
	v_lshl_add_u64 v[0:1], v[64:65], 0, v[0:1]
	v_mul_f32_e32 v8, v10, v2
	global_store_dword v[0:1], v8, off
	v_mul_f32_e32 v8, v58, v2
	global_store_dword v[0:1], v8, off offset:128
	v_mul_f32_e32 v8, v42, v2
	v_mul_f32_e32 v2, v26, v2
	global_store_dword v[0:1], v2, off offset:384
	v_rcp_f32_e32 v2, v3
	global_store_dword v[0:1], v8, off offset:256
	v_or_b32_e32 v0, 19, v66
	v_ashrrev_i32_e32 v1, 31, v0
	v_lshlrev_b64 v[0:1], 11, v[0:1]
	v_lshl_add_u64 v[0:1], v[64:65], 0, v[0:1]
	v_mul_f32_e32 v3, v11, v2
	global_store_dword v[0:1], v3, off
	v_mul_f32_e32 v3, v59, v2
	global_store_dword v[0:1], v3, off offset:128
	v_mul_f32_e32 v3, v43, v2
	v_mul_f32_e32 v2, v27, v2
	global_store_dword v[0:1], v2, off offset:384
	v_rcp_f32_e32 v2, v4
	global_store_dword v[0:1], v3, off offset:256
	v_or_b32_e32 v0, 24, v66
	v_ashrrev_i32_e32 v1, 31, v0
	v_lshlrev_b64 v[0:1], 11, v[0:1]
	v_lshl_add_u64 v[0:1], v[64:65], 0, v[0:1]
	v_mul_f32_e32 v3, v12, v2
	global_store_dword v[0:1], v3, off
	v_mul_f32_e32 v3, v60, v2
	global_store_dword v[0:1], v3, off offset:128
	v_mul_f32_e32 v3, v44, v2
	v_mul_f32_e32 v2, v28, v2
	global_store_dword v[0:1], v2, off offset:384
	v_rcp_f32_e32 v2, v5
	global_store_dword v[0:1], v3, off offset:256
	v_or_b32_e32 v0, 25, v66
	v_ashrrev_i32_e32 v1, 31, v0
	v_lshlrev_b64 v[0:1], 11, v[0:1]
	v_lshl_add_u64 v[0:1], v[64:65], 0, v[0:1]
	v_mul_f32_e32 v3, v13, v2
	global_store_dword v[0:1], v3, off
	v_mul_f32_e32 v3, v61, v2
	global_store_dword v[0:1], v3, off offset:128
	v_mul_f32_e32 v3, v45, v2
	v_mul_f32_e32 v2, v29, v2
	global_store_dword v[0:1], v2, off offset:384
	v_rcp_f32_e32 v2, v6
	global_store_dword v[0:1], v3, off offset:256
	v_or_b32_e32 v0, 26, v66
	v_ashrrev_i32_e32 v1, 31, v0
	v_lshlrev_b64 v[0:1], 11, v[0:1]
	v_lshl_add_u64 v[0:1], v[64:65], 0, v[0:1]
	v_mul_f32_e32 v3, v14, v2
	global_store_dword v[0:1], v3, off
	v_mul_f32_e32 v3, v62, v2
	global_store_dword v[0:1], v3, off offset:128
	v_mul_f32_e32 v3, v46, v2
	v_mul_f32_e32 v2, v30, v2
	global_store_dword v[0:1], v2, off offset:384
	v_rcp_f32_e32 v2, v7
	global_store_dword v[0:1], v3, off offset:256
	v_or_b32_e32 v0, 27, v66
	v_ashrrev_i32_e32 v1, 31, v0
	v_lshlrev_b64 v[0:1], 11, v[0:1]
	v_lshl_add_u64 v[0:1], v[64:65], 0, v[0:1]
	v_mul_f32_e32 v3, v15, v2
	global_store_dword v[0:1], v3, off
	v_mul_f32_e32 v3, v63, v2
	global_store_dword v[0:1], v3, off offset:128
	v_mul_f32_e32 v3, v47, v2
	v_mul_f32_e32 v2, v31, v2
	global_store_dword v[0:1], v3, off offset:256
	global_store_dword v[0:1], v2, off offset:384
	s_waitcnt vmcnt(0)
	s_barrier
; DI float bf2f(unsigned short h) { return __uint_as_float((unsigned)h << 16); }
; template <int DQK, int MODE, int LDQ, int LDK, int LDV> ...
;     ...
;     int kgo[NKP], vgo[2];
; #pragma unroll
;     for (int i = 0; i < NKP; ++i) { const int L = (wid + 8 * i) * 64 + lane, row = L / CPR, slot = L % CPR, cc = (slot & ~7) | ((slot & 7) ^ ((row >> 1) & 7)); kgo[i] = row * LDK + cc * 8; }
; #pragma unroll
;     for (int i = 0; i < 2; ++i) { const int L = (2 * wid + i) * 64 + lane, st = L >> 5, w5 = L & 31, kk = (st >> 2) * 8 + (w5 >> 2), c = (st & 3) * 32 + (w5 & 3) * 8;
;         const int k = (kk & ~0xC) | ((kk & 4) << 1) | ((kk & 8) >> 1); vgo[i] = k * LDV + c; }
;     ...
;     ATT_DMA_K(0); ATT_DMA_K(1); ATT_DMA_V(0, 0); ATT_DMA_K(2); ATT_DMA_V(1, 1);
;     bf16x8 qr[ND0];
;     { const bf16_t* Qw = Qb + (size_t)(wid * 32 + r32) * LDQ + hi * 8;
; #pragma unroll
;       for (int d0 = 0; d0 < ND0; ++d0) qr[d0] = *(const bf16x8*)(Qw + d0 * 16);
;       if constexpr (MODE == 0) {
;           float ss = 0.f;
; #pragma unroll
;           for (int d0 = 0; d0 < ND0; ++d0)
; #pragma unroll
;               for (int j = 0; j < 8; ++j) { const float f = bf2f((unsigned short)qr[d0][j]); ss += f * f; }
;           ss = swap_sum(ss);
;           const float rstd = rsqrtf(ss * (1.f / DQK) + EPS) * C;
; #pragma unroll
;           for (int d0 = 0; d0 < ND0; ++d0) { const float* g = gq + d0 * 16 + hi * 8;
;               { float f[8]; _Pragma("unroll") for (int j = 0; j < 8; ++j) f[j] = bf2f((unsigned short)qr[d0][j]) * rstd * g[j];
;                 u32x4 w = {cvtpk(f[0], f[1]), cvtpk(f[2], f[3]), cvtpk(f[4], f[5]), cvtpk(f[6], f[7])}; qr[d0] = __builtin_bit_cast(bf16x8, w); asm volatile("" ::: "memory"); } }
;       } }
;     const int qlo = q0 + wid * 32, qpos = qlo + r32;
;     const int tL = MODE == 0 ? 0 : (qlo >= 191 ? (qlo - 127) >> 6 : 0), tR = MODE == 0 ? NT : min(NT, (qlo + 222) >> 6);
;     float fL = 1.f, fR = 1.f; if constexpr (MODE != 0) { fL = __builtin_amdgcn_exp2f(bt[0]); fR = __builtin_amdgcn_exp2f(-bt[448]); }
;     ...
;     const int vbase = (int)(unsigned)(size_t)lds + V_OFF + v_rd_base(lane);
;     ...
;     constexpr int NDA = ND0 > 6 ? 6 : ND0;
;     ...
;     f32x16 pA, pB; bf16x8 pa0, pa1;
;     int v0 = 0, v1 = 1, v2 = 2;
;     ATT_TOP(NKP + 2);
;     { bf16x8 kf[NDA]; k_reads<DQK, 0, NDA>(kf, lds, 0, r32, hi); ATT_LGKM0(); qk_mma<0, NDA>(pA, kf, qr);
	v_mbcnt_lo_u32_b32 v7, -1, 0
	v_mbcnt_hi_u32_b32 v7, -1, v7
	s_mov_b64 s[4:5], 0x880
	v_add_u32_e32 v0, s33, v7
	v_bfe_u32 v4, v0, 2, 2
	v_readfirstlane_b32 s0, v0
	s_ashr_i32 s2, s0, 31
	s_ashr_i32 s1, s0, 6
	v_mov_b32_e32 v1, s0
	v_bfi_b32 v1, s63, v1, v7
	s_lshr_b32 s2, s2, 29
	v_add_u32_e32 v3, s2, v1
	s_lshl_b32 s2, s1, 7
	v_ashrrev_i32_e32 v9, 3, v3
	v_and_b32_e32 v3, 0x1ffffff8, v3
	s_ashr_i32 s3, s2, 4
	v_lshrrev_b32_e32 v0, 2, v0
	v_sub_u32_e32 v1, v1, v3
	v_lshrrev_b32_e32 v3, 1, v9
	v_lshlrev_b32_e32 v18, 3, v7
	s_and_b32 s2, s3, -16
	v_and_b32_e32 v6, 4, v0
	s_lshr_b32 s3, s3, 0
	v_bitop3_b32 v1, v3, v1, 7 bitop3:0x6c
	v_and_b32_e32 v3, 32, v7
	v_and_b32_e32 v5, 24, v18
	s_and_b32 s3, s3, 8
	v_or3_b32 v0, v6, v4, s2
	v_or_b32_e32 v10, v3, v5
	v_or_b32_e32 v0, s3, v0
	v_lshl_or_b32 v96, v0, 11, v10
	v_lshlrev_b32_e32 v0, 11, v9
	v_lshl_add_u32 v0, v1, 3, v0
	v_ashrrev_i32_e32 v1, 31, v0
	v_lshlrev_b64 v[10:11], 1, v[0:1]
	v_lshl_add_u64 v[12:13], s[46:47], 0, v[10:11]
	v_lshl_add_u64 v[12:13], v[12:13], 0, s[4:5]
	s_lshl_b32 s4, s1, 10
	s_add_i32 s94, s4, 0
	s_mov_b32 m0, s94
	v_lshl_add_u64 v[10:11], s[48:49], 0, v[10:11]
	s_mov_b64 s[4:5], 0x40080
	global_load_lds_dwordx4 v[12:13], off
	v_lshl_add_u64 v[12:13], v[10:11], 0, s[4:5]
	s_add_i32 m0, s94, 0x2000
	s_lshl_b32 s4, s1, 11
	v_ashrrev_i32_e32 v97, 31, v96
	global_load_lds_dwordx4 v[12:13], off
	s_add_i32 s6, s4, 0
	v_lshlrev_b64 v[12:13], 1, v[96:97]
	s_add_i32 s48, s6, 0x18000
	v_lshl_add_u64 v[14:15], s[46:47], 0, v[12:13]
	v_lshl_add_u64 v[16:17], v[14:15], 0, s[96:97]
	s_mov_b32 m0, s48
	s_mov_b64 s[4:5], 0xc80
	global_load_lds_dwordx4 v[16:17], off
	v_lshl_add_u64 v[14:15], v[14:15], 0, s[4:5]
	s_add_i32 m0, s6, 0x18400
	s_mov_b64 s[4:5], 0x80080
	v_or_b32_e32 v98, 64, v96
	global_load_lds_dwordx4 v[14:15], off
	v_lshl_add_u64 v[10:11], v[10:11], 0, s[4:5]
	s_add_i32 m0, s94, 0x4000
	v_ashrrev_i32_e32 v99, 31, v98
	global_load_lds_dwordx4 v[10:11], off
	s_add_i32 m0, s6, 0x1c000
	v_lshl_add_u64 v[10:11], s[52:53], 0, v[12:13]
	v_and_b32_e32 v2, 31, v7
	global_load_lds_dwordx4 v[10:11], off
	v_lshl_add_u64 v[10:11], v[98:99], 1, s[52:53]
	s_add_i32 m0, s6, 0x1c400
	s_lshl_b32 s46, s1, 5
	global_load_lds_dwordx4 v[10:11], off
	v_or_b32_e32 v10, s46, v2
	v_ashrrev_i32_e32 v11, 31, v10
	v_bfe_u32 v8, v7, 5, 1
	v_lshlrev_b64 v[10:11], 12, v[10:11]
	v_lshl_add_u64 v[10:11], s[44:45], 0, v[10:11]
	v_lshlrev_b32_e32 v130, 4, v8
	v_lshl_add_u64 v[10:11], v[10:11], 0, v[130:131]
	global_load_dwordx4 v[92:95], v[10:11], off offset:1152
	global_load_dwordx4 v[88:91], v[10:11], off offset:1184
	global_load_dwordx4 v[84:87], v[10:11], off offset:1216
	global_load_dwordx4 v[80:83], v[10:11], off offset:1248
	v_and_b32_e32 v11, 0x70, v18
	v_mov_b32_e32 v9, s88
	v_mov_b32_e32 v10, s81
	v_lshl_add_u32 v114, v2, 7, 0
	v_bitop3_b32 v115, v130, v18, s64 bitop3:0x78
	v_bitop3_b32 v117, v130, v11, 64 bitop3:0x36
	s_add_i32 s4, s46, s89
	ds_read_b32 v9, v9
	ds_read_b32 v10, v10
	s_waitcnt vmcnt(3)
	s_barrier
	v_add_u32_e32 v107, v114, v115
	v_bitop3_b32 v116, v130, v11, 32 bitop3:0x36
	v_add_u32_e32 v109, v114, v117
	v_bitop3_b32 v118, v130, v11, s65 bitop3:0x36
	s_add_i32 s5, s4, 0xffffff81
	v_add_u32_e32 v108, v114, v116
	ds_read_b128 v[12:15], v107
	ds_read_b128 v[16:19], v108
	v_add_u32_e32 v110, v114, v118
	ds_read_b128 v[20:23], v109
	ds_read_b128 v[24:27], v110
	s_ashr_i32 s5, s5, 6
	s_cmpk_gt_i32 s4, 0xbe
	v_or_b32_e32 v111, s4, v2
	s_cselect_b32 s47, s5, 0
	s_addk_i32 s4, 0xde
	s_ashr_i32 s45, s4, 6
	s_waitcnt lgkmcnt(0)
	s_waitcnt vmcnt(0) lgkmcnt(0)
	v_mfma_f32_32x32x16_bf16 v[64:79], v[12:15], v[92:95], 0
	s_cmp_gt_i32 s47, 0
	s_cselect_b64 s[4:5], -1, 0
	s_cmp_lt_i32 s45, 1
	s_cselect_b64 s[6:7], -1, 0
	s_or_b64 s[4:5], s[6:7], s[4:5]
	s_and_b64 vcc, exec, s[4:5]
	v_mfma_f32_32x32x16_bf16 v[64:79], v[16:19], v[88:91], v[64:79]
	v_mfma_f32_32x32x16_bf16 v[64:79], v[20:23], v[84:87], v[64:79]
	v_mfma_f32_32x32x16_bf16 v[64:79], v[24:27], v[80:83], v[64:79]
	s_cbranch_vccnz .LBB0_1948
	v_lshlrev_b32_e32 v8, 2, v8
	v_sub_u32_e32 v8, v8, v111
	v_lshl_add_u32 v8, v8, 2, s88
	ds_read2_b32 v[12:13], v8 offset0:240 offset1:241
	ds_read2_b32 v[14:15], v8 offset0:242 offset1:243
	ds_read2_b32 v[16:17], v8 offset0:248 offset1:249
	ds_read2_b32 v[18:19], v8 offset0:250 offset1:251
	ds_read2_b32 v[20:21], v8 offset0:224 offset1:225
	ds_read2_b32 v[22:23], v8 offset0:226 offset1:227
	ds_read2_b32 v[24:25], v8 offset0:232 offset1:233
	ds_read2_b32 v[26:27], v8 offset0:234 offset1:235
	s_waitcnt lgkmcnt(4)
	v_add_f32_e32 v78, v78, v18
	v_add_f32_e32 v79, v79, v19
	v_add_f32_e32 v76, v76, v16
	v_add_f32_e32 v77, v77, v17
	v_add_f32_e32 v74, v74, v14
	v_add_f32_e32 v75, v75, v15
	v_add_f32_e32 v72, v72, v12
	v_add_f32_e32 v73, v73, v13
	s_waitcnt lgkmcnt(0)
	v_add_f32_e32 v70, v70, v26
	v_add_f32_e32 v71, v71, v27
	v_add_f32_e32 v68, v68, v24
	v_add_f32_e32 v69, v69, v25
	v_add_f32_e32 v66, v66, v22
	v_add_f32_e32 v67, v67, v23
	v_add_f32_e32 v64, v64, v20
	v_add_f32_e32 v65, v65, v21

.Lhw_d1_b_dtd1resc:
	s_cmp_eq_u32 s0, s98
	s_cselect_b64 s[2:3], -1, 0
	s_and_b64 vcc, s[4:5], s[2:3]
	s_cmp_eq_u32 s0, s99
	s_cselect_b64 s[2:3], -1, 0
	s_or_b64 vcc, s[2:3], vcc
	s_andn2_b64 vcc, exec, vcc
	s_cbranch_vccnz .Lhw_d1_b_n1953
	v_cndmask_b32_e64 v122, v112, v113, s[2:3]
	v_mul_f32_e32 v14, v14, v122
	v_mul_f32_e32 v15, v15, v122
	v_mul_f32_e32 v12, v12, v122
	v_mul_f32_e32 v13, v13, v122
	v_mul_f32_e32 v10, v10, v122
	v_mul_f32_e32 v11, v11, v122
	v_mul_f32_e32 v8, v8, v122
	v_mul_f32_e32 v9, v9, v122
	v_mul_f32_e32 v6, v6, v122
	v_mul_f32_e32 v7, v7, v122
	v_mul_f32_e32 v4, v4, v122
	v_mul_f32_e32 v5, v5, v122
	v_mul_f32_e32 v2, v2, v122
	v_mul_f32_e32 v3, v3, v122
	v_mul_f32_e32 v0, v0, v122
	v_mul_f32_e32 v1, v1, v122
	v_mul_f32_e32 v62, v62, v122
	v_mul_f32_e32 v63, v63, v122
	v_mul_f32_e32 v60, v60, v122
	v_mul_f32_e32 v61, v61, v122
	v_mul_f32_e32 v58, v58, v122
	v_mul_f32_e32 v59, v59, v122
	v_mul_f32_e32 v56, v56, v122
	v_mul_f32_e32 v57, v57, v122
	v_mul_f32_e32 v54, v54, v122
	v_mul_f32_e32 v55, v55, v122
	v_mul_f32_e32 v52, v52, v122
	v_mul_f32_e32 v53, v53, v122
	v_mul_f32_e32 v50, v50, v122
	v_mul_f32_e32 v51, v51, v122
	v_mul_f32_e32 v48, v48, v122
	v_mul_f32_e32 v49, v49, v122
	v_mul_f32_e32 v30, v30, v122
	v_mul_f32_e32 v31, v31, v122
	v_mul_f32_e32 v28, v28, v122
	v_mul_f32_e32 v29, v29, v122
	v_mul_f32_e32 v26, v26, v122
	v_mul_f32_e32 v27, v27, v122
	v_mul_f32_e32 v24, v24, v122
	v_mul_f32_e32 v25, v25, v122
	v_mul_f32_e32 v22, v22, v122
	v_mul_f32_e32 v23, v23, v122
	v_mul_f32_e32 v20, v20, v122
	v_mul_f32_e32 v21, v21, v122
	v_mul_f32_e32 v18, v18, v122
	v_mul_f32_e32 v19, v19, v122
	v_mul_f32_e32 v16, v16, v122
	v_mul_f32_e32 v17, v17, v122
	v_mul_f32_e32 v46, v46, v122
	v_mul_f32_e32 v47, v47, v122
	v_mul_f32_e32 v44, v44, v122
	v_mul_f32_e32 v45, v45, v122
	v_mul_f32_e32 v42, v42, v122
	v_mul_f32_e32 v43, v43, v122
	v_mul_f32_e32 v40, v40, v122
	v_mul_f32_e32 v41, v41, v122
	v_mul_f32_e32 v38, v38, v122
	v_mul_f32_e32 v39, v39, v122
	v_mul_f32_e32 v36, v36, v122
	v_mul_f32_e32 v37, v37, v122
	v_mul_f32_e32 v34, v34, v122
	v_mul_f32_e32 v35, v35, v122
	v_mul_f32_e32 v32, v32, v122
	v_mul_f32_e32 v33, v33, v122
	v_mul_f32_e32 v120, v120, v122
	s_branch .Lhw_d1_b_n1953

.Lhw_d1_b_dtd1bias2:
	v_add_u32_e32 v122, s7, v119
	v_add_u32_e32 v136, 0x28988, v122
	v_add_u32_e32 v138, 0x289a0, v122
	v_add_u32_e32 v140, 0x289a8, v122
	v_add_u32_e32 v123, 0x289c0, v122
	v_add_u32_e32 v124, 0x289c8, v122
	v_add_u32_e32 v126, 0x289e0, v122
	v_add_u32_e32 v132, 0x289e8, v122
	v_add_u32_e32 v121, 0x28980, v122
	ds_read2_b32 v[122:123], v123 offset1:1
	ds_read2_b32 v[124:125], v124 offset1:1
	ds_read2_b32 v[126:127], v126 offset1:1
	ds_read2_b32 v[132:133], v132 offset1:1
	ds_read2_b32 v[134:135], v121 offset1:1
	ds_read2_b32 v[136:137], v136 offset1:1
	ds_read2_b32 v[138:139], v138 offset1:1
	ds_read2_b32 v[140:141], v140 offset1:1
	s_waitcnt lgkmcnt(0)
	v_add_f32_e32 v78, v78, v132
	v_add_f32_e32 v79, v79, v133
	v_add_f32_e32 v76, v76, v126
	v_add_f32_e32 v77, v77, v127
	v_add_f32_e32 v74, v74, v124
	v_add_f32_e32 v75, v75, v125
	v_add_f32_e32 v72, v72, v122
	v_add_f32_e32 v73, v73, v123
	v_add_f32_e32 v70, v70, v140
	v_add_f32_e32 v71, v71, v141
	v_add_f32_e32 v68, v68, v138
	v_add_f32_e32 v69, v69, v139
	v_add_f32_e32 v66, v66, v136
	v_add_f32_e32 v67, v67, v137
	v_add_f32_e32 v64, v64, v134
	v_add_f32_e32 v65, v65, v135
	v_lshl_add_u32 v121, s49, 14, v106
	s_branch .Lhw_d1_b_n1957

; #define SBAR() __builtin_amdgcn_sched_barrier(0)
; DI int v_rd_base(int lane) { return ((lane & 3) << 3) | (((lane >> 2) & 3) << 6) | (((lane >> 4) & 1) << 5) | (((lane >> 5) & 1) << 8); }
; #define ATT_DMA_K(t) do { const bf16_t* kg_ = Kh + (size_t)(t) * 64 * LDK; LAS unsigned char* sb_ = lds + ((t) & 3) * KBUF; \
;     _Pragma("unroll") for (int i_ = 0; i_ < NKP; ++i_) __builtin_amdgcn_global_load_lds((const unsigned*)(kg_ + kgo[i_]), (LAS unsigned*)(sb_ + (wid + 8 * i_) * 1024), 16, 0, 0); } while (0)
; #define ATT_DMA_V(t, vs) do { const bf16_t* vg_ = Vh + (size_t)(t) * 64 * LDV; LAS unsigned char* sb_ = lds + V_OFF + (vs) * SHM_V; \
;     _Pragma("unroll") for (int i_ = 0; i_ < 2; ++i_) __builtin_amdgcn_global_load_lds((const unsigned*)(vg_ + vgo[i_]), (LAS unsigned*)(sb_ + (2 * wid + i_) * 1024), 16, 0, 0); } while (0)
; #define ATT_SEG(t) do { if constexpr (MODE != 0) { if (((t) == tL && tL > 0) || (t) == tR) { const float f_ = (t) == tR ? fR : fL; l_reg *= f_; \
;     _Pragma("unroll") for (int d = 0; d < 4; ++d) _Pragma("unroll") for (int r = 0; r < 16; ++r) o[d][r] *= f_; } } } while (0)
; template <int DQK, int MODE, int LDQ, int LDK, int LDV> ...
;     ...
;     const int vbase = (int)(unsigned)(size_t)lds + V_OFF + v_rd_base(lane);
;     ...
;     constexpr int NDA = ND0 > 6 ? 6 : ND0;
;     ...
;         if (j + 3 < NT) ATT_DMA_K(j + 3);
;         if (j + 2 < NT) ATT_DMA_V(j + 2, v2);
;         ATT_SEG(j); SBAR();
;         ATT_STEP(pA, pB, 0, v0, true, 1, j);
;         ATT_STEP(pB, pA, 1, v0, (j + 1 < NT), 0, j + 1);
.Lstg_d1_t61_20:
	s_setprio 0
	s_add_i32 s1, s0, 0x400
	v_lshl_add_u64 v[96:97], v[96:97], 1, s[56:57]
	s_mov_b32 m0, s0
	v_lshl_add_u64 v[98:99], v[98:99], 1, s[56:57]
	global_load_lds_dwordx4 v[96:97], off
	s_mov_b32 m0, s1
	s_cmp_lg_u32 s47, 61
	global_load_lds_dwordx4 v[98:99], off
	s_cselect_b64 s[0:1], -1, 0
	s_cmp_eq_u32 s45, 61
	s_cselect_b64 s[2:3], -1, 0
	s_cmp_lg_u32 s45, 61
	s_cselect_b64 s[4:5], -1, 0
	s_and_b64 s[0:1], s[4:5], s[0:1]
	s_and_b64 vcc, exec, s[0:1]
	s_cbranch_vccnz .LBB0_1961
	v_cndmask_b32_e64 v96, v112, v113, s[2:3]
	v_mul_f32_e32 v14, v14, v96
	v_mul_f32_e32 v15, v15, v96
	v_mul_f32_e32 v12, v12, v96
	v_mul_f32_e32 v13, v13, v96
	v_mul_f32_e32 v10, v10, v96
	v_mul_f32_e32 v11, v11, v96
	v_mul_f32_e32 v8, v8, v96
	v_mul_f32_e32 v9, v9, v96
	v_mul_f32_e32 v6, v6, v96
	v_mul_f32_e32 v7, v7, v96
	v_mul_f32_e32 v4, v4, v96
	v_mul_f32_e32 v5, v5, v96
	v_mul_f32_e32 v2, v2, v96
	v_mul_f32_e32 v3, v3, v96
	v_mul_f32_e32 v0, v0, v96
	v_mul_f32_e32 v1, v1, v96
	v_mul_f32_e32 v62, v62, v96
	v_mul_f32_e32 v63, v63, v96
	v_mul_f32_e32 v60, v60, v96
	v_mul_f32_e32 v61, v61, v96
	v_mul_f32_e32 v58, v58, v96
	v_mul_f32_e32 v59, v59, v96
	v_mul_f32_e32 v56, v56, v96
	v_mul_f32_e32 v57, v57, v96
	v_mul_f32_e32 v54, v54, v96
	v_mul_f32_e32 v55, v55, v96
	v_mul_f32_e32 v52, v52, v96
	v_mul_f32_e32 v53, v53, v96
	v_mul_f32_e32 v50, v50, v96
	v_mul_f32_e32 v51, v51, v96
	v_mul_f32_e32 v48, v48, v96
	v_mul_f32_e32 v49, v49, v96
	v_mul_f32_e32 v30, v30, v96
	v_mul_f32_e32 v31, v31, v96
	v_mul_f32_e32 v28, v28, v96
	v_mul_f32_e32 v29, v29, v96
	v_mul_f32_e32 v26, v26, v96
	v_mul_f32_e32 v27, v27, v96
	v_mul_f32_e32 v24, v24, v96
	v_mul_f32_e32 v25, v25, v96
	v_mul_f32_e32 v22, v22, v96
	v_mul_f32_e32 v23, v23, v96
	v_mul_f32_e32 v20, v20, v96
	v_mul_f32_e32 v21, v21, v96
	v_mul_f32_e32 v18, v18, v96
	v_mul_f32_e32 v19, v19, v96
	v_mul_f32_e32 v16, v16, v96
	v_mul_f32_e32 v17, v17, v96
	v_mul_f32_e32 v46, v46, v96
	v_mul_f32_e32 v47, v47, v96
	v_mul_f32_e32 v44, v44, v96
	v_mul_f32_e32 v45, v45, v96
	v_mul_f32_e32 v42, v42, v96
	v_mul_f32_e32 v43, v43, v96
	v_mul_f32_e32 v40, v40, v96
	v_mul_f32_e32 v41, v41, v96
	v_mul_f32_e32 v38, v38, v96
	v_mul_f32_e32 v39, v39, v96
	v_mul_f32_e32 v36, v36, v96
	v_mul_f32_e32 v37, v37, v96
	v_mul_f32_e32 v34, v34, v96
	v_mul_f32_e32 v35, v35, v96
	v_mul_f32_e32 v32, v32, v96
	v_mul_f32_e32 v33, v33, v96
	v_mul_f32_e32 v120, v120, v96
.LBB0_1961:
	ds_read_b128 v[98:101], v107 offset:12288
	ds_read_b128 v[102:105], v108 offset:12288
	ds_read_b128 v[114:117], v109 offset:12288
	ds_read_b128 v[122:125], v110 offset:12288
	v_lshl_add_u32 v96, s49, 14, v106
	ds_read_b64_tr_b16 v[132:133], v96 offset:0
	ds_read_b64_tr_b16 v[134:135], v96 offset:0x800
	ds_read_b64_tr_b16 v[136:137], v96 offset:0x1000
	ds_read_b64_tr_b16 v[138:139], v96 offset:0x1800
	ds_read_b64_tr_b16 v[140:141], v96 offset:0x200
	ds_read_b64_tr_b16 v[142:143], v96 offset:0xa00
	ds_read_b64_tr_b16 v[144:145], v96 offset:0x1200
	ds_read_b64_tr_b16 v[146:147], v96 offset:0x1a00
	ds_read_b64_tr_b16 v[148:149], v96 offset:0x400
	ds_read_b64_tr_b16 v[150:151], v96 offset:0xc00
	ds_read_b64_tr_b16 v[152:153], v96 offset:0x1400
	ds_read_b64_tr_b16 v[154:155], v96 offset:0x1c00
	ds_read_b64_tr_b16 v[156:157], v96 offset:0x600
	ds_read_b64_tr_b16 v[158:159], v96 offset:0xe00
	ds_read_b64_tr_b16 v[162:163], v96 offset:0x1600
	ds_read_b64_tr_b16 v[164:165], v96 offset:0x1e00
	s_setprio 1
	v_exp_f32_e32 v64, v64
	v_exp_f32_e32 v65, v65
	v_exp_f32_e32 v66, v66
	v_exp_f32_e32 v67, v67
	v_exp_f32_e32 v68, v68
	v_exp_f32_e32 v69, v69
	v_add_f32_e32 v97, v65, v64
	v_exp_f32_e32 v70, v70
	v_add_f32_e32 v97, v66, v97
	v_exp_f32_e32 v71, v71
	v_add_f32_e32 v97, v67, v97
	v_exp_f32_e32 v72, v72
	v_add_f32_e32 v97, v68, v97
	v_exp_f32_e32 v73, v73
	v_add_f32_e32 v97, v69, v97
	v_exp_f32_e32 v74, v74
	v_add_f32_e32 v97, v70, v97
	v_exp_f32_e32 v75, v75
	v_add_f32_e32 v97, v71, v97
	v_exp_f32_e32 v76, v76
	v_add_f32_e32 v97, v72, v97
	v_exp_f32_e32 v77, v77
	v_add_f32_e32 v97, v73, v97
	v_exp_f32_e32 v78, v78
	v_add_f32_e32 v97, v74, v97
	v_exp_f32_e32 v79, v79
	v_add_f32_e32 v97, v75, v97
	v_add_f32_e32 v97, v76, v97
	v_add_f32_e32 v97, v77, v97
	v_add_f32_e32 v97, v78, v97
	v_add_f32_e32 v97, v79, v97
	v_add_f32_e32 v97, v97, v120
	v_cvt_pk_bf16_f32 v64, v64, v65
	v_cvt_pk_bf16_f32 v65, v66, v67
	v_cvt_pk_bf16_f32 v66, v68, v69
	v_cvt_pk_bf16_f32 v67, v70, v71
	v_cvt_pk_bf16_f32 v68, v72, v73
	v_cvt_pk_bf16_f32 v69, v74, v75
	v_cvt_pk_bf16_f32 v70, v76, v77
	v_cvt_pk_bf16_f32 v71, v78, v79
	s_waitcnt lgkmcnt(0)
	s_setprio 2
	v_mfma_f32_32x32x16_bf16 v[0:15], v[64:67], v[132:135], v[0:15]
	s_cmp_gt_i32 s47, 61
	s_cselect_b64 s[0:1], -1, 0
	s_cmp_lt_i32 s45, 62
	s_cselect_b64 s[2:3], -1, 0
	s_or_b64 s[0:1], s[0:1], s[2:3]
	s_and_b64 vcc, exec, s[0:1]
	v_mfma_f32_32x32x16_bf16 v[48:63], v[64:67], v[140:143], v[48:63]
	v_mfma_f32_32x32x16_bf16 v[16:31], v[64:67], v[148:151], v[16:31]
	v_mfma_f32_32x32x16_bf16 v[32:47], v[64:67], v[156:159], v[32:47]
	v_mfma_f32_32x32x16_bf16 v[0:15], v[68:71], v[136:139], v[0:15]
	v_mfma_f32_32x32x16_bf16 v[48:63], v[68:71], v[144:147], v[48:63]
	v_mfma_f32_32x32x16_bf16 v[16:31], v[68:71], v[152:155], v[16:31]
	v_mfma_f32_32x32x16_bf16 v[32:47], v[68:71], v[162:165], v[32:47]
	s_waitcnt lgkmcnt(0)
	v_mfma_f32_32x32x16_bf16 v[64:79], v[98:101], v[92:95], 0
	v_mfma_f32_32x32x16_bf16 v[64:79], v[102:105], v[88:91], v[64:79]
	v_mfma_f32_32x32x16_bf16 v[64:79], v[114:117], v[84:87], v[64:79]
	v_mfma_f32_32x32x16_bf16 v[64:79], v[122:125], v[80:83], v[64:79]
	s_setprio 0
	s_cbranch_vccnz .LBB0_1963
	v_sub_u32_e32 v98, 0xf40, v111
	v_lshlrev_b32_e32 v98, 2, v98
	v_add3_u32 v98, s88, v98, v130
	v_add_u32_e32 v114, 0x400, v98
	v_add_u32_e32 v116, 0x408, v98
	v_add_u32_e32 v118, 0x420, v98
	v_add_u32_e32 v120, 0x428, v98
	v_add_u32_e32 v99, 0x440, v98
	v_add_u32_e32 v100, 0x448, v98
	v_add_u32_e32 v102, 0x460, v98
	v_add_u32_e32 v104, 0x468, v98
	ds_read2_b32 v[98:99], v99 offset1:1
	ds_read2_b32 v[100:101], v100 offset1:1
	ds_read2_b32 v[102:103], v102 offset1:1
	ds_read2_b32 v[104:105], v104 offset1:1
	ds_read2_b32 v[114:115], v114 offset1:1
	ds_read2_b32 v[116:117], v116 offset1:1
	ds_read2_b32 v[118:119], v118 offset1:1
	ds_read2_b32 v[120:121], v120 offset1:1
	s_waitcnt lgkmcnt(0)
	v_add_f32_e32 v78, v78, v104
	v_add_f32_e32 v79, v79, v105
	v_add_f32_e32 v76, v76, v102
	v_add_f32_e32 v77, v77, v103
	v_add_f32_e32 v74, v74, v100
	v_add_f32_e32 v75, v75, v101
	v_add_f32_e32 v72, v72, v98
	v_add_f32_e32 v73, v73, v99
	v_add_f32_e32 v70, v70, v120
	v_add_f32_e32 v71, v71, v121
	v_add_f32_e32 v68, v68, v118
	v_add_f32_e32 v69, v69, v119
	v_add_f32_e32 v66, v66, v116
	v_add_f32_e32 v67, v67, v117
	v_add_f32_e32 v64, v64, v114
	v_add_f32_e32 v65, v65, v115

.Lstg_d1_m61_21:
	v_mfma_f32_32x32x16_bf16 v[0:15], v[64:67], v[122:125], v[0:15]
	s_cmp_lt_i32 s47, 63
	s_cselect_b64 s[0:1], -1, 0
	s_cmp_gt_i32 s45, 62
	s_cselect_b64 s[2:3], -1, 0
	s_and_b64 s[0:1], s[0:1], s[2:3]
	v_cndmask_b32_e64 v97, 0, 1, s[0:1]
	v_cmp_ne_u32_e64 s[2:3], 1, v97
	v_mfma_f32_32x32x16_bf16 v[48:63], v[64:67], v[136:139], v[48:63]
	v_sub_u32_e32 v97, 0xf80, v111
	s_andn2_b64 vcc, exec, s[0:1]
	v_lshlrev_b32_e32 v97, 2, v97
	v_mfma_f32_32x32x16_bf16 v[16:31], v[64:67], v[144:147], v[16:31]
	v_mfma_f32_32x32x16_bf16 v[32:47], v[64:67], v[152:155], v[32:47]
	v_mfma_f32_32x32x16_bf16 v[0:15], v[68:71], v[132:135], v[0:15]
	v_mfma_f32_32x32x16_bf16 v[48:63], v[68:71], v[140:143], v[48:63]
	v_mfma_f32_32x32x16_bf16 v[16:31], v[68:71], v[148:151], v[16:31]
	v_mfma_f32_32x32x16_bf16 v[32:47], v[68:71], v[156:159], v[32:47]
	s_waitcnt lgkmcnt(0)
	v_mfma_f32_32x32x16_bf16 v[64:79], v[98:101], v[92:95], 0
	v_mfma_f32_32x32x16_bf16 v[64:79], v[102:105], v[88:91], v[64:79]
	v_mfma_f32_32x32x16_bf16 v[64:79], v[114:117], v[84:87], v[64:79]
	v_mfma_f32_32x32x16_bf16 v[64:79], v[118:121], v[80:83], v[64:79]
	s_cbranch_vccnz .LBB0_1965
	v_add3_u32 v120, s88, v97, v130
	ds_read2_b32 v[98:99], v120 offset0:240 offset1:241
	ds_read2_b32 v[100:101], v120 offset0:242 offset1:243
	ds_read2_b32 v[102:103], v120 offset0:248 offset1:249
	ds_read2_b32 v[104:105], v120 offset0:250 offset1:251
	ds_read2_b32 v[114:115], v120 offset0:224 offset1:225
	ds_read2_b32 v[116:117], v120 offset0:226 offset1:227
	ds_read2_b32 v[118:119], v120 offset0:232 offset1:233
	ds_read2_b32 v[120:121], v120 offset0:234 offset1:235
	s_waitcnt lgkmcnt(0)
	s_nop 0
	v_add_f32_e32 v78, v78, v104
	v_add_f32_e32 v79, v79, v105
	v_add_f32_e32 v76, v76, v102
	v_add_f32_e32 v77, v77, v103
	v_add_f32_e32 v74, v74, v100
	v_add_f32_e32 v75, v75, v101
	v_add_f32_e32 v72, v72, v98
	v_add_f32_e32 v73, v73, v99
	v_add_f32_e32 v70, v70, v120
	v_add_f32_e32 v71, v71, v121
	v_add_f32_e32 v68, v68, v118
	v_add_f32_e32 v69, v69, v119
	v_add_f32_e32 v66, v66, v116
	v_add_f32_e32 v67, v67, v117
	v_add_f32_e32 v64, v64, v114
	v_add_f32_e32 v65, v65, v115

.LBB0_1967:
	ds_read_b128 v[100:103], v107 offset:20480
	ds_read_b128 v[114:117], v108 offset:20480
	ds_read_b128 v[118:121], v109 offset:20480
	ds_read_b128 v[122:125], v110 offset:20480
	v_add_u32_e32 v98, 0x8000, v106
	ds_read_b64_tr_b16 v[132:133], v98 offset:0
	ds_read_b64_tr_b16 v[134:135], v98 offset:0x800
	ds_read_b64_tr_b16 v[136:137], v98 offset:0x1000
	ds_read_b64_tr_b16 v[138:139], v98 offset:0x1800
	ds_read_b64_tr_b16 v[140:141], v98 offset:0x200
	ds_read_b64_tr_b16 v[142:143], v98 offset:0xa00
	ds_read_b64_tr_b16 v[144:145], v98 offset:0x1200
	ds_read_b64_tr_b16 v[146:147], v98 offset:0x1a00
	ds_read_b64_tr_b16 v[148:149], v98 offset:0x400
	ds_read_b64_tr_b16 v[150:151], v98 offset:0xc00
	ds_read_b64_tr_b16 v[152:153], v98 offset:0x1400
	ds_read_b64_tr_b16 v[154:155], v98 offset:0x1c00
	ds_read_b64_tr_b16 v[156:157], v98 offset:0x600
	ds_read_b64_tr_b16 v[158:159], v98 offset:0xe00
	ds_read_b64_tr_b16 v[162:163], v98 offset:0x1600
	ds_read_b64_tr_b16 v[164:165], v98 offset:0x1e00
	s_setprio 1
	v_exp_f32_e32 v64, v64
	v_exp_f32_e32 v65, v65
	v_exp_f32_e32 v66, v66
	v_exp_f32_e32 v67, v67
	v_exp_f32_e32 v68, v68
	v_exp_f32_e32 v69, v69
	v_add_f32_e32 v99, v65, v64
	v_exp_f32_e32 v70, v70
	v_add_f32_e32 v99, v66, v99
	v_exp_f32_e32 v71, v71
	v_add_f32_e32 v99, v67, v99
	v_exp_f32_e32 v72, v72
	v_add_f32_e32 v99, v68, v99
	v_exp_f32_e32 v73, v73
	v_add_f32_e32 v99, v69, v99
	v_exp_f32_e32 v74, v74
	v_add_f32_e32 v99, v70, v99
	v_exp_f32_e32 v75, v75
	v_add_f32_e32 v99, v71, v99
	v_exp_f32_e32 v76, v76
	v_add_f32_e32 v99, v72, v99
	v_exp_f32_e32 v77, v77
	v_add_f32_e32 v99, v73, v99
	v_exp_f32_e32 v78, v78
	v_add_f32_e32 v99, v74, v99
	v_exp_f32_e32 v79, v79
	v_add_f32_e32 v99, v75, v99
	v_add_f32_e32 v99, v76, v99
	v_add_f32_e32 v99, v77, v99
	v_add_f32_e32 v99, v78, v99
	v_add_f32_e32 v99, v79, v99
	v_add_f32_e32 v96, v99, v96
	v_cvt_pk_bf16_f32 v64, v64, v65
	v_cvt_pk_bf16_f32 v65, v66, v67
	v_cvt_pk_bf16_f32 v66, v68, v69
	v_cvt_pk_bf16_f32 v67, v70, v71
	v_cvt_pk_bf16_f32 v68, v72, v73
	v_cvt_pk_bf16_f32 v69, v74, v75
	v_cvt_pk_bf16_f32 v70, v76, v77
	v_cvt_pk_bf16_f32 v71, v78, v79
	s_waitcnt lgkmcnt(0)
	s_setprio 2
	v_mfma_f32_32x32x16_bf16 v[0:15], v[64:67], v[132:135], v[0:15]
	s_and_b64 vcc, exec, s[2:3]
	v_mfma_f32_32x32x16_bf16 v[48:63], v[64:67], v[140:143], v[48:63]
	v_mfma_f32_32x32x16_bf16 v[16:31], v[64:67], v[148:151], v[16:31]
	v_mfma_f32_32x32x16_bf16 v[32:47], v[64:67], v[156:159], v[32:47]
	v_mfma_f32_32x32x16_bf16 v[0:15], v[68:71], v[136:139], v[0:15]
	v_mfma_f32_32x32x16_bf16 v[48:63], v[68:71], v[144:147], v[48:63]
	v_mfma_f32_32x32x16_bf16 v[16:31], v[68:71], v[152:155], v[16:31]
	v_mfma_f32_32x32x16_bf16 v[32:47], v[68:71], v[162:165], v[32:47]
	s_waitcnt lgkmcnt(0)
	v_mfma_f32_32x32x16_bf16 v[64:79], v[100:103], v[92:95], 0
	v_mfma_f32_32x32x16_bf16 v[64:79], v[114:117], v[88:91], v[64:79]
	v_mfma_f32_32x32x16_bf16 v[64:79], v[118:121], v[84:87], v[64:79]
	v_mfma_f32_32x32x16_bf16 v[64:79], v[122:125], v[80:83], v[64:79]
	s_setprio 0
	s_cbranch_vccnz .LBB0_1969
	v_add3_u32 v97, s88, v97, v130
	v_add_u32_e32 v118, 0x408, v97
	v_add_u32_e32 v120, 0x420, v97
	v_add_u32_e32 v122, 0x428, v97
	v_add_u32_e32 v100, 0x440, v97
	v_add_u32_e32 v102, 0x448, v97
	v_add_u32_e32 v104, 0x460, v97
	v_add_u32_e32 v99, 0x400, v97
	v_add_u32_e32 v97, 0x468, v97
	ds_read2_b32 v[100:101], v100 offset1:1
	ds_read2_b32 v[102:103], v102 offset1:1
	ds_read2_b32 v[104:105], v104 offset1:1
	ds_read2_b32 v[114:115], v97 offset1:1
	ds_read2_b32 v[116:117], v99 offset1:1
	ds_read2_b32 v[118:119], v118 offset1:1
	ds_read2_b32 v[120:121], v120 offset1:1
	ds_read2_b32 v[122:123], v122 offset1:1
	s_waitcnt lgkmcnt(0)
	v_add_f32_e32 v78, v78, v114
	v_add_f32_e32 v79, v79, v115
	v_add_f32_e32 v76, v76, v104
	v_add_f32_e32 v77, v77, v105
	v_add_f32_e32 v74, v74, v102
	v_add_f32_e32 v75, v75, v103
	v_add_f32_e32 v72, v72, v100
	v_add_f32_e32 v73, v73, v101
	v_add_f32_e32 v70, v70, v122
	v_add_f32_e32 v71, v71, v123
	v_add_f32_e32 v68, v68, v120
	v_add_f32_e32 v69, v69, v121
	v_add_f32_e32 v66, v66, v118
	v_add_f32_e32 v67, v67, v119
	v_add_f32_e32 v64, v64, v116
	v_add_f32_e32 v65, v65, v117

.Lstg_d1_m62_23:
	v_mfma_f32_32x32x16_bf16 v[0:15], v[64:67], v[132:135], v[0:15]
	s_cmp_lt_i32 s47, 64
	s_cselect_b64 s[0:1], -1, 0
	s_cmp_gt_i32 s45, 63
	s_cselect_b64 s[2:3], -1, 0
	s_and_b64 s[0:1], s[2:3], s[0:1]
	v_cndmask_b32_e64 v97, 0, 1, s[0:1]
	v_cmp_ne_u32_e64 s[2:3], 1, v97
	v_mfma_f32_32x32x16_bf16 v[48:63], v[64:67], v[140:143], v[48:63]
	v_sub_u32_e32 v97, 0xfc0, v111
	s_andn2_b64 vcc, exec, s[0:1]
	v_lshlrev_b32_e32 v97, 2, v97
	v_mfma_f32_32x32x16_bf16 v[16:31], v[64:67], v[148:151], v[16:31]
	v_mfma_f32_32x32x16_bf16 v[32:47], v[64:67], v[156:159], v[32:47]
	v_mfma_f32_32x32x16_bf16 v[0:15], v[68:71], v[136:139], v[0:15]
	v_mfma_f32_32x32x16_bf16 v[48:63], v[68:71], v[144:147], v[48:63]
	v_mfma_f32_32x32x16_bf16 v[16:31], v[68:71], v[152:155], v[16:31]
	v_mfma_f32_32x32x16_bf16 v[32:47], v[68:71], v[162:165], v[32:47]
	s_waitcnt lgkmcnt(0)
	v_mfma_f32_32x32x16_bf16 v[64:79], v[100:103], v[92:95], 0
	v_mfma_f32_32x32x16_bf16 v[64:79], v[114:117], v[88:91], v[64:79]
	v_mfma_f32_32x32x16_bf16 v[64:79], v[118:121], v[84:87], v[64:79]
	v_mfma_f32_32x32x16_bf16 v[64:79], v[122:125], v[80:83], v[64:79]
	s_cbranch_vccnz .LBB0_1971
	v_add3_u32 v111, s88, v97, v130
	ds_read2_b32 v[98:99], v111 offset0:240 offset1:241
	ds_read2_b32 v[100:101], v111 offset0:242 offset1:243
	ds_read2_b32 v[102:103], v111 offset0:248 offset1:249
	ds_read2_b32 v[104:105], v111 offset0:250 offset1:251
	ds_read2_b32 v[114:115], v111 offset0:224 offset1:225
	ds_read2_b32 v[116:117], v111 offset0:226 offset1:227
	ds_read2_b32 v[118:119], v111 offset0:232 offset1:233
	ds_read2_b32 v[120:121], v111 offset0:234 offset1:235
	s_waitcnt lgkmcnt(0)
	s_nop 0
	v_add_f32_e32 v78, v78, v104
	v_add_f32_e32 v79, v79, v105
	v_add_f32_e32 v76, v76, v102
	v_add_f32_e32 v77, v77, v103
	v_add_f32_e32 v74, v74, v100
	v_add_f32_e32 v75, v75, v101
	v_add_f32_e32 v72, v72, v98
	v_add_f32_e32 v73, v73, v99
	v_add_f32_e32 v70, v70, v120
	v_add_f32_e32 v71, v71, v121
	v_add_f32_e32 v68, v68, v118
	v_add_f32_e32 v69, v69, v119
	v_add_f32_e32 v66, v66, v116
	v_add_f32_e32 v67, v67, v117
	v_add_f32_e32 v64, v64, v114
	v_add_f32_e32 v65, v65, v115

; template <int DQK, int MODE, int LDQ, int LDK, int LDV> ...
;     ...
;         ATT_STEP(pA, pB, 0, v0, true, 1, j);
;         ATT_STEP(pB, pA, 1, v0, (j + 1 < NT), 0, j + 1);
.LBB0_1973:
	ds_read_b128 v[98:101], v107 offset:28672
	ds_read_b128 v[102:105], v108 offset:28672
	ds_read_b128 v[112:115], v109 offset:28672
	ds_read_b128 v[108:111], v110 offset:28672
	ds_read_b64_tr_b16 v[116:117], v106 offset:0
	ds_read_b64_tr_b16 v[118:119], v106 offset:0x800
	ds_read_b64_tr_b16 v[120:121], v106 offset:0x1000
	ds_read_b64_tr_b16 v[122:123], v106 offset:0x1800
	ds_read_b64_tr_b16 v[124:125], v106 offset:0x200
	ds_read_b64_tr_b16 v[126:127], v106 offset:0xa00
	ds_read_b64_tr_b16 v[132:133], v106 offset:0x1200
	ds_read_b64_tr_b16 v[134:135], v106 offset:0x1a00
	ds_read_b64_tr_b16 v[136:137], v106 offset:0x400
	ds_read_b64_tr_b16 v[138:139], v106 offset:0xc00
	ds_read_b64_tr_b16 v[140:141], v106 offset:0x1400
	ds_read_b64_tr_b16 v[142:143], v106 offset:0x1c00
	ds_read_b64_tr_b16 v[144:145], v106 offset:0x600
	ds_read_b64_tr_b16 v[146:147], v106 offset:0xe00
	ds_read_b64_tr_b16 v[148:149], v106 offset:0x1600
	ds_read_b64_tr_b16 v[150:151], v106 offset:0x1e00
	s_setprio 1
	v_exp_f32_e32 v64, v64
	v_exp_f32_e32 v65, v65
	v_exp_f32_e32 v66, v66
	v_exp_f32_e32 v67, v67
	v_exp_f32_e32 v68, v68
	v_exp_f32_e32 v69, v69
	v_add_f32_e32 v107, v65, v64
	v_exp_f32_e32 v70, v70
	v_add_f32_e32 v107, v66, v107
	v_exp_f32_e32 v71, v71
	v_add_f32_e32 v107, v67, v107
	v_exp_f32_e32 v72, v72
	v_add_f32_e32 v107, v68, v107
	v_exp_f32_e32 v73, v73
	v_add_f32_e32 v107, v69, v107
	v_exp_f32_e32 v74, v74
	v_add_f32_e32 v107, v70, v107
	v_exp_f32_e32 v75, v75
	v_add_f32_e32 v107, v71, v107
	v_exp_f32_e32 v76, v76
	v_add_f32_e32 v107, v72, v107
	v_exp_f32_e32 v77, v77
	v_add_f32_e32 v107, v73, v107
	v_exp_f32_e32 v78, v78
	v_add_f32_e32 v107, v74, v107
	v_exp_f32_e32 v79, v79
	v_add_f32_e32 v107, v75, v107
	v_add_f32_e32 v107, v76, v107
	v_add_f32_e32 v107, v77, v107
	v_add_f32_e32 v107, v78, v107
	v_add_f32_e32 v107, v79, v107
	v_add_f32_e32 v96, v107, v96
	v_cvt_pk_bf16_f32 v64, v64, v65
	v_cvt_pk_bf16_f32 v65, v66, v67
	v_cvt_pk_bf16_f32 v66, v68, v69
	v_cvt_pk_bf16_f32 v67, v70, v71
	v_cvt_pk_bf16_f32 v68, v72, v73
	v_cvt_pk_bf16_f32 v69, v74, v75
	v_cvt_pk_bf16_f32 v70, v76, v77
	v_cvt_pk_bf16_f32 v71, v78, v79
	s_waitcnt lgkmcnt(0)
	s_setprio 2
	v_mfma_f32_32x32x16_bf16 v[0:15], v[64:67], v[116:119], v[0:15]
	s_and_b64 vcc, exec, s[2:3]
	v_mfma_f32_32x32x16_bf16 v[48:63], v[64:67], v[124:127], v[48:63]
	v_mfma_f32_32x32x16_bf16 v[16:31], v[64:67], v[136:139], v[16:31]
	v_mfma_f32_32x32x16_bf16 v[32:47], v[64:67], v[144:147], v[32:47]
	v_mfma_f32_32x32x16_bf16 v[0:15], v[68:71], v[120:123], v[0:15]
	v_mfma_f32_32x32x16_bf16 v[48:63], v[68:71], v[132:135], v[48:63]
	v_mfma_f32_32x32x16_bf16 v[16:31], v[68:71], v[140:143], v[16:31]
	v_mfma_f32_32x32x16_bf16 v[32:47], v[68:71], v[148:151], v[32:47]
	s_waitcnt lgkmcnt(0)
	v_mfma_f32_32x32x16_bf16 v[64:79], v[98:101], v[92:95], 0
	v_mfma_f32_32x32x16_bf16 v[64:79], v[102:105], v[88:91], v[64:79]
	v_mfma_f32_32x32x16_bf16 v[64:79], v[112:115], v[84:87], v[64:79]
	v_mfma_f32_32x32x16_bf16 v[64:79], v[108:111], v[80:83], v[64:79]
	s_setprio 0
	s_cbranch_vccnz .LBB0_1975
	v_add3_u32 v80, s88, v97, v130
	v_add_u32_e32 v88, 0x400, v80
	v_add_u32_e32 v90, 0x408, v80
	v_add_u32_e32 v92, 0x420, v80
	v_add_u32_e32 v94, 0x428, v80
	v_add_u32_e32 v81, 0x440, v80
	v_add_u32_e32 v82, 0x448, v80
	v_add_u32_e32 v84, 0x460, v80
	v_add_u32_e32 v86, 0x468, v80
	ds_read2_b32 v[80:81], v81 offset1:1
	ds_read2_b32 v[82:83], v82 offset1:1
	ds_read2_b32 v[84:85], v84 offset1:1
	ds_read2_b32 v[86:87], v86 offset1:1
	ds_read2_b32 v[88:89], v88 offset1:1
	ds_read2_b32 v[90:91], v90 offset1:1
	ds_read2_b32 v[92:93], v92 offset1:1
	ds_read2_b32 v[94:95], v94 offset1:1
	s_waitcnt lgkmcnt(0)
	v_add_f32_e32 v78, v78, v86
	v_add_f32_e32 v79, v79, v87
	v_add_f32_e32 v76, v76, v84
	v_add_f32_e32 v77, v77, v85
	v_add_f32_e32 v74, v74, v82
	v_add_f32_e32 v75, v75, v83
	v_add_f32_e32 v72, v72, v80
	v_add_f32_e32 v73, v73, v81
	v_add_f32_e32 v70, v70, v94
	v_add_f32_e32 v71, v71, v95
	v_add_f32_e32 v68, v68, v92
	v_add_f32_e32 v69, v69, v93
	v_add_f32_e32 v66, v66, v90
	v_add_f32_e32 v67, v67, v91
	v_add_f32_e32 v64, v64, v88
	v_add_f32_e32 v65, v65, v89
.LBB0_1975:
	s_lshl_b32 s0, s44, 2
	s_add_i32 s0, s0, 0
	s_add_i32 s0, s0, 0x24000
	ds_read_b64_tr_b16 v[80:81], v106 offset:0x2000
	ds_read_b64_tr_b16 v[82:83], v106 offset:0x2800
	ds_read_b64_tr_b16 v[84:85], v106 offset:0x3000
	ds_read_b64_tr_b16 v[86:87], v106 offset:0x3800
	ds_read_b64_tr_b16 v[88:89], v106 offset:0x2200
	ds_read_b64_tr_b16 v[90:91], v106 offset:0x2a00
	ds_read_b64_tr_b16 v[92:93], v106 offset:0x3200
	ds_read_b64_tr_b16 v[94:95], v106 offset:0x3a00
	ds_read_b64_tr_b16 v[98:99], v106 offset:0x2400
	ds_read_b64_tr_b16 v[100:101], v106 offset:0x2c00
	ds_read_b64_tr_b16 v[102:103], v106 offset:0x3400
	ds_read_b64_tr_b16 v[104:105], v106 offset:0x3c00
	ds_read_b64_tr_b16 v[108:109], v106 offset:0x2600
	ds_read_b64_tr_b16 v[110:111], v106 offset:0x2e00
	ds_read_b64_tr_b16 v[112:113], v106 offset:0x3600
	ds_read_b64_tr_b16 v[114:115], v106 offset:0x3e00
	s_nop 7
	s_setprio 1
	v_exp_f32_e32 v97, v64
	v_exp_f32_e32 v65, v65
	v_exp_f32_e32 v106, v66
	v_exp_f32_e32 v67, v67
	v_exp_f32_e32 v68, v68
	v_exp_f32_e32 v69, v69
	v_add_f32_e32 v64, v65, v97
	v_exp_f32_e32 v70, v70
	v_add_f32_e32 v64, v106, v64
	v_exp_f32_e32 v71, v71
	v_add_f32_e32 v64, v67, v64
	v_exp_f32_e32 v72, v72
	v_add_f32_e32 v64, v68, v64
	v_exp_f32_e32 v73, v73
	v_add_f32_e32 v64, v69, v64
	v_exp_f32_e32 v74, v74
	v_add_f32_e32 v64, v70, v64
	v_exp_f32_e32 v75, v75
	v_add_f32_e32 v64, v71, v64
	v_exp_f32_e32 v76, v76
	v_add_f32_e32 v64, v72, v64
	v_exp_f32_e32 v77, v77
	v_add_f32_e32 v64, v73, v64
	v_exp_f32_e32 v78, v78
	v_add_f32_e32 v64, v74, v64
	v_exp_f32_e32 v79, v79
	v_add_f32_e32 v64, v75, v64
	v_add_f32_e32 v64, v76, v64
	v_add_f32_e32 v64, v77, v64
	v_add_f32_e32 v64, v78, v64
	v_add_f32_e32 v64, v79, v64
	v_add_f32_e32 v64, v96, v64
	v_cvt_pk_bf16_f32 v66, v97, v65
	v_cvt_pk_bf16_f32 v67, v106, v67
	v_cvt_pk_bf16_f32 v68, v68, v69
	v_cvt_pk_bf16_f32 v69, v70, v71
	v_cvt_pk_bf16_f32 v70, v72, v73
	v_cvt_pk_bf16_f32 v71, v74, v75
	v_cvt_pk_bf16_f32 v72, v76, v77
	v_cvt_pk_bf16_f32 v73, v78, v79
	s_waitcnt lgkmcnt(0)
; template <int TAG = 0> DI int fresh_tid(int wv) { int l; asm volatile("v_mbcnt_lo_u32_b32 %0, -1, 0\n\tv_mbcnt_hi_u32_b32 %0, -1, %0 ; site %1" : "=v"(l) : "n"(TAG)); return wv * 64 + l; }
; DI int crow(int r, int hi) { return (r & 3) + 8 * (r >> 2) + 4 * hi; }
; DI float swap_sum(float v) { auto rr = __builtin_amdgcn_permlane32_swap(__float_as_uint(v), __float_as_uint(v), false, false); return __uint_as_float(rr[0]) + __uint_as_float(rr[1]); }
; template <int DQK, int MODE, int LDQ, int LDK, int LDV> ...
;     ...
;     l_reg = swap_sum(l_reg);
;     { const int lane2 = fresh_tid<110 + MODE>(wv) & 63, r32 = lane2 & 31, hi = lane2 >> 5;
;     if (hi == 0) li_l[r32] = l_reg;
;     asm volatile("s_waitcnt lgkmcnt(0)" ::: "memory");
;     float s0v[MODE == 2 ? 16 : 1][4];
;     if constexpr (MODE == 2) {
; #pragma unroll
;         for (int r = 0; r < 16; ++r)
; #pragma unroll
;             for (int d0 = 0; d0 < 4; ++d0) s0v[r][d0] = S0[(size_t)(wid * 32 + crow(r, hi)) * 512 + d0 * 32 + r32];
;     }
	s_setprio 2
	v_mfma_f32_32x32x16_bf16 v[0:15], v[66:69], v[80:83], v[0:15]
	v_mfma_f32_32x32x16_bf16 v[48:63], v[66:69], v[88:91], v[48:63]
	v_mfma_f32_32x32x16_bf16 v[16:31], v[66:69], v[98:101], v[16:31]
	v_mfma_f32_32x32x16_bf16 v[32:47], v[66:69], v[108:111], v[32:47]
	v_mfma_f32_32x32x16_bf16 v[0:15], v[70:73], v[84:87], v[0:15]
	v_mfma_f32_32x32x16_bf16 v[48:63], v[70:73], v[92:95], v[48:63]
	v_mfma_f32_32x32x16_bf16 v[16:31], v[70:73], v[102:105], v[16:31]
	v_mfma_f32_32x32x16_bf16 v[32:47], v[70:73], v[112:115], v[32:47]
	s_setprio 0
	v_mov_b32_e32 v66, v64
	v_mbcnt_lo_u32_b32 v65, -1, 0
	v_mbcnt_hi_u32_b32 v65, -1, v65
	s_nop 1
	v_permlane32_swap_b32_e32 v64, v66
	v_and_b32_e32 v114, 63, v65
	v_and_b32_e32 v170, 31, v65
	v_cmp_gt_u32_e32 vcc, 32, v114
	s_and_saveexec_b64 s[2:3], vcc
	v_lshl_add_u32 v67, v170, 2, s0
	v_add_f32_e32 v64, v64, v66
	ds_write_b32 v67, v64
	s_or_b64 exec, exec, s[2:3]
	v_lshrrev_b32_e32 v64, 3, v65
	v_and_b32_e32 v69, 4, v64
	v_or_b32_e32 v102, s46, v69
	v_lshlrev_b32_e32 v130, 2, v170
	v_ashrrev_i32_e32 v103, 31, v102
	v_or_b32_e32 v66, 1, v102
	v_lshl_add_u64 v[92:93], s[54:55], 0, v[130:131]
	v_lshlrev_b64 v[156:157], 11, v[102:103]
	v_ashrrev_i32_e32 v67, 31, v66
	s_waitcnt lgkmcnt(0)
	v_lshl_add_u64 v[64:65], v[92:93], 0, v[156:157]
	v_lshlrev_b64 v[148:149], 11, v[66:67]
	v_lshl_add_u64 v[66:67], v[92:93], 0, v[148:149]
	global_load_dword v110, v[64:65], off
	global_load_dword v111, v[64:65], off offset:128
	global_load_dword v109, v[64:65], off offset:256
	global_load_dword v108, v[64:65], off offset:384
	global_load_dword v106, v[66:67], off
	global_load_dword v107, v[66:67], off offset:128
	global_load_dword v105, v[66:67], off offset:256
	global_load_dword v104, v[66:67], off offset:384
	v_or_b32_e32 v64, 2, v102
	v_or_b32_e32 v66, 3, v102
	v_ashrrev_i32_e32 v65, 31, v64
	v_ashrrev_i32_e32 v67, 31, v66
	v_lshlrev_b64 v[146:147], 11, v[64:65]
	v_lshlrev_b64 v[136:137], 11, v[66:67]
	v_lshl_add_u64 v[64:65], v[92:93], 0, v[146:147]
	v_lshl_add_u64 v[66:67], v[92:93], 0, v[136:137]
	global_load_dword v158, v[64:65], off
	global_load_dword v159, v[64:65], off offset:128
	global_load_dword v155, v[64:65], off offset:256
	global_load_dword v154, v[64:65], off offset:384
	global_load_dword v152, v[66:67], off
	global_load_dword v153, v[66:67], off offset:128
	global_load_dword v151, v[66:67], off offset:256
	global_load_dword v150, v[66:67], off offset:384
	v_or_b32_e32 v64, 8, v102
	v_or_b32_e32 v66, 9, v102
	v_ashrrev_i32_e32 v65, 31, v64
	v_ashrrev_i32_e32 v67, 31, v66
	v_lshlrev_b64 v[134:135], 11, v[64:65]
	v_lshlrev_b64 v[120:121], 11, v[66:67]
	v_lshl_add_u64 v[64:65], v[92:93], 0, v[134:135]
	v_lshl_add_u64 v[66:67], v[92:93], 0, v[120:121]
	global_load_dword v144, v[64:65], off
	global_load_dword v145, v[64:65], off offset:128
	global_load_dword v143, v[64:65], off offset:256
	global_load_dword v142, v[64:65], off offset:384
	global_load_dword v140, v[66:67], off
	global_load_dword v141, v[66:67], off offset:128
	global_load_dword v139, v[66:67], off offset:256
	global_load_dword v138, v[66:67], off offset:384
	v_or_b32_e32 v64, 10, v102
	v_or_b32_e32 v66, 11, v102
	v_ashrrev_i32_e32 v65, 31, v64
	v_ashrrev_i32_e32 v67, 31, v66
	v_lshlrev_b64 v[118:119], 11, v[64:65]
	v_lshlrev_b64 v[90:91], 11, v[66:67]
	v_lshl_add_u64 v[64:65], v[92:93], 0, v[118:119]
	v_lshl_add_u64 v[66:67], v[92:93], 0, v[90:91]
	global_load_dword v132, v[64:65], off
	global_load_dword v133, v[64:65], off offset:128
	global_load_dword v127, v[64:65], off offset:256
	global_load_dword v126, v[64:65], off offset:384
	global_load_dword v124, v[66:67], off
	global_load_dword v125, v[66:67], off offset:128
	global_load_dword v123, v[66:67], off offset:256
	global_load_dword v122, v[66:67], off offset:384
	v_or_b32_e32 v64, 16, v102
	v_or_b32_e32 v66, 17, v102
	v_ashrrev_i32_e32 v65, 31, v64
	v_ashrrev_i32_e32 v67, 31, v66
	v_lshlrev_b64 v[86:87], 11, v[64:65]
	v_lshlrev_b64 v[78:79], 11, v[66:67]
	v_lshl_add_u64 v[64:65], v[92:93], 0, v[86:87]
	v_lshl_add_u64 v[66:67], v[92:93], 0, v[78:79]
	global_load_dword v100, v[64:65], off
	global_load_dword v101, v[64:65], off offset:128
	global_load_dword v99, v[64:65], off offset:256
	global_load_dword v98, v[64:65], off offset:384
	global_load_dword v96, v[66:67], off
	global_load_dword v97, v[66:67], off offset:128
	global_load_dword v95, v[66:67], off offset:256
	global_load_dword v94, v[66:67], off offset:384
	v_or_b32_e32 v64, 18, v102
	v_or_b32_e32 v66, 19, v102
	v_ashrrev_i32_e32 v65, 31, v64
	v_ashrrev_i32_e32 v67, 31, v66
	v_lshlrev_b64 v[76:77], 11, v[64:65]
	v_lshlrev_b64 v[72:73], 11, v[66:67]
	v_lshl_add_u64 v[64:65], v[92:93], 0, v[76:77]
	v_lshl_add_u64 v[66:67], v[92:93], 0, v[72:73]
	v_lshl_add_u32 v169, v69, 2, s0
	global_load_dword v88, v[64:65], off
	global_load_dword v89, v[64:65], off offset:128
	global_load_dword v85, v[64:65], off offset:256
	global_load_dword v84, v[64:65], off offset:384
	global_load_dword v82, v[66:67], off
	global_load_dword v83, v[66:67], off offset:128
	global_load_dword v81, v[66:67], off offset:256
	global_load_dword v80, v[66:67], off offset:384
	ds_read_b128 v[64:67], v169
	v_or_b32_e32 v68, 24, v102
	v_ashrrev_i32_e32 v69, 31, v68
	v_lshlrev_b64 v[74:75], 11, v[68:69]
	ds_read_b128 v[68:71], v169 offset:32
	s_waitcnt lgkmcnt(0)
; DI unsigned short f2bf(float x) { unsigned u = __float_as_uint(x); u += 0x7fffu + ((u >> 16) & 1u); return (unsigned short)(u >> 16); }
; DI float shx(float v, int mask, int lane) { return __int_as_float(__builtin_amdgcn_ds_bpermute((lane ^ mask) << 2, __float_as_int(v))); }
; DI int crow(int r, int hi) { return (r & 3) + 8 * (r >> 2) + 4 * hi; }
; template <int DQK, int MODE, int LDQ, int LDK, int LDV> ...
;     ...
;     for (int r = 0; r < 16; ++r) { const int orow = wid * 32 + crow(r, hi); const float rl = __builtin_amdgcn_rcpf(li_l[crow(r, hi)]);
;         if constexpr (MODE == 0) {
; #pragma unroll
;             for (int d0 = 0; d0 < 4; ++d0) AOb[(size_t)orow * 1024 + d0 * 32 + r32] = f2bf(o[d0][r] * rl);
;         } else if constexpr (MODE == 1) {
; #pragma unroll
;             for (int d0 = 0; d0 < 4; ++d0) S0[(size_t)orow * 512 + d0 * 32 + r32] = o[d0][r] * rl;
;         } else {
;             float v[4]; float ss = 0.f;
; #pragma unroll
;             for (int d0 = 0; d0 < 4; ++d0) { v[d0] = s0v[r][d0] - lam * (o[d0][r] * rl); ss += v[d0] * v[d0]; }
; #pragma unroll
;             for (int mk = 1; mk <= 16; mk <<= 1) ss += shx(ss, mk, lane2);
;             const float rs = rsqrtf(ss * (1.f / 128.f) + EPS) * 0.8f;
; #pragma unroll
;             for (int d0 = 0; d0 < 4; ++d0) AOb[(size_t)orow * 1024 + d0 * 32 + r32] = f2bf(v[d0] * rs * gout[d0 * 32 + r32]);
	v_rcp_f32_e32 v64, v64
	v_mov_b32_e32 v162, v0
	v_mov_b32_e32 v163, v48
	v_rcp_f32_e32 v0, v65
	v_mul_f32_e32 v162, v162, v64
	v_mul_f32_e32 v163, v163, v64
	v_mov_b32_e32 v48, v1
	v_lshlrev_b32_e32 v166, 2, v114
	v_mul_f32_e32 v48, v48, v0
	v_mul_f32_e32 v49, v49, v0
	v_xor_b32_e32 v164, 4, v166
	v_xor_b32_e32 v165, 8, v166
	v_xor_b32_e32 v168, 16, v166
	v_xor_b32_e32 v167, 32, v166
	v_or_b32_e32 v116, 25, v102
	v_ashrrev_i32_e32 v117, 31, v116
	v_xor_b32_e32 v166, 64, v166
	v_lshl_add_u64 v[112:113], v[92:93], 0, v[74:75]
	s_add_u32 s1, s60, s58
	s_mov_b32 s0, 0x358637bd
	s_addc_u32 s3, s61, s59
	s_lshl_b32 s2, s87, 1
	s_add_u32 s2, s1, s2
	s_addc_u32 s3, s3, 0
	s_waitcnt vmcnt(0)
	v_pk_fma_f32 v[172:173], v[128:129], v[162:163], v[110:111] neg_lo:[1,0,0] neg_hi:[1,0,0]
	v_mov_b32_e32 v162, v32
	v_mov_b32_e32 v163, v16
	v_mul_f32_e32 v162, v162, v64
	v_mul_f32_e32 v163, v163, v64
	v_mov_b32_e32 v16, v33
	v_pk_fma_f32 v[174:175], v[128:129], v[162:163], v[108:109] neg_lo:[1,0,0] neg_hi:[1,0,0]
	global_load_dword v163, v130, s[50:51]
	global_load_dword v162, v130, s[50:51] offset:128
	global_load_dword v161, v130, s[50:51] offset:256
	s_nop 0
	global_load_dword v130, v130, s[50:51] offset:384
	v_pk_fma_f32 v[176:177], v[128:129], v[48:49], v[106:107] neg_lo:[1,0,0] neg_hi:[1,0,0]
	v_mul_f32_e32 v1, v17, v0
	v_mul_f32_e32 v0, v16, v0
	v_pk_mul_f32 v[110:111], v[172:173], v[172:173]
	v_pk_mul_f32 v[48:49], v[176:177], v[176:177]
	v_pk_fma_f32 v[0:1], v[128:129], v[0:1], v[104:105] neg_lo:[1,0,0] neg_hi:[1,0,0]
	v_pk_mul_f32 v[108:109], v[174:175], v[174:175]
	v_pk_mul_f32 v[16:17], v[0:1], v[0:1]
	v_mov_b32_e32 v32, v48
	v_mov_b32_e32 v33, v110
	v_mov_b32_e32 v110, v49
	v_add_f32_e32 v32, v32, v110
	v_add_f32_e32 v33, v33, v111
	v_mov_b32_e32 v48, v17
	v_mov_b32_e32 v49, v109
	v_add_f32_e32 v32, v48, v32
	v_add_f32_e32 v33, v49, v33
	v_mov_b32_e32 v17, v108
	v_add_f32_e32 v16, v16, v32
	v_add_f32_e32 v17, v17, v33
	ds_bpermute_b32 v33, v164, v17
	ds_bpermute_b32 v32, v164, v16
	v_lshlrev_b64 v[64:65], 11, v[116:117]
	v_lshl_add_u64 v[48:49], v[92:93], 0, v[64:65]
	global_load_dword v116, v[112:113], off
	global_load_dword v117, v[112:113], off offset:128
	global_load_dword v115, v[112:113], off offset:256
	global_load_dword v114, v[112:113], off offset:384
	s_nop 0
	global_load_dword v112, v[48:49], off
	global_load_dword v113, v[48:49], off offset:128
	global_load_dword v111, v[48:49], off offset:256
	global_load_dword v110, v[48:49], off offset:384
	v_or_b32_e32 v48, 26, v102
	s_waitcnt lgkmcnt(0)
	v_add_f32_e32 v16, v16, v32
	v_add_f32_e32 v17, v17, v33
	ds_bpermute_b32 v33, v165, v17
	ds_bpermute_b32 v32, v165, v16
	v_or_b32_e32 v102, 27, v102
	v_ashrrev_i32_e32 v49, 31, v48
	v_ashrrev_i32_e32 v103, 31, v102
	v_lshlrev_b64 v[48:49], 11, v[48:49]
	s_waitcnt lgkmcnt(0)
	v_add_f32_e32 v16, v16, v32
	v_add_f32_e32 v17, v17, v33
	ds_bpermute_b32 v33, v168, v17
	ds_bpermute_b32 v32, v168, v16
	v_lshl_add_u64 v[104:105], v[92:93], 0, v[48:49]
	v_lshlrev_b32_e32 v170, 1, v170
	v_mov_b32_e32 v171, v131
	v_rcp_f32_e32 v66, v66
	s_waitcnt lgkmcnt(0)
	v_add_f32_e32 v32, v16, v32
	v_add_f32_e32 v33, v17, v33
	ds_bpermute_b32 v107, v167, v33
	ds_bpermute_b32 v106, v167, v32
	v_lshlrev_b64 v[16:17], 11, v[102:103]
	v_lshl_add_u64 v[92:93], v[92:93], 0, v[16:17]
	s_waitcnt lgkmcnt(0)
	v_add_f32_e32 v32, v32, v106
	v_add_f32_e32 v33, v33, v107
	ds_bpermute_b32 v179, v166, v33
	ds_bpermute_b32 v178, v166, v32
	global_load_dword v108, v[104:105], off
	global_load_dword v109, v[104:105], off offset:128
	global_load_dword v107, v[104:105], off offset:256
	global_load_dword v106, v[104:105], off offset:384
	s_nop 0
	global_load_dword v104, v[92:93], off
	global_load_dword v105, v[92:93], off offset:128
	global_load_dword v103, v[92:93], off offset:256
	global_load_dword v102, v[92:93], off offset:384
	v_mov_b64_e32 v[92:93], s[0:1]
	s_waitcnt lgkmcnt(0)
	v_add_f32_e32 v32, v32, v178
	v_add_f32_e32 v33, v33, v179
	s_nop 0
	v_pk_fma_f32 v[178:179], v[32:33], s[24:25], v[92:93] op_sel_hi:[1,0,0]
	s_nop 0
	v_mul_f32_e32 v32, 0x4b800000, v179
	v_cmp_gt_f32_e32 vcc, s67, v179
	s_nop 1
	v_cndmask_b32_e32 v32, v179, v32, vcc
	v_rsq_f32_e32 v179, v32
	v_lshl_add_u64 v[32:33], s[2:3], 0, v[170:171]
	v_lshl_add_u64 v[156:157], v[32:33], 0, v[156:157]
	v_lshl_add_u64 v[148:149], v[32:33], 0, v[148:149]
	v_mul_f32_e32 v170, 0x45800000, v179
	v_cndmask_b32_e32 v170, v179, v170, vcc
	v_mul_f32_e32 v170, 0x3f4ccccd, v170
	v_mul_f32_e32 v171, v172, v170
	v_cmp_gt_f32_e32 vcc, s67, v178
	s_mov_b64 s[2:3], 0
	s_waitcnt vmcnt(19)
	v_mul_f32_e32 v171, v163, v171
	v_bfe_u32 v172, v171, 16, 1
	v_add3_u32 v171, v171, v172, s68
	global_store_short_d16_hi v[156:157], v171, off offset:1024
	v_mul_f32_e32 v171, v173, v170
	s_waitcnt vmcnt(19)
	v_mul_f32_e32 v171, v162, v171
	v_bfe_u32 v172, v171, 16, 1
	v_add3_u32 v171, v171, v172, s68
	global_store_short_d16_hi v[156:157], v171, off offset:1088
	v_mul_f32_e32 v171, v175, v170
	s_waitcnt vmcnt(19)
	v_mul_f32_e32 v171, v161, v171
	v_bfe_u32 v172, v171, 16, 1
	v_add3_u32 v171, v171, v172, s68
	global_store_short_d16_hi v[156:157], v171, off offset:1152
	v_mul_f32_e32 v171, 0x4b800000, v178
	v_cndmask_b32_e32 v171, v178, v171, vcc
	v_mul_f32_e32 v170, v174, v170
	v_rsq_f32_e32 v171, v171
	s_waitcnt vmcnt(19)
; DI unsigned short f2bf(float x) { unsigned u = __float_as_uint(x); u += 0x7fffu + ((u >> 16) & 1u); return (unsigned short)(u >> 16); }
; DI float shx(float v, int mask, int lane) { return __int_as_float(__builtin_amdgcn_ds_bpermute((lane ^ mask) << 2, __float_as_int(v))); }
; DI int crow(int r, int hi) { return (r & 3) + 8 * (r >> 2) + 4 * hi; }
; template <int DQK, int MODE, int LDQ, int LDK, int LDV> ...
;     ...
;     for (int r = 0; r < 16; ++r) { const int orow = wid * 32 + crow(r, hi); const float rl = __builtin_amdgcn_rcpf(li_l[crow(r, hi)]);
;         if constexpr (MODE == 0) {
; #pragma unroll
;             for (int d0 = 0; d0 < 4; ++d0) AOb[(size_t)orow * 1024 + d0 * 32 + r32] = f2bf(o[d0][r] * rl);
;         } else if constexpr (MODE == 1) {
; #pragma unroll
;             for (int d0 = 0; d0 < 4; ++d0) S0[(size_t)orow * 512 + d0 * 32 + r32] = o[d0][r] * rl;
;         } else {
;             float v[4]; float ss = 0.f;
; #pragma unroll
;             for (int d0 = 0; d0 < 4; ++d0) { v[d0] = s0v[r][d0] - lam * (o[d0][r] * rl); ss += v[d0] * v[d0]; }
; #pragma unroll
;             for (int mk = 1; mk <= 16; mk <<= 1) ss += shx(ss, mk, lane2);
;             const float rs = rsqrtf(ss * (1.f / 128.f) + EPS) * 0.8f;
; #pragma unroll
;             for (int d0 = 0; d0 < 4; ++d0) AOb[(size_t)orow * 1024 + d0 * 32 + r32] = f2bf(v[d0] * rs * gout[d0 * 32 + r32]);
	v_mul_f32_e32 v170, v130, v170
	v_bfe_u32 v172, v170, 16, 1
	v_add3_u32 v170, v170, v172, s68
	global_store_short_d16_hi v[156:157], v170, off offset:1216
	v_mul_f32_e32 v156, 0x45800000, v171
	v_cndmask_b32_e32 v172, v171, v156, vcc
	v_mov_b32_e32 v156, v2
	v_rcp_f32_e32 v2, v67
	v_mov_b32_e32 v157, v50
	v_mov_b32_e32 v50, v3
	v_mul_f32_e32 v156, v156, v66
	v_mul_f32_e32 v157, v157, v66
	v_mov_b32_e32 v170, v34
	v_mov_b32_e32 v171, v18
	v_mul_f32_e32 v50, v50, v2
	v_mul_f32_e32 v51, v51, v2
	v_mov_b32_e32 v18, v35
	v_pk_fma_f32 v[156:157], v[128:129], v[156:157], v[158:159] neg_lo:[1,0,0] neg_hi:[1,0,0]
	v_mul_f32_e32 v170, v170, v66
	v_mul_f32_e32 v171, v171, v66
	v_pk_fma_f32 v[50:51], v[128:129], v[50:51], v[152:153] neg_lo:[1,0,0] neg_hi:[1,0,0]
	v_mul_f32_e32 v3, v19, v2
	v_mul_f32_e32 v2, v18, v2
	v_pk_mul_f32 v[158:159], v[156:157], v[156:157]
	v_pk_fma_f32 v[66:67], v[128:129], v[170:171], v[154:155] neg_lo:[1,0,0] neg_hi:[1,0,0]
	v_pk_mul_f32 v[152:153], v[50:51], v[50:51]
	v_pk_fma_f32 v[2:3], v[128:129], v[2:3], v[150:151] neg_lo:[1,0,0] neg_hi:[1,0,0]
	v_pk_mul_f32 v[154:155], v[66:67], v[66:67]
	v_pk_mul_f32 v[18:19], v[2:3], v[2:3]
	v_mov_b32_e32 v34, v152
	v_mov_b32_e32 v35, v158
	v_mov_b32_e32 v158, v153
	v_add_f32_e32 v34, v34, v158
	v_add_f32_e32 v35, v35, v159
	v_mov_b32_e32 v150, v19
	v_mov_b32_e32 v151, v155
	v_add_f32_e32 v34, v150, v34
	v_add_f32_e32 v35, v151, v35
	v_mov_b32_e32 v19, v154
	v_add_f32_e32 v18, v18, v34
	v_add_f32_e32 v19, v19, v35
	ds_bpermute_b32 v35, v164, v19
	ds_bpermute_b32 v34, v164, v18
	v_mul_f32_e32 v150, 0x3f4ccccd, v172
	v_mul_f32_e32 v151, v176, v150
	v_mul_f32_e32 v151, v163, v151
	v_bfe_u32 v152, v151, 16, 1
	s_waitcnt lgkmcnt(0)
	v_add_f32_e32 v18, v18, v34
	v_add_f32_e32 v19, v19, v35
	ds_bpermute_b32 v35, v165, v19
	ds_bpermute_b32 v34, v165, v18
	v_add3_u32 v151, v151, v152, s68
	global_store_short_d16_hi v[148:149], v151, off offset:1024
	v_mul_f32_e32 v151, v177, v150
	v_mul_f32_e32 v151, v162, v151
	s_waitcnt lgkmcnt(0)
	v_add_f32_e32 v18, v18, v34
	v_add_f32_e32 v19, v19, v35
	ds_bpermute_b32 v35, v168, v19
	ds_bpermute_b32 v34, v168, v18
	v_bfe_u32 v152, v151, 16, 1
	v_mul_f32_e32 v1, v1, v150
	v_add3_u32 v151, v151, v152, s68
	v_mul_f32_e32 v1, v161, v1
	s_waitcnt lgkmcnt(0)
	v_add_f32_e32 v18, v18, v34
	v_add_f32_e32 v19, v19, v35
	ds_bpermute_b32 v35, v167, v19
	ds_bpermute_b32 v34, v167, v18
	global_store_short_d16_hi v[148:149], v151, off offset:1088
	v_bfe_u32 v151, v1, 16, 1
	v_add3_u32 v1, v1, v151, s68
	v_mul_f32_e32 v0, v0, v150
	s_waitcnt lgkmcnt(0)
	v_add_f32_e32 v18, v18, v34
	v_add_f32_e32 v19, v19, v35
	ds_bpermute_b32 v35, v166, v19
	ds_bpermute_b32 v34, v166, v18
	global_store_short_d16_hi v[148:149], v1, off offset:1152
	v_mul_f32_e32 v150, v130, v0
	v_bfe_u32 v151, v150, 16, 1
	s_waitcnt lgkmcnt(0)
	v_add_f32_e32 v0, v18, v34
	v_add_f32_e32 v1, v19, v35
	s_nop 0
	v_pk_fma_f32 v[0:1], v[0:1], s[24:25], v[92:93] op_sel_hi:[1,0,0]
	s_nop 0
	v_mul_f32_e32 v18, 0x4b800000, v1
	v_cmp_gt_f32_e32 vcc, s67, v1
	s_nop 1
	v_cndmask_b32_e32 v1, v1, v18, vcc
	v_rsq_f32_e32 v1, v1
	v_add3_u32 v18, v150, v151, s68
	global_store_short_d16_hi v[148:149], v18, off offset:1216
	v_lshl_add_u64 v[18:19], v[32:33], 0, v[146:147]
	v_mul_f32_e32 v34, 0x45800000, v1
	v_cndmask_b32_e32 v1, v1, v34, vcc
	v_mul_f32_e32 v1, 0x3f4ccccd, v1
	v_mul_f32_e32 v34, v156, v1
	v_mul_f32_e32 v34, v163, v34
	v_bfe_u32 v35, v34, 16, 1
	v_add3_u32 v34, v34, v35, s68
	global_store_short_d16_hi v[18:19], v34, off offset:1024
	v_mul_f32_e32 v34, v157, v1
	v_mul_f32_e32 v34, v162, v34
	v_bfe_u32 v35, v34, 16, 1
	v_add3_u32 v34, v34, v35, s68
	global_store_short_d16_hi v[18:19], v34, off offset:1088
	v_mul_f32_e32 v34, v67, v1
	v_mul_f32_e32 v34, v161, v34
	v_bfe_u32 v35, v34, 16, 1
	v_add3_u32 v34, v34, v35, s68
	global_store_short_d16_hi v[18:19], v34, off offset:1152
	v_mul_f32_e32 v1, v66, v1
	v_mul_f32_e32 v34, 0x4b800000, v0
	v_cmp_gt_f32_e32 vcc, s67, v0
	v_mul_f32_e32 v1, v130, v1
	v_mov_b32_e32 v66, v36
	v_cndmask_b32_e32 v0, v0, v34, vcc
	v_rsq_f32_e32 v34, v0
	v_bfe_u32 v0, v1, 16, 1
	v_add3_u32 v0, v1, v0, s68
	global_store_short_d16_hi v[18:19], v0, off offset:1216
	v_rcp_f32_e32 v0, v68
	v_mov_b32_e32 v18, v4
	v_rcp_f32_e32 v4, v69
	v_mul_f32_e32 v1, 0x45800000, v34
	v_mov_b32_e32 v19, v52
	v_mov_b32_e32 v52, v5
	v_mul_f32_e32 v18, v18, v0
	v_mul_f32_e32 v19, v19, v0
	v_mov_b32_e32 v67, v20
	v_mul_f32_e32 v52, v52, v4
	v_mul_f32_e32 v53, v53, v4
	v_mov_b32_e32 v20, v37
	v_cndmask_b32_e32 v146, v34, v1, vcc
	v_pk_fma_f32 v[18:19], v[128:129], v[18:19], v[144:145] neg_lo:[1,0,0] neg_hi:[1,0,0]
	v_mul_f32_e32 v1, v67, v0
	v_mul_f32_e32 v0, v66, v0
	v_pk_fma_f32 v[52:53], v[128:129], v[52:53], v[140:141] neg_lo:[1,0,0] neg_hi:[1,0,0]
	v_mul_f32_e32 v5, v21, v4
	v_mul_f32_e32 v4, v20, v4
	v_pk_mul_f32 v[34:35], v[18:19], v[18:19]
	v_pk_fma_f32 v[0:1], v[128:129], v[0:1], v[142:143] neg_lo:[1,0,0] neg_hi:[1,0,0]
	v_pk_mul_f32 v[68:69], v[52:53], v[52:53]
	v_pk_fma_f32 v[4:5], v[128:129], v[4:5], v[138:139] neg_lo:[1,0,0] neg_hi:[1,0,0]
	v_pk_mul_f32 v[66:67], v[0:1], v[0:1]
	v_pk_mul_f32 v[20:21], v[4:5], v[4:5]
	v_mov_b32_e32 v36, v68
	v_mov_b32_e32 v37, v34
	v_mov_b32_e32 v34, v69
	v_add_f32_e32 v34, v36, v34
	v_add_f32_e32 v35, v37, v35
	v_mov_b32_e32 v36, v21
	v_mov_b32_e32 v37, v67
	v_add_f32_e32 v34, v36, v34
	v_add_f32_e32 v35, v37, v35
	v_mov_b32_e32 v21, v66
	v_add_f32_e32 v20, v20, v34
	v_add_f32_e32 v21, v21, v35
	ds_bpermute_b32 v35, v164, v21
	ds_bpermute_b32 v34, v164, v20
	v_mul_f32_e32 v66, 0x3f4ccccd, v146
	v_mul_f32_e32 v50, v50, v66
	v_mul_f32_e32 v50, v163, v50
	v_bfe_u32 v67, v50, 16, 1
	s_waitcnt lgkmcnt(0)
; DI unsigned short f2bf(float x) { unsigned u = __float_as_uint(x); u += 0x7fffu + ((u >> 16) & 1u); return (unsigned short)(u >> 16); }
; DI float shx(float v, int mask, int lane) { return __int_as_float(__builtin_amdgcn_ds_bpermute((lane ^ mask) << 2, __float_as_int(v))); }
; DI int crow(int r, int hi) { return (r & 3) + 8 * (r >> 2) + 4 * hi; }
; template <int DQK, int MODE, int LDQ, int LDK, int LDV> ...
;     ...
;     for (int r = 0; r < 16; ++r) { const int orow = wid * 32 + crow(r, hi); const float rl = __builtin_amdgcn_rcpf(li_l[crow(r, hi)]);
;         if constexpr (MODE == 0) {
; #pragma unroll
;             for (int d0 = 0; d0 < 4; ++d0) AOb[(size_t)orow * 1024 + d0 * 32 + r32] = f2bf(o[d0][r] * rl);
;         } else if constexpr (MODE == 1) {
; #pragma unroll
;             for (int d0 = 0; d0 < 4; ++d0) S0[(size_t)orow * 512 + d0 * 32 + r32] = o[d0][r] * rl;
;         } else {
;             float v[4]; float ss = 0.f;
; #pragma unroll
;             for (int d0 = 0; d0 < 4; ++d0) { v[d0] = s0v[r][d0] - lam * (o[d0][r] * rl); ss += v[d0] * v[d0]; }
; #pragma unroll
;             for (int mk = 1; mk <= 16; mk <<= 1) ss += shx(ss, mk, lane2);
;             const float rs = rsqrtf(ss * (1.f / 128.f) + EPS) * 0.8f;
; #pragma unroll
;             for (int d0 = 0; d0 < 4; ++d0) AOb[(size_t)orow * 1024 + d0 * 32 + r32] = f2bf(v[d0] * rs * gout[d0 * 32 + r32]);
	v_add_f32_e32 v20, v20, v34
	v_add_f32_e32 v21, v21, v35
	ds_bpermute_b32 v35, v165, v21
	ds_bpermute_b32 v34, v165, v20
	v_lshl_add_u64 v[36:37], v[32:33], 0, v[136:137]
	v_add3_u32 v50, v50, v67, s68
	global_store_short_d16_hi v[36:37], v50, off offset:1024
	v_mul_f32_e32 v50, v51, v66
	s_waitcnt lgkmcnt(0)
	v_add_f32_e32 v20, v20, v34
	v_add_f32_e32 v21, v21, v35
	ds_bpermute_b32 v35, v168, v21
	ds_bpermute_b32 v34, v168, v20
	v_mul_f32_e32 v50, v162, v50
	v_bfe_u32 v51, v50, 16, 1
	v_mul_f32_e32 v3, v3, v66
	v_add3_u32 v50, v50, v51, s68
	s_waitcnt lgkmcnt(0)
	v_add_f32_e32 v20, v20, v34
	v_add_f32_e32 v21, v21, v35
	ds_bpermute_b32 v35, v167, v21
	ds_bpermute_b32 v34, v167, v20
	v_mul_f32_e32 v3, v161, v3
	global_store_short_d16_hi v[36:37], v50, off offset:1088
	v_bfe_u32 v50, v3, 16, 1
	v_add3_u32 v3, v3, v50, s68
	s_waitcnt lgkmcnt(0)
	v_add_f32_e32 v20, v20, v34
	v_add_f32_e32 v21, v21, v35
	ds_bpermute_b32 v35, v166, v21
	ds_bpermute_b32 v34, v166, v20
	v_mul_f32_e32 v2, v2, v66
	global_store_short_d16_hi v[36:37], v3, off offset:1152
	v_mul_f32_e32 v50, v130, v2
	v_bfe_u32 v51, v50, 16, 1
	s_waitcnt lgkmcnt(0)
	v_add_f32_e32 v2, v20, v34
	v_add_f32_e32 v3, v21, v35
	s_nop 0
	v_pk_fma_f32 v[2:3], v[2:3], s[24:25], v[92:93] op_sel_hi:[1,0,0]
	s_nop 0
	v_mul_f32_e32 v20, 0x4b800000, v3
	v_cmp_gt_f32_e32 vcc, s67, v3
	s_nop 1
	v_cndmask_b32_e32 v3, v3, v20, vcc
	v_rsq_f32_e32 v3, v3
	v_add3_u32 v20, v50, v51, s68
	global_store_short_d16_hi v[36:37], v20, off offset:1216
	v_lshl_add_u64 v[20:21], v[32:33], 0, v[134:135]
	v_mul_f32_e32 v34, 0x45800000, v3
	v_cndmask_b32_e32 v3, v3, v34, vcc
	v_mul_f32_e32 v3, 0x3f4ccccd, v3
	v_mul_f32_e32 v18, v18, v3
	v_mul_f32_e32 v18, v163, v18
	v_bfe_u32 v34, v18, 16, 1
	v_add3_u32 v18, v18, v34, s68
	global_store_short_d16_hi v[20:21], v18, off offset:1024
	v_mul_f32_e32 v18, v19, v3
	v_mul_f32_e32 v18, v162, v18
	v_bfe_u32 v19, v18, 16, 1
	v_mul_f32_e32 v1, v1, v3
	v_add3_u32 v18, v18, v19, s68
	v_mul_f32_e32 v1, v161, v1
	global_store_short_d16_hi v[20:21], v18, off offset:1088
	v_bfe_u32 v18, v1, 16, 1
	v_add3_u32 v1, v1, v18, s68
	global_store_short_d16_hi v[20:21], v1, off offset:1152
	v_mul_f32_e32 v1, 0x4b800000, v2
	v_cmp_gt_f32_e32 vcc, s67, v2
	v_mul_f32_e32 v0, v0, v3
	v_mul_f32_e32 v0, v130, v0
	v_cndmask_b32_e32 v1, v2, v1, vcc
	v_rsq_f32_e32 v1, v1
	v_bfe_u32 v2, v0, 16, 1
	v_add3_u32 v0, v0, v2, s68
	global_store_short_d16_hi v[20:21], v0, off offset:1216
	v_mul_f32_e32 v2, 0x45800000, v1
	v_rcp_f32_e32 v0, v70
	v_cndmask_b32_e32 v66, v1, v2, vcc
	v_mov_b32_e32 v2, v6
	v_rcp_f32_e32 v6, v71
	v_mov_b32_e32 v3, v54
	v_mov_b32_e32 v18, v38
	v_mov_b32_e32 v19, v22
	v_mov_b32_e32 v54, v7
	v_mul_f32_e32 v2, v2, v0
	v_mul_f32_e32 v3, v3, v0
	v_mul_f32_e32 v1, v19, v0
	v_mul_f32_e32 v0, v18, v0
	v_mul_f32_e32 v18, v54, v6
	v_mul_f32_e32 v19, v55, v6
	v_mov_b32_e32 v22, v39
	v_pk_fma_f32 v[2:3], v[128:129], v[2:3], v[132:133] neg_lo:[1,0,0] neg_hi:[1,0,0]
	v_pk_fma_f32 v[20:21], v[128:129], v[18:19], v[124:125] neg_lo:[1,0,0] neg_hi:[1,0,0]
	v_mul_f32_e32 v7, v23, v6
	v_mul_f32_e32 v6, v22, v6
	v_pk_mul_f32 v[34:35], v[2:3], v[2:3]
	v_pk_fma_f32 v[0:1], v[128:129], v[0:1], v[126:127] neg_lo:[1,0,0] neg_hi:[1,0,0]
	v_pk_mul_f32 v[50:51], v[20:21], v[20:21]
	v_pk_fma_f32 v[18:19], v[128:129], v[6:7], v[122:123] neg_lo:[1,0,0] neg_hi:[1,0,0]
	v_pk_mul_f32 v[36:37], v[0:1], v[0:1]
	v_pk_mul_f32 v[6:7], v[18:19], v[18:19]
	v_mov_b32_e32 v22, v50
	v_mov_b32_e32 v23, v34
	v_mov_b32_e32 v34, v51
	v_add_f32_e32 v22, v22, v34
	v_add_f32_e32 v23, v23, v35
	v_mov_b32_e32 v34, v7
	v_mov_b32_e32 v35, v37
	v_add_f32_e32 v22, v34, v22
	v_add_f32_e32 v23, v35, v23
	v_mov_b32_e32 v7, v36
	v_add_f32_e32 v6, v6, v22
	v_add_f32_e32 v7, v7, v23
	ds_bpermute_b32 v23, v164, v7
	ds_bpermute_b32 v22, v164, v6
	v_mul_f32_e32 v36, 0x3f4ccccd, v66
	v_mul_f32_e32 v37, v52, v36
	v_mul_f32_e32 v37, v163, v37
	v_bfe_u32 v38, v37, 16, 1
	s_waitcnt lgkmcnt(0)
	v_add_f32_e32 v6, v6, v22
	v_add_f32_e32 v7, v7, v23
	ds_bpermute_b32 v23, v165, v7
	ds_bpermute_b32 v22, v165, v6
	v_lshl_add_u64 v[34:35], v[32:33], 0, v[120:121]
	v_add3_u32 v37, v37, v38, s68
	global_store_short_d16_hi v[34:35], v37, off offset:1024
	v_mul_f32_e32 v37, v53, v36
	s_waitcnt lgkmcnt(0)
	v_add_f32_e32 v6, v6, v22
	v_add_f32_e32 v7, v7, v23
	ds_bpermute_b32 v23, v168, v7
	ds_bpermute_b32 v22, v168, v6
	v_mul_f32_e32 v37, v162, v37
	v_bfe_u32 v38, v37, 16, 1
	v_mul_f32_e32 v5, v5, v36
	v_add3_u32 v37, v37, v38, s68
	s_waitcnt lgkmcnt(0)
	v_add_f32_e32 v6, v6, v22
	v_add_f32_e32 v7, v7, v23
	ds_bpermute_b32 v23, v167, v7
	ds_bpermute_b32 v22, v167, v6
	v_mul_f32_e32 v5, v161, v5
	global_store_short_d16_hi v[34:35], v37, off offset:1088
	v_bfe_u32 v37, v5, 16, 1
	v_add3_u32 v5, v5, v37, s68
	s_waitcnt lgkmcnt(0)
	v_add_f32_e32 v6, v6, v22
	v_add_f32_e32 v7, v7, v23
	ds_bpermute_b32 v23, v166, v7
	ds_bpermute_b32 v22, v166, v6
	v_mul_f32_e32 v4, v4, v36
	global_store_short_d16_hi v[34:35], v5, off offset:1152
	v_mul_f32_e32 v36, v130, v4
	v_bfe_u32 v37, v36, 16, 1
	s_waitcnt lgkmcnt(0)
; DI unsigned short f2bf(float x) { unsigned u = __float_as_uint(x); u += 0x7fffu + ((u >> 16) & 1u); return (unsigned short)(u >> 16); }
; DI float shx(float v, int mask, int lane) { return __int_as_float(__builtin_amdgcn_ds_bpermute((lane ^ mask) << 2, __float_as_int(v))); }
; DI int crow(int r, int hi) { return (r & 3) + 8 * (r >> 2) + 4 * hi; }
; template <int DQK, int MODE, int LDQ, int LDK, int LDV> ...
;     ...
;     for (int r = 0; r < 16; ++r) { const int orow = wid * 32 + crow(r, hi); const float rl = __builtin_amdgcn_rcpf(li_l[crow(r, hi)]);
;         if constexpr (MODE == 0) {
; #pragma unroll
;             for (int d0 = 0; d0 < 4; ++d0) AOb[(size_t)orow * 1024 + d0 * 32 + r32] = f2bf(o[d0][r] * rl);
;         } else if constexpr (MODE == 1) {
; #pragma unroll
;             for (int d0 = 0; d0 < 4; ++d0) S0[(size_t)orow * 512 + d0 * 32 + r32] = o[d0][r] * rl;
;         } else {
;             float v[4]; float ss = 0.f;
; #pragma unroll
;             for (int d0 = 0; d0 < 4; ++d0) { v[d0] = s0v[r][d0] - lam * (o[d0][r] * rl); ss += v[d0] * v[d0]; }
; #pragma unroll
;             for (int mk = 1; mk <= 16; mk <<= 1) ss += shx(ss, mk, lane2);
;             const float rs = rsqrtf(ss * (1.f / 128.f) + EPS) * 0.8f;
; #pragma unroll
;             for (int d0 = 0; d0 < 4; ++d0) AOb[(size_t)orow * 1024 + d0 * 32 + r32] = f2bf(v[d0] * rs * gout[d0 * 32 + r32]);
	v_add_f32_e32 v4, v6, v22
	v_add_f32_e32 v5, v7, v23
	v_lshl_add_u64 v[22:23], v[32:33], 0, v[118:119]
	v_pk_fma_f32 v[4:5], v[4:5], s[24:25], v[92:93] op_sel_hi:[1,0,0]
	s_nop 0
	v_mul_f32_e32 v6, 0x4b800000, v5
	v_cmp_gt_f32_e32 vcc, s67, v5
	s_nop 1
	v_cndmask_b32_e32 v5, v5, v6, vcc
	v_rsq_f32_e32 v5, v5
	v_add3_u32 v6, v36, v37, s68
	global_store_short_d16_hi v[34:35], v6, off offset:1216
	v_mov_b32_e32 v36, v40
	v_mul_f32_e32 v6, 0x45800000, v5
	v_cndmask_b32_e32 v5, v5, v6, vcc
	v_mul_f32_e32 v5, 0x3f4ccccd, v5
	v_mul_f32_e32 v2, v2, v5
	v_mul_f32_e32 v2, v163, v2
	v_bfe_u32 v6, v2, 16, 1
	v_add3_u32 v2, v2, v6, s68
	global_store_short_d16_hi v[22:23], v2, off offset:1024
	v_mul_f32_e32 v2, v3, v5
	v_mul_f32_e32 v2, v162, v2
	v_bfe_u32 v3, v2, 16, 1
	v_mul_f32_e32 v1, v1, v5
	v_add3_u32 v2, v2, v3, s68
	v_mul_f32_e32 v1, v161, v1
	global_store_short_d16_hi v[22:23], v2, off offset:1088
	v_bfe_u32 v2, v1, 16, 1
	v_add3_u32 v1, v1, v2, s68
	v_mul_f32_e32 v2, 0x4b800000, v4
	v_cmp_gt_f32_e32 vcc, s67, v4
	v_mul_f32_e32 v0, v0, v5
	v_mul_f32_e32 v0, v130, v0
	v_cndmask_b32_e32 v2, v4, v2, vcc
	ds_read_b128 v[4:7], v169 offset:64
	global_store_short_d16_hi v[22:23], v1, off offset:1152
	v_bfe_u32 v1, v0, 16, 1
	v_rsq_f32_e32 v34, v2
	v_add3_u32 v0, v0, v1, s68
	global_store_short_d16_hi v[22:23], v0, off offset:1216
	ds_read_b128 v[0:3], v169 offset:96
	s_waitcnt lgkmcnt(1)
	v_rcp_f32_e32 v4, v4
	v_mul_f32_e32 v22, 0x45800000, v34
	v_cndmask_b32_e32 v52, v34, v22, vcc
	v_mov_b32_e32 v22, v8
	v_mov_b32_e32 v23, v56
	v_mov_b32_e32 v37, v24
	v_mul_f32_e32 v22, v22, v4
	v_mul_f32_e32 v23, v23, v4
	v_mul_f32_e32 v36, v36, v4
	v_mul_f32_e32 v37, v37, v4
	v_rcp_f32_e32 v4, v5
	v_mov_b32_e32 v56, v9
	v_mov_b32_e32 v24, v41
	v_pk_fma_f32 v[22:23], v[128:129], v[22:23], v[100:101] neg_lo:[1,0,0] neg_hi:[1,0,0]
	v_mul_f32_e32 v8, v56, v4
	v_mul_f32_e32 v9, v57, v4
	v_mul_f32_e32 v5, v25, v4
	v_mul_f32_e32 v4, v24, v4
	v_pk_fma_f32 v[8:9], v[128:129], v[8:9], v[96:97] neg_lo:[1,0,0] neg_hi:[1,0,0]
	v_pk_mul_f32 v[34:35], v[22:23], v[22:23]
	v_pk_fma_f32 v[36:37], v[128:129], v[36:37], v[98:99] neg_lo:[1,0,0] neg_hi:[1,0,0]
	v_pk_mul_f32 v[50:51], v[8:9], v[8:9]
	v_pk_fma_f32 v[4:5], v[128:129], v[4:5], v[94:95] neg_lo:[1,0,0] neg_hi:[1,0,0]
	v_pk_mul_f32 v[38:39], v[36:37], v[36:37]
	v_pk_mul_f32 v[24:25], v[4:5], v[4:5]
	v_mov_b32_e32 v40, v50
	v_mov_b32_e32 v41, v34
	v_mov_b32_e32 v34, v51
	v_add_f32_e32 v34, v40, v34
	v_add_f32_e32 v35, v41, v35
	v_mov_b32_e32 v40, v25
	v_mov_b32_e32 v41, v39
	v_add_f32_e32 v34, v40, v34
	v_add_f32_e32 v35, v41, v35
	v_mov_b32_e32 v25, v38
	v_add_f32_e32 v24, v24, v34
	v_add_f32_e32 v25, v25, v35
	ds_bpermute_b32 v35, v164, v25
	ds_bpermute_b32 v34, v164, v24
	v_mul_f32_e32 v40, 0x3f4ccccd, v52
	v_mul_f32_e32 v20, v20, v40
	v_mul_f32_e32 v20, v163, v20
	v_bfe_u32 v41, v20, 16, 1
	s_waitcnt lgkmcnt(0)
	v_add_f32_e32 v24, v24, v34
	v_add_f32_e32 v25, v25, v35
	ds_bpermute_b32 v35, v165, v25
	ds_bpermute_b32 v34, v165, v24
	v_lshl_add_u64 v[38:39], v[32:33], 0, v[90:91]
	v_add3_u32 v20, v20, v41, s68
	global_store_short_d16_hi v[38:39], v20, off offset:1024
	v_mul_f32_e32 v41, v21, v40
	s_waitcnt lgkmcnt(0)
	v_add_f32_e32 v20, v24, v34
	v_add_f32_e32 v21, v25, v35
	ds_bpermute_b32 v25, v168, v21
	ds_bpermute_b32 v24, v168, v20
	v_mul_f32_e32 v34, v162, v41
	v_bfe_u32 v35, v34, 16, 1
	v_mul_f32_e32 v19, v19, v40
	v_add3_u32 v34, v34, v35, s68
	s_waitcnt lgkmcnt(0)
	v_add_f32_e32 v20, v20, v24
	v_add_f32_e32 v21, v21, v25
	ds_bpermute_b32 v25, v167, v21
	ds_bpermute_b32 v24, v167, v20
	v_mul_f32_e32 v19, v161, v19
	global_store_short_d16_hi v[38:39], v34, off offset:1088
	v_bfe_u32 v34, v19, 16, 1
	v_add3_u32 v19, v19, v34, s68
	s_waitcnt lgkmcnt(0)
	v_add_f32_e32 v20, v20, v24
	v_add_f32_e32 v21, v21, v25
	ds_bpermute_b32 v25, v166, v21
	ds_bpermute_b32 v24, v166, v20
	v_mul_f32_e32 v18, v18, v40
	global_store_short_d16_hi v[38:39], v19, off offset:1152
	v_mul_f32_e32 v34, v130, v18
	v_bfe_u32 v35, v34, 16, 1
	s_waitcnt lgkmcnt(0)
	v_add_f32_e32 v18, v20, v24
	v_add_f32_e32 v19, v21, v25
	v_rcp_f32_e32 v6, v6
	v_pk_fma_f32 v[18:19], v[18:19], s[24:25], v[92:93] op_sel_hi:[1,0,0]
	v_rcp_f32_e32 v0, v0
	v_mul_f32_e32 v20, 0x4b800000, v19
	v_cmp_gt_f32_e32 vcc, s67, v19
	v_rcp_f32_e32 v2, v2
	s_nop 0
	v_cndmask_b32_e32 v19, v19, v20, vcc
	v_rsq_f32_e32 v19, v19
	v_add3_u32 v20, v34, v35, s68
	global_store_short_d16_hi v[38:39], v20, off offset:1216
	v_lshl_add_u64 v[20:21], v[32:33], 0, v[86:87]
	v_mul_f32_e32 v24, 0x45800000, v19
	v_cndmask_b32_e32 v19, v19, v24, vcc
	v_mul_f32_e32 v19, 0x3f4ccccd, v19
	v_mul_f32_e32 v22, v22, v19
	v_mul_f32_e32 v22, v163, v22
	v_bfe_u32 v24, v22, 16, 1
	v_add3_u32 v22, v22, v24, s68
	global_store_short_d16_hi v[20:21], v22, off offset:1024
	v_mul_f32_e32 v22, v23, v19
	v_mul_f32_e32 v22, v162, v22
	v_bfe_u32 v23, v22, 16, 1
	v_add3_u32 v22, v22, v23, s68
	global_store_short_d16_hi v[20:21], v22, off offset:1088
	v_mul_f32_e32 v22, v37, v19
	v_mul_f32_e32 v22, v161, v22
	v_bfe_u32 v23, v22, 16, 1
	v_add3_u32 v22, v22, v23, s68
	global_store_short_d16_hi v[20:21], v22, off offset:1152
	v_mul_f32_e32 v22, 0x4b800000, v18
	v_cmp_gt_f32_e32 vcc, s67, v18
	v_mul_f32_e32 v19, v36, v19
	v_mul_f32_e32 v19, v130, v19
	v_cndmask_b32_e32 v18, v18, v22, vcc
	v_rsq_f32_e32 v18, v18
	v_bfe_u32 v22, v19, 16, 1
	v_add3_u32 v19, v19, v22, s68
	global_store_short_d16_hi v[20:21], v19, off offset:1216
	v_mul_f32_e32 v19, 0x45800000, v18
	v_cndmask_b32_e32 v38, v18, v19, vcc
	v_mov_b32_e32 v18, v10
	v_mov_b32_e32 v19, v58
	v_mov_b32_e32 v22, v42
	v_mov_b32_e32 v23, v26
	v_mul_f32_e32 v18, v18, v6
	v_mul_f32_e32 v19, v19, v6
	v_mul_f32_e32 v22, v22, v6
	v_mul_f32_e32 v23, v23, v6
	v_rcp_f32_e32 v6, v7
	v_mov_b32_e32 v58, v11
	v_mov_b32_e32 v26, v43
	v_pk_fma_f32 v[18:19], v[128:129], v[18:19], v[88:89] neg_lo:[1,0,0] neg_hi:[1,0,0]
	v_mul_f32_e32 v10, v58, v6
	v_mul_f32_e32 v11, v59, v6
	v_mul_f32_e32 v7, v27, v6
	v_mul_f32_e32 v6, v26, v6
	v_pk_fma_f32 v[10:11], v[128:129], v[10:11], v[82:83] neg_lo:[1,0,0] neg_hi:[1,0,0]
	v_pk_mul_f32 v[20:21], v[18:19], v[18:19]
	v_pk_fma_f32 v[22:23], v[128:129], v[22:23], v[84:85] neg_lo:[1,0,0] neg_hi:[1,0,0]
	v_pk_mul_f32 v[34:35], v[10:11], v[10:11]
	v_pk_fma_f32 v[6:7], v[128:129], v[6:7], v[80:81] neg_lo:[1,0,0] neg_hi:[1,0,0]
	v_pk_mul_f32 v[24:25], v[22:23], v[22:23]
	v_pk_mul_f32 v[26:27], v[6:7], v[6:7]
	v_mov_b32_e32 v36, v34
	v_mov_b32_e32 v37, v20
	v_mov_b32_e32 v20, v35
	v_add_f32_e32 v20, v36, v20
	v_add_f32_e32 v21, v37, v21
	v_mov_b32_e32 v34, v27
	v_mov_b32_e32 v35, v25
	v_add_f32_e32 v20, v34, v20
	v_add_f32_e32 v21, v35, v21
	v_mov_b32_e32 v27, v24
	v_add_f32_e32 v20, v26, v20
	v_add_f32_e32 v21, v27, v21
	ds_bpermute_b32 v25, v164, v21
	ds_bpermute_b32 v24, v164, v20
	v_mul_f32_e32 v34, 0x3f4ccccd, v38
	v_mul_f32_e32 v8, v8, v34
	v_mul_f32_e32 v8, v163, v8
	v_bfe_u32 v35, v8, 16, 1
	s_waitcnt lgkmcnt(0)
; DI unsigned short f2bf(float x) { unsigned u = __float_as_uint(x); u += 0x7fffu + ((u >> 16) & 1u); return (unsigned short)(u >> 16); }
; DI float shx(float v, int mask, int lane) { return __int_as_float(__builtin_amdgcn_ds_bpermute((lane ^ mask) << 2, __float_as_int(v))); }
; DI int crow(int r, int hi) { return (r & 3) + 8 * (r >> 2) + 4 * hi; }
; template <int DQK, int MODE, int LDQ, int LDK, int LDV> ...
;     ...
;     for (int r = 0; r < 16; ++r) { const int orow = wid * 32 + crow(r, hi); const float rl = __builtin_amdgcn_rcpf(li_l[crow(r, hi)]);
;         if constexpr (MODE == 0) {
; #pragma unroll
;             for (int d0 = 0; d0 < 4; ++d0) AOb[(size_t)orow * 1024 + d0 * 32 + r32] = f2bf(o[d0][r] * rl);
;         } else if constexpr (MODE == 1) {
; #pragma unroll
;             for (int d0 = 0; d0 < 4; ++d0) S0[(size_t)orow * 512 + d0 * 32 + r32] = o[d0][r] * rl;
;         } else {
;             float v[4]; float ss = 0.f;
; #pragma unroll
;             for (int d0 = 0; d0 < 4; ++d0) { v[d0] = s0v[r][d0] - lam * (o[d0][r] * rl); ss += v[d0] * v[d0]; }
; #pragma unroll
;             for (int mk = 1; mk <= 16; mk <<= 1) ss += shx(ss, mk, lane2);
;             const float rs = rsqrtf(ss * (1.f / 128.f) + EPS) * 0.8f;
; #pragma unroll
;             for (int d0 = 0; d0 < 4; ++d0) AOb[(size_t)orow * 1024 + d0 * 32 + r32] = f2bf(v[d0] * rs * gout[d0 * 32 + r32]);
	v_add_f32_e32 v20, v20, v24
	v_add_f32_e32 v21, v21, v25
	ds_bpermute_b32 v25, v165, v21
	ds_bpermute_b32 v24, v165, v20
	v_lshl_add_u64 v[26:27], v[32:33], 0, v[78:79]
	v_add3_u32 v8, v8, v35, s68
	global_store_short_d16_hi v[26:27], v8, off offset:1024
	v_mul_f32_e32 v35, v9, v34
	s_waitcnt lgkmcnt(0)
	v_add_f32_e32 v8, v20, v24
	v_add_f32_e32 v9, v21, v25
	ds_bpermute_b32 v21, v168, v9
	ds_bpermute_b32 v20, v168, v8
	v_mul_f32_e32 v24, v162, v35
	v_bfe_u32 v25, v24, 16, 1
	v_mul_f32_e32 v5, v5, v34
	v_add3_u32 v24, v24, v25, s68
	s_waitcnt lgkmcnt(0)
	v_add_f32_e32 v8, v8, v20
	v_add_f32_e32 v9, v9, v21
	ds_bpermute_b32 v21, v167, v9
	ds_bpermute_b32 v20, v167, v8
	v_mul_f32_e32 v5, v161, v5
	global_store_short_d16_hi v[26:27], v24, off offset:1088
	v_bfe_u32 v24, v5, 16, 1
	v_add3_u32 v5, v5, v24, s68
	s_waitcnt lgkmcnt(0)
	v_add_f32_e32 v8, v8, v20
	v_add_f32_e32 v9, v9, v21
	ds_bpermute_b32 v21, v166, v9
	ds_bpermute_b32 v20, v166, v8
	v_mul_f32_e32 v4, v4, v34
	global_store_short_d16_hi v[26:27], v5, off offset:1152
	v_mul_f32_e32 v24, v130, v4
	v_bfe_u32 v25, v24, 16, 1
	s_waitcnt lgkmcnt(0)
	v_add_f32_e32 v4, v8, v20
	v_add_f32_e32 v5, v9, v21
	s_nop 0
	v_pk_fma_f32 v[4:5], v[4:5], s[24:25], v[92:93] op_sel_hi:[1,0,0]
	s_nop 0
	v_mul_f32_e32 v8, 0x4b800000, v5
	v_cmp_gt_f32_e32 vcc, s67, v5
	s_nop 1
	v_cndmask_b32_e32 v5, v5, v8, vcc
	v_rsq_f32_e32 v5, v5
	v_add3_u32 v8, v24, v25, s68
	global_store_short_d16_hi v[26:27], v8, off offset:1216
	v_lshl_add_u64 v[8:9], v[32:33], 0, v[76:77]
	v_mul_f32_e32 v20, 0x45800000, v5
	v_cndmask_b32_e32 v5, v5, v20, vcc
	v_mul_f32_e32 v5, 0x3f4ccccd, v5
	v_mul_f32_e32 v18, v18, v5
	v_mul_f32_e32 v18, v163, v18
	v_bfe_u32 v20, v18, 16, 1
	v_add3_u32 v18, v18, v20, s68
	global_store_short_d16_hi v[8:9], v18, off offset:1024
	v_mul_f32_e32 v18, v19, v5
	v_mul_f32_e32 v18, v162, v18
	v_bfe_u32 v19, v18, 16, 1
	v_add3_u32 v18, v18, v19, s68
	global_store_short_d16_hi v[8:9], v18, off offset:1088
	v_mul_f32_e32 v18, v23, v5
	v_mul_f32_e32 v18, v161, v18
	v_bfe_u32 v19, v18, 16, 1
	v_add3_u32 v18, v18, v19, s68
	global_store_short_d16_hi v[8:9], v18, off offset:1152
	v_mul_f32_e32 v18, 0x4b800000, v4
	v_cmp_gt_f32_e32 vcc, s67, v4
	v_mul_f32_e32 v5, v22, v5
	v_mul_f32_e32 v5, v130, v5
	v_cndmask_b32_e32 v4, v4, v18, vcc
	v_rsq_f32_e32 v4, v4
	v_bfe_u32 v18, v5, 16, 1
	v_add3_u32 v5, v5, v18, s68
	global_store_short_d16_hi v[8:9], v5, off offset:1216
	v_mul_f32_e32 v5, 0x45800000, v4
	v_cndmask_b32_e32 v34, v4, v5, vcc
	v_mov_b32_e32 v4, v12
	v_mov_b32_e32 v5, v60
	v_mov_b32_e32 v18, v44
	v_mov_b32_e32 v19, v28
	v_mul_f32_e32 v4, v4, v0
	v_mul_f32_e32 v5, v5, v0
	v_mul_f32_e32 v18, v18, v0
	v_mul_f32_e32 v19, v19, v0
	v_rcp_f32_e32 v0, v1
	v_mov_b32_e32 v60, v13
	v_mov_b32_e32 v28, v45
	s_waitcnt vmcnt(58)
	v_pk_fma_f32 v[4:5], v[128:129], v[4:5], v[116:117] neg_lo:[1,0,0] neg_hi:[1,0,0]
	v_mul_f32_e32 v12, v60, v0
	v_mul_f32_e32 v13, v61, v0
	v_mul_f32_e32 v1, v29, v0
	v_mul_f32_e32 v0, v28, v0
	s_waitcnt vmcnt(54)
	v_pk_fma_f32 v[12:13], v[128:129], v[12:13], v[112:113] neg_lo:[1,0,0] neg_hi:[1,0,0]
	v_pk_mul_f32 v[8:9], v[4:5], v[4:5]
	v_pk_fma_f32 v[18:19], v[128:129], v[18:19], v[114:115] neg_lo:[1,0,0] neg_hi:[1,0,0]
	v_pk_mul_f32 v[22:23], v[12:13], v[12:13]
	s_waitcnt vmcnt(52)
	v_pk_fma_f32 v[0:1], v[128:129], v[0:1], v[110:111] neg_lo:[1,0,0] neg_hi:[1,0,0]
	v_pk_mul_f32 v[20:21], v[18:19], v[18:19]
	v_pk_mul_f32 v[24:25], v[0:1], v[0:1]
	v_mov_b32_e32 v26, v22
	v_mov_b32_e32 v27, v8
	v_mov_b32_e32 v8, v23
	v_add_f32_e32 v8, v26, v8
	v_add_f32_e32 v9, v27, v9
	v_mov_b32_e32 v22, v25
	v_mov_b32_e32 v23, v21
	v_add_f32_e32 v8, v22, v8
	v_add_f32_e32 v9, v23, v9
	v_mov_b32_e32 v25, v20
	v_add_f32_e32 v8, v24, v8
	v_add_f32_e32 v9, v25, v9
	ds_bpermute_b32 v21, v164, v9
	ds_bpermute_b32 v20, v164, v8
	v_mul_f32_e32 v24, 0x3f4ccccd, v34
	v_mul_f32_e32 v10, v10, v24
	v_mul_f32_e32 v10, v163, v10
	v_bfe_u32 v25, v10, 16, 1
	s_waitcnt lgkmcnt(0)
	v_add_f32_e32 v8, v8, v20
	v_add_f32_e32 v9, v9, v21
	ds_bpermute_b32 v21, v165, v9
	ds_bpermute_b32 v20, v165, v8
	v_lshl_add_u64 v[22:23], v[32:33], 0, v[72:73]
	v_add3_u32 v10, v10, v25, s68
	global_store_short_d16_hi v[22:23], v10, off offset:1024
	v_mul_f32_e32 v25, v11, v24
	s_waitcnt lgkmcnt(0)
	v_add_f32_e32 v8, v8, v20
	v_add_f32_e32 v9, v9, v21
	ds_bpermute_b32 v11, v168, v9
	ds_bpermute_b32 v10, v168, v8
	v_mul_f32_e32 v20, v162, v25
	v_bfe_u32 v21, v20, 16, 1
	v_mul_f32_e32 v7, v7, v24
	v_add3_u32 v20, v20, v21, s68
	s_waitcnt lgkmcnt(0)
	v_add_f32_e32 v8, v8, v10
	v_add_f32_e32 v9, v9, v11
	ds_bpermute_b32 v11, v167, v9
	ds_bpermute_b32 v10, v167, v8
	v_mul_f32_e32 v7, v161, v7
	global_store_short_d16_hi v[22:23], v20, off offset:1088
	v_bfe_u32 v20, v7, 16, 1
	v_add3_u32 v7, v7, v20, s68
	s_waitcnt lgkmcnt(0)
	v_add_f32_e32 v8, v8, v10
	v_add_f32_e32 v9, v9, v11
	ds_bpermute_b32 v11, v166, v9
	ds_bpermute_b32 v10, v166, v8
	v_mul_f32_e32 v6, v6, v24
	global_store_short_d16_hi v[22:23], v7, off offset:1152
	v_mul_f32_e32 v20, v130, v6
	v_bfe_u32 v21, v20, 16, 1
	s_waitcnt lgkmcnt(0)
; DI unsigned short f2bf(float x) { unsigned u = __float_as_uint(x); u += 0x7fffu + ((u >> 16) & 1u); return (unsigned short)(u >> 16); }
; DI float shx(float v, int mask, int lane) { return __int_as_float(__builtin_amdgcn_ds_bpermute((lane ^ mask) << 2, __float_as_int(v))); }
; DI int crow(int r, int hi) { return (r & 3) + 8 * (r >> 2) + 4 * hi; }
; template <int DQK, int MODE, int LDQ, int LDK, int LDV> ...
;     ...
;     for (int r = 0; r < 16; ++r) { const int orow = wid * 32 + crow(r, hi); const float rl = __builtin_amdgcn_rcpf(li_l[crow(r, hi)]);
;         if constexpr (MODE == 0) {
; #pragma unroll
;             for (int d0 = 0; d0 < 4; ++d0) AOb[(size_t)orow * 1024 + d0 * 32 + r32] = f2bf(o[d0][r] * rl);
;         } else if constexpr (MODE == 1) {
; #pragma unroll
;             for (int d0 = 0; d0 < 4; ++d0) S0[(size_t)orow * 512 + d0 * 32 + r32] = o[d0][r] * rl;
;         } else {
;             float v[4]; float ss = 0.f;
; #pragma unroll
;             for (int d0 = 0; d0 < 4; ++d0) { v[d0] = s0v[r][d0] - lam * (o[d0][r] * rl); ss += v[d0] * v[d0]; }
; #pragma unroll
;             for (int mk = 1; mk <= 16; mk <<= 1) ss += shx(ss, mk, lane2);
;             const float rs = rsqrtf(ss * (1.f / 128.f) + EPS) * 0.8f;
; #pragma unroll
;             for (int d0 = 0; d0 < 4; ++d0) AOb[(size_t)orow * 1024 + d0 * 32 + r32] = f2bf(v[d0] * rs * gout[d0 * 32 + r32]);
;         } }
	v_add_f32_e32 v6, v8, v10
	v_add_f32_e32 v7, v9, v11
	s_nop 0
	v_pk_fma_f32 v[6:7], v[6:7], s[24:25], v[92:93] op_sel_hi:[1,0,0]
	s_nop 0
	v_mul_f32_e32 v8, 0x4b800000, v7
	v_cmp_gt_f32_e32 vcc, s67, v7
	s_nop 1
	v_cndmask_b32_e32 v7, v7, v8, vcc
	v_rsq_f32_e32 v7, v7
	v_add3_u32 v8, v20, v21, s68
	global_store_short_d16_hi v[22:23], v8, off offset:1216
	v_lshl_add_u64 v[8:9], v[32:33], 0, v[74:75]
	v_mul_f32_e32 v10, 0x45800000, v7
	v_cndmask_b32_e32 v7, v7, v10, vcc
	v_mul_f32_e32 v7, 0x3f4ccccd, v7
	v_mul_f32_e32 v4, v4, v7
	v_mul_f32_e32 v4, v163, v4
	v_bfe_u32 v10, v4, 16, 1
	v_add3_u32 v4, v4, v10, s68
	global_store_short_d16_hi v[8:9], v4, off offset:1024
	v_mul_f32_e32 v4, v5, v7
	v_mul_f32_e32 v4, v162, v4
	v_bfe_u32 v5, v4, 16, 1
	v_add3_u32 v4, v4, v5, s68
	global_store_short_d16_hi v[8:9], v4, off offset:1088
	v_mul_f32_e32 v4, v19, v7
	v_mul_f32_e32 v4, v161, v4
	v_bfe_u32 v5, v4, 16, 1
	v_add3_u32 v4, v4, v5, s68
	v_mul_f32_e32 v5, 0x4b800000, v6
	v_cmp_gt_f32_e32 vcc, s67, v6
	global_store_short_d16_hi v[8:9], v4, off offset:1152
	v_mul_f32_e32 v4, v18, v7
	v_cndmask_b32_e32 v5, v6, v5, vcc
	v_rsq_f32_e32 v5, v5
	v_mul_f32_e32 v4, v130, v4
	v_bfe_u32 v6, v4, 16, 1
	v_add3_u32 v4, v4, v6, s68
	global_store_short_d16_hi v[8:9], v4, off offset:1216
	v_mul_f32_e32 v4, 0x45800000, v5
	v_cndmask_b32_e32 v24, v5, v4, vcc
	v_mov_b32_e32 v4, v14
	v_mov_b32_e32 v5, v62
	v_mov_b32_e32 v8, v46
	v_mov_b32_e32 v9, v30
	v_mul_f32_e32 v4, v4, v2
	v_mul_f32_e32 v5, v5, v2
	v_mul_f32_e32 v8, v8, v2
	v_mul_f32_e32 v9, v9, v2
	v_rcp_f32_e32 v2, v3
	v_mov_b32_e32 v62, v15
	v_mov_b32_e32 v30, v47
	s_waitcnt vmcnt(58)
	v_pk_fma_f32 v[4:5], v[128:129], v[4:5], v[108:109] neg_lo:[1,0,0] neg_hi:[1,0,0]
	v_mul_f32_e32 v14, v62, v2
	v_mul_f32_e32 v15, v63, v2
	v_mul_f32_e32 v3, v31, v2
	v_mul_f32_e32 v2, v30, v2
	s_waitcnt vmcnt(54)
	v_pk_fma_f32 v[14:15], v[128:129], v[14:15], v[104:105] neg_lo:[1,0,0] neg_hi:[1,0,0]
	v_pk_mul_f32 v[6:7], v[4:5], v[4:5]
	v_pk_fma_f32 v[8:9], v[128:129], v[8:9], v[106:107] neg_lo:[1,0,0] neg_hi:[1,0,0]
	v_pk_mul_f32 v[18:19], v[14:15], v[14:15]
	s_waitcnt vmcnt(52)
	v_pk_fma_f32 v[2:3], v[128:129], v[2:3], v[102:103] neg_lo:[1,0,0] neg_hi:[1,0,0]
	v_pk_mul_f32 v[10:11], v[8:9], v[8:9]
	v_pk_mul_f32 v[20:21], v[2:3], v[2:3]
	v_mov_b32_e32 v22, v18
	v_mov_b32_e32 v23, v6
	v_mov_b32_e32 v6, v19
	v_add_f32_e32 v6, v22, v6
	v_add_f32_e32 v7, v23, v7
	v_mov_b32_e32 v18, v21
	v_mov_b32_e32 v19, v11
	v_add_f32_e32 v6, v18, v6
	v_add_f32_e32 v7, v19, v7
	v_mov_b32_e32 v21, v10
	v_add_f32_e32 v6, v20, v6
	v_add_f32_e32 v7, v21, v7
	ds_bpermute_b32 v11, v164, v7
	ds_bpermute_b32 v10, v164, v6
	v_mul_f32_e32 v20, 0x3f4ccccd, v24
	v_mul_f32_e32 v12, v12, v20
	v_mul_f32_e32 v12, v163, v12
	v_bfe_u32 v21, v12, 16, 1
	s_waitcnt lgkmcnt(0)
	v_add_f32_e32 v6, v6, v10
	v_add_f32_e32 v7, v7, v11
	ds_bpermute_b32 v11, v165, v7
	ds_bpermute_b32 v10, v165, v6
	v_lshl_add_u64 v[18:19], v[32:33], 0, v[64:65]
	v_add3_u32 v12, v12, v21, s68
	global_store_short_d16_hi v[18:19], v12, off offset:1024
	v_mul_f32_e32 v12, v13, v20
	s_waitcnt lgkmcnt(0)
	v_add_f32_e32 v6, v6, v10
	v_add_f32_e32 v7, v7, v11
	ds_bpermute_b32 v11, v168, v7
	ds_bpermute_b32 v10, v168, v6
	v_mul_f32_e32 v12, v162, v12
	v_bfe_u32 v13, v12, 16, 1
	v_mul_f32_e32 v1, v1, v20
	v_add3_u32 v12, v12, v13, s68
	s_waitcnt lgkmcnt(0)
	v_add_f32_e32 v6, v6, v10
	v_add_f32_e32 v7, v7, v11
	ds_bpermute_b32 v11, v167, v7
	ds_bpermute_b32 v10, v167, v6
	v_mul_f32_e32 v1, v161, v1
	global_store_short_d16_hi v[18:19], v12, off offset:1088
	v_bfe_u32 v12, v1, 16, 1
	v_add3_u32 v1, v1, v12, s68
	s_waitcnt lgkmcnt(0)
	v_add_f32_e32 v6, v6, v10
	v_add_f32_e32 v7, v7, v11
	ds_bpermute_b32 v11, v166, v7
	ds_bpermute_b32 v10, v166, v6
	v_mul_f32_e32 v0, v0, v20
	global_store_short_d16_hi v[18:19], v1, off offset:1152
	v_mul_f32_e32 v12, v130, v0
	v_bfe_u32 v13, v12, 16, 1
	s_waitcnt lgkmcnt(0)
	v_add_f32_e32 v0, v6, v10
	v_add_f32_e32 v1, v7, v11
	s_nop 0
	v_pk_fma_f32 v[0:1], v[0:1], s[24:25], v[92:93] op_sel_hi:[1,0,0]
	s_nop 0
	v_mul_f32_e32 v6, 0x4b800000, v1
	v_cmp_gt_f32_e32 vcc, s67, v1
	s_nop 1
	v_cndmask_b32_e32 v1, v1, v6, vcc
	v_rsq_f32_e32 v1, v1
	v_add3_u32 v6, v12, v13, s68
	global_store_short_d16_hi v[18:19], v6, off offset:1216
	v_lshl_add_u64 v[6:7], v[32:33], 0, v[48:49]
	v_mul_f32_e32 v10, 0x45800000, v1
	v_cndmask_b32_e32 v1, v1, v10, vcc
	v_mul_f32_e32 v1, 0x3f4ccccd, v1
	v_mul_f32_e32 v4, v4, v1
	v_mul_f32_e32 v4, v163, v4
	v_bfe_u32 v10, v4, 16, 1
	v_add3_u32 v4, v4, v10, s68
	global_store_short_d16_hi v[6:7], v4, off offset:1024
	v_mul_f32_e32 v4, v5, v1
	v_mul_f32_e32 v4, v162, v4
	v_bfe_u32 v5, v4, 16, 1
	v_add3_u32 v4, v4, v5, s68
	global_store_short_d16_hi v[6:7], v4, off offset:1088
	v_mul_f32_e32 v4, v9, v1
	v_mul_f32_e32 v4, v161, v4
	v_bfe_u32 v5, v4, 16, 1
	v_add3_u32 v4, v4, v5, s68
	global_store_short_d16_hi v[6:7], v4, off offset:1152
	v_mul_f32_e32 v4, 0x4b800000, v0
	v_cmp_gt_f32_e32 vcc, s67, v0
	v_mul_f32_e32 v1, v8, v1
	v_mul_f32_e32 v1, v130, v1
	v_cndmask_b32_e32 v0, v0, v4, vcc
	v_rsq_f32_e32 v0, v0
	v_bfe_u32 v4, v1, 16, 1
	v_add3_u32 v1, v1, v4, s68
	global_store_short_d16_hi v[6:7], v1, off offset:1216
	v_mul_f32_e32 v1, 0x45800000, v0
	v_cndmask_b32_e32 v0, v0, v1, vcc
	v_mul_f32_e32 v4, 0x3f4ccccd, v0
	v_mul_f32_e32 v5, v14, v4
	v_mul_f32_e32 v5, v163, v5
	v_bfe_u32 v6, v5, 16, 1
	v_lshl_add_u64 v[0:1], v[32:33], 0, v[16:17]
	v_add3_u32 v5, v5, v6, s68
	global_store_short_d16_hi v[0:1], v5, off offset:1024
	v_mul_f32_e32 v5, v15, v4
	v_mul_f32_e32 v5, v162, v5
	v_bfe_u32 v6, v5, 16, 1
	v_mul_f32_e32 v3, v3, v4
	v_add3_u32 v5, v5, v6, s68
	v_mul_f32_e32 v3, v161, v3
	global_store_short_d16_hi v[0:1], v5, off offset:1088
	v_bfe_u32 v5, v3, 16, 1
	v_mul_f32_e32 v2, v2, v4
	v_add3_u32 v3, v3, v5, s68
	v_mul_f32_e32 v2, v130, v2
	global_store_short_d16_hi v[0:1], v3, off offset:1152
	v_bfe_u32 v3, v2, 16, 1
	v_add3_u32 v2, v2, v3, s68
	global_store_short_d16_hi v[0:1], v2, off offset:1216
	s_waitcnt vmcnt(63) expcnt(7) lgkmcnt(15)
	s_barrier
